# GEMM K-loops: in each load segment the HBM to LDS tile loads are issued before the LDS fragment reads instead of after (earlier prefetch issue)
# baseline (speedup 1.0000x reference)
; #define PG8_STAGE(bufoff, gbase, voff) do { _Pragma("unroll") for (int _i = 0; _i < 2; ++_i) \
;         __builtin_amdgcn_global_load_lds((const unsigned*)((const char*)(gbase) + (voff)[_i]), (PG8_LAS unsigned*)(lds + (bufoff) + ldsw + _i * 8192), 16, 0, 0); } while (0)
; #define PG8_LDA(dst, b, h) do { _Pragma("unroll") for (int m = 0; m < 4; ++m) _Pragma("unroll") for (int k = 0; k < 2; ++k) dst[m][k] = *(const PG8_LAS bf16x8*)(lds + PG8_SA(b, h) + aoff + m * 2048 + k * 1024); } while (0)
; #define PG8_LDB(dst, b, h) do { _Pragma("unroll") for (int n = 0; n < 2; ++n) _Pragma("unroll") for (int k = 0; k < 2; ++k) dst[n][k] = *(const PG8_LAS bf16x8*)(lds + PG8_SB(b, h) + boff + n * 2048 + k * 1024); } while (0)
; #define PG8_MMA(ai, bj, At, Bt) do { __builtin_amdgcn_s_setprio(1); _Pragma("unroll") for (int m = 0; m < 4; ++m) _Pragma("unroll") for (int n = 0; n < 2; ++n) _Pragma("unroll") for (int k = 0; k < 2; ++k) \
;         acc[ai][bj][m][n] = __builtin_amdgcn_mfma_f32_16x16x32_bf16(Bt[n][k], At[m][k], acc[ai][bj][m][n], 0, 0, 0); __builtin_amdgcn_s_setprio(0); } while (0)
; #define PG8_WAIT_V(n) asm volatile("s_waitcnt vmcnt(" #n ")" ::: "memory")
; #define PG8_WAIT_L(n) asm volatile("s_waitcnt lgkmcnt(" #n ")" ::: "memory")
; #define PG8_BAR __builtin_amdgcn_s_barrier()
; #define PG8_SCHED __builtin_amdgcn_sched_barrier(0)
; template <class Epi, class Sched, bool ALIGN_EPI = true, bool SP2 = true, bool GS = false>
; __device__ __forceinline__ void gemm_phase(PG8_LAS unsigned char* lds, const Gemm g, const Sched& S, const Epi& E, const float* gs_ss = nullptr) {
;     ...
;             PG8_LDB(B0, 0, 0); PG8_LDB(B1, 0, 1); PG8_SCHED; PG8_LDA(At, 0, 0); PG8_STAGE(PG8_SA(1, 1), a1 + hstep, voffA);
;             PG8_WAIT_V(8); PG8_WAIT_L(0); PG8_BAR; PG8_MMA(0, 0, At, B0); PG8_MMA(0, 1, At, B1); PG8_BAR; PG8_SCHED;
;             PG8_LDA(At, 0, 1); PG8_STAGE(PG8_SB(0, 0), b2, voffB); PG8_STAGE(PG8_SB(0, 1), b2 + hstep, voffB); PG8_STAGE(PG8_SA(0, 0), a2, voffA);
;             PG8_WAIT_V(8); PG8_WAIT_L(0); PG8_BAR; PG8_MMA(1, 0, At, B0); PG8_MMA(1, 1, At, B1); PG8_BAR; PG8_SCHED;
.LBB0_151:
	s_add_u32 s2, s40, 0xfff80080
	s_addc_u32 s3, s41, -1
	s_cmp_eq_u32 s65, 28
	s_cselect_b32 s21, s13, s3
	s_cselect_b32 s20, s53, s2
	s_cselect_b32 s3, s51, s43
	s_cselect_b32 s2, s64, s42
	v_lshl_add_u64 v[176:177], s[40:41], 0, v[142:143]
	s_add_i32 m0, s24, 0xc000
	s_nop 0
	global_load_lds_dwordx4 v[176:177], off
	v_lshl_add_u64 v[176:177], s[40:41], 0, v[144:145]
	s_add_i32 m0, s24, 0xe000
	s_nop 0
	global_load_lds_dwordx4 v[176:177], off
	s_add_i32 s67, 0, 0x10000
	v_add_u32_e32 v0, s67, v167
	s_add_i32 s69, 0, 0x14000
	ds_read_b128 v[146:149], v0
	ds_read_b128 v[150:153], v0 offset:1024
	ds_read_b128 v[154:157], v0 offset:2048
	ds_read_b128 v[158:161], v0 offset:3072
	v_add_u32_e32 v0, s69, v167
	ds_read_b128 v[162:165], v0
	ds_read_b128 v[172:175], v0 offset:1024
	ds_read_b128 v[180:183], v0 offset:2048
	ds_read_b128 v[184:187], v0 offset:3072
	ds_read_b128 v[188:191], v171
	ds_read_b128 v[192:195], v171 offset:1024
	ds_read_b128 v[196:199], v171 offset:2048
	ds_read_b128 v[200:203], v171 offset:3072
	ds_read_b128 v[204:207], v171 offset:4096
	ds_read_b128 v[208:211], v171 offset:5120
	ds_read_b128 v[212:215], v171 offset:6144
	ds_read_b128 v[216:219], v171 offset:7168
	s_waitcnt vmcnt(8)
	s_waitcnt lgkmcnt(0)
	s_barrier
	s_setprio 1
	s_waitcnt lgkmcnt(0)
	v_mfma_f32_16x16x32_bf16 v[126:129], v[146:149], v[188:191], v[126:129]
	v_mfma_f32_16x16x32_bf16 v[122:125], v[154:157], v[188:191], v[122:125]
	v_mfma_f32_16x16x32_bf16 v[110:113], v[146:149], v[196:199], v[110:113]
	v_mfma_f32_16x16x32_bf16 v[106:109], v[154:157], v[196:199], v[106:109]
	v_mfma_f32_16x16x32_bf16 v[94:97], v[146:149], v[204:207], v[94:97]
	v_mfma_f32_16x16x32_bf16 v[90:93], v[154:157], v[204:207], v[90:93]
	v_mfma_f32_16x16x32_bf16 v[78:81], v[146:149], v[212:215], v[78:81]
	v_mfma_f32_16x16x32_bf16 v[74:77], v[154:157], v[212:215], v[74:77]
	v_mfma_f32_16x16x32_bf16 v[126:129], v[150:153], v[192:195], v[126:129]
	v_mfma_f32_16x16x32_bf16 v[122:125], v[158:161], v[192:195], v[122:125]
	v_mfma_f32_16x16x32_bf16 v[110:113], v[150:153], v[200:203], v[110:113]
	v_mfma_f32_16x16x32_bf16 v[106:109], v[158:161], v[200:203], v[106:109]
	v_mfma_f32_16x16x32_bf16 v[94:97], v[150:153], v[208:211], v[94:97]
	v_mfma_f32_16x16x32_bf16 v[90:93], v[158:161], v[208:211], v[90:93]
	v_mfma_f32_16x16x32_bf16 v[78:81], v[150:153], v[216:219], v[78:81]
	v_mfma_f32_16x16x32_bf16 v[74:77], v[158:161], v[216:219], v[74:77]
	s_setprio 0
	s_setprio 1
	v_mfma_f32_16x16x32_bf16 v[118:121], v[162:165], v[188:191], v[118:121]
	v_mfma_f32_16x16x32_bf16 v[114:117], v[180:183], v[188:191], v[114:117]
	v_mfma_f32_16x16x32_bf16 v[102:105], v[162:165], v[196:199], v[102:105]
	v_mfma_f32_16x16x32_bf16 v[98:101], v[180:183], v[196:199], v[98:101]
	v_mfma_f32_16x16x32_bf16 v[86:89], v[162:165], v[204:207], v[86:89]
	v_mfma_f32_16x16x32_bf16 v[82:85], v[180:183], v[204:207], v[82:85]
	v_mfma_f32_16x16x32_bf16 v[70:73], v[162:165], v[212:215], v[70:73]
	v_mfma_f32_16x16x32_bf16 v[66:69], v[180:183], v[212:215], v[66:69]
	v_mfma_f32_16x16x32_bf16 v[118:121], v[172:175], v[192:195], v[118:121]
	v_mfma_f32_16x16x32_bf16 v[114:117], v[184:187], v[192:195], v[114:117]
	v_mfma_f32_16x16x32_bf16 v[102:105], v[172:175], v[200:203], v[102:105]
	v_mfma_f32_16x16x32_bf16 v[98:101], v[184:187], v[200:203], v[98:101]
	v_mfma_f32_16x16x32_bf16 v[86:89], v[172:175], v[208:211], v[86:89]
	v_mfma_f32_16x16x32_bf16 v[82:85], v[184:187], v[208:211], v[82:85]
	v_mfma_f32_16x16x32_bf16 v[70:73], v[172:175], v[216:219], v[70:73]
	v_mfma_f32_16x16x32_bf16 v[66:69], v[184:187], v[216:219], v[66:69]
	s_setprio 0
	s_barrier
	s_add_i32 s67, s67, s23
	v_lshl_add_u64 v[176:177], s[2:3], 0, v[132:133]
	s_mov_b32 m0, s67
	s_nop 0
	global_load_lds_dwordx4 v[176:177], off
	s_add_i32 m0, s67, 0x2000
	s_add_u32 s70, s2, 0x80000
	v_lshl_add_u64 v[220:221], s[2:3], 0, v[136:137]
	s_addc_u32 s71, s3, 0
	s_add_i32 s67, s69, s23
	global_load_lds_dwordx4 v[220:221], off
	v_lshl_add_u64 v[236:237], s[70:71], 0, v[132:133]
	s_mov_b32 m0, s67
	v_lshl_add_u64 v[238:239], s[20:21], 0, v[134:135]
	global_load_lds_dwordx4 v[236:237], off
	v_lshl_add_u64 v[236:237], s[70:71], 0, v[136:137]
	s_add_i32 m0, s67, 0x2000
	s_nop 0
	global_load_lds_dwordx4 v[236:237], off
	v_lshl_add_u64 v[236:237], s[20:21], 0, v[130:131]
	s_mov_b32 m0, s24
	s_nop 0
	global_load_lds_dwordx4 v[236:237], off
	s_mov_b32 m0, s25
	s_nop 0
	global_load_lds_dwordx4 v[238:239], off
	ds_read_b128 v[188:191], v171 offset:16384
	ds_read_b128 v[192:195], v171 offset:17408
	ds_read_b128 v[196:199], v171 offset:18432
	ds_read_b128 v[200:203], v171 offset:19456
	ds_read_b128 v[204:207], v171 offset:20480
	ds_read_b128 v[208:211], v171 offset:21504
	ds_read_b128 v[212:215], v171 offset:22528
	ds_read_b128 v[216:219], v171 offset:23552
	s_waitcnt vmcnt(8)
	s_waitcnt lgkmcnt(0)
	s_barrier
; #define PG8_STAGE(bufoff, gbase, voff) do { _Pragma("unroll") for (int _i = 0; _i < 2; ++_i) \
;         __builtin_amdgcn_global_load_lds((const unsigned*)((const char*)(gbase) + (voff)[_i]), (PG8_LAS unsigned*)(lds + (bufoff) + ldsw + _i * 8192), 16, 0, 0); } while (0)
; #define PG8_LDA(dst, b, h) do { _Pragma("unroll") for (int m = 0; m < 4; ++m) _Pragma("unroll") for (int k = 0; k < 2; ++k) dst[m][k] = *(const PG8_LAS bf16x8*)(lds + PG8_SA(b, h) + aoff + m * 2048 + k * 1024); } while (0)
; #define PG8_LDB(dst, b, h) do { _Pragma("unroll") for (int n = 0; n < 2; ++n) _Pragma("unroll") for (int k = 0; k < 2; ++k) dst[n][k] = *(const PG8_LAS bf16x8*)(lds + PG8_SB(b, h) + boff + n * 2048 + k * 1024); } while (0)
; #define PG8_MMA(ai, bj, At, Bt) do { __builtin_amdgcn_s_setprio(1); _Pragma("unroll") for (int m = 0; m < 4; ++m) _Pragma("unroll") for (int n = 0; n < 2; ++n) _Pragma("unroll") for (int k = 0; k < 2; ++k) \
;         acc[ai][bj][m][n] = __builtin_amdgcn_mfma_f32_16x16x32_bf16(Bt[n][k], At[m][k], acc[ai][bj][m][n], 0, 0, 0); __builtin_amdgcn_s_setprio(0); } while (0)
; #define PG8_WAIT_V(n) asm volatile("s_waitcnt vmcnt(" #n ")" ::: "memory")
; #define PG8_WAIT_L(n) asm volatile("s_waitcnt lgkmcnt(" #n ")" ::: "memory")
; #define PG8_BAR __builtin_amdgcn_s_barrier()
; #define PG8_SCHED __builtin_amdgcn_sched_barrier(0)
; template <class Epi, class Sched, bool ALIGN_EPI = true, bool SP2 = true, bool GS = false>
; __device__ __forceinline__ void gemm_phase(PG8_LAS unsigned char* lds, const Gemm g, const Sched& S, const Epi& E, const float* gs_ss = nullptr) {
;     ...
;             PG8_WAIT_V(8); PG8_WAIT_L(0); PG8_BAR; PG8_MMA(1, 0, At, B0); PG8_MMA(1, 1, At, B1); PG8_BAR; PG8_SCHED;
;             PG8_LDB(B0, 1, 0); PG8_LDB(B1, 1, 1); PG8_SCHED; PG8_LDA(At, 1, 0); PG8_STAGE(PG8_SA(0, 1), a2 + hstep, voffA);
;             PG8_WAIT_V(8); PG8_WAIT_L(0); PG8_BAR; PG8_MMA(0, 0, At, B0); PG8_MMA(0, 1, At, B1); PG8_BAR; PG8_SCHED;
	s_setprio 1
	s_waitcnt lgkmcnt(0)
	v_mfma_f32_16x16x32_bf16 v[62:65], v[146:149], v[188:191], v[62:65]
	v_mfma_f32_16x16x32_bf16 v[58:61], v[154:157], v[188:191], v[58:61]
	v_mfma_f32_16x16x32_bf16 v[46:49], v[146:149], v[196:199], v[46:49]
	v_mfma_f32_16x16x32_bf16 v[42:45], v[154:157], v[196:199], v[42:45]
	v_mfma_f32_16x16x32_bf16 v[30:33], v[146:149], v[204:207], v[30:33]
	v_mfma_f32_16x16x32_bf16 v[26:29], v[154:157], v[204:207], v[26:29]
	v_mfma_f32_16x16x32_bf16 v[14:17], v[146:149], v[212:215], v[14:17]
	v_mfma_f32_16x16x32_bf16 v[10:13], v[154:157], v[212:215], v[10:13]
	v_mfma_f32_16x16x32_bf16 v[62:65], v[150:153], v[192:195], v[62:65]
	v_mfma_f32_16x16x32_bf16 v[58:61], v[158:161], v[192:195], v[58:61]
	v_mfma_f32_16x16x32_bf16 v[46:49], v[150:153], v[200:203], v[46:49]
	v_mfma_f32_16x16x32_bf16 v[42:45], v[158:161], v[200:203], v[42:45]
	v_mfma_f32_16x16x32_bf16 v[30:33], v[150:153], v[208:211], v[30:33]
	v_mfma_f32_16x16x32_bf16 v[26:29], v[158:161], v[208:211], v[26:29]
	v_mfma_f32_16x16x32_bf16 v[14:17], v[150:153], v[216:219], v[14:17]
	v_mfma_f32_16x16x32_bf16 v[10:13], v[158:161], v[216:219], v[10:13]
	s_setprio 0
	s_setprio 1
	v_mfma_f32_16x16x32_bf16 v[54:57], v[162:165], v[188:191], v[54:57]
	v_mfma_f32_16x16x32_bf16 v[50:53], v[180:183], v[188:191], v[50:53]
	v_mfma_f32_16x16x32_bf16 v[38:41], v[162:165], v[196:199], v[38:41]
	v_mfma_f32_16x16x32_bf16 v[34:37], v[180:183], v[196:199], v[34:37]
	v_mfma_f32_16x16x32_bf16 v[22:25], v[162:165], v[204:207], v[22:25]
	v_mfma_f32_16x16x32_bf16 v[18:21], v[180:183], v[204:207], v[18:21]
	v_mfma_f32_16x16x32_bf16 v[6:9], v[162:165], v[212:215], v[6:9]
	v_mfma_f32_16x16x32_bf16 v[2:5], v[180:183], v[212:215], v[2:5]
	v_mfma_f32_16x16x32_bf16 v[54:57], v[172:175], v[192:195], v[54:57]
	v_mfma_f32_16x16x32_bf16 v[50:53], v[184:187], v[192:195], v[50:53]
	v_mfma_f32_16x16x32_bf16 v[38:41], v[172:175], v[200:203], v[38:41]
	v_mfma_f32_16x16x32_bf16 v[34:37], v[184:187], v[200:203], v[34:37]
	v_mfma_f32_16x16x32_bf16 v[22:25], v[172:175], v[208:211], v[22:25]
	v_mfma_f32_16x16x32_bf16 v[18:21], v[184:187], v[208:211], v[18:21]
	v_mfma_f32_16x16x32_bf16 v[6:9], v[172:175], v[216:219], v[6:9]
	v_mfma_f32_16x16x32_bf16 v[2:5], v[184:187], v[216:219], v[2:5]
	s_setprio 0
	s_barrier
	s_add_u32 s20, s20, 0x80000
	s_addc_u32 s21, s21, 0
	s_mov_b32 m0, s30
	v_lshl_add_u64 v[240:241], s[20:21], 0, v[130:131]
	global_load_lds_dwordx4 v[240:241], off
	v_lshl_add_u64 v[240:241], s[20:21], 0, v[134:135]
	s_mov_b32 m0, s35
	s_nop 0
	global_load_lds_dwordx4 v[240:241], off
	s_add_i32 s67, 0, 0x18000
	v_add_u32_e32 v0, s67, v167
	s_add_i32 s69, 0, 0x1c000
	ds_read_b128 v[146:149], v0
	ds_read_b128 v[150:153], v0 offset:1024
	ds_read_b128 v[154:157], v0 offset:2048
	ds_read_b128 v[158:161], v0 offset:3072
	v_add_u32_e32 v0, s69, v167
	ds_read_b128 v[162:165], v0
	ds_read_b128 v[172:175], v0 offset:1024
	ds_read_b128 v[180:183], v0 offset:2048
	ds_read_b128 v[184:187], v0 offset:3072
	ds_read_b128 v[188:191], v171 offset:32768
	ds_read_b128 v[192:195], v171 offset:33792
	ds_read_b128 v[196:199], v171 offset:34816
	ds_read_b128 v[200:203], v171 offset:35840
	ds_read_b128 v[204:207], v171 offset:36864
	ds_read_b128 v[208:211], v171 offset:37888
	ds_read_b128 v[212:215], v171 offset:38912
	ds_read_b128 v[216:219], v171 offset:39936
	s_waitcnt vmcnt(8)
	s_waitcnt lgkmcnt(0)
	s_barrier
	s_setprio 1
	s_waitcnt lgkmcnt(0)
	v_mfma_f32_16x16x32_bf16 v[126:129], v[146:149], v[188:191], v[126:129]
	v_mfma_f32_16x16x32_bf16 v[122:125], v[154:157], v[188:191], v[122:125]
	v_mfma_f32_16x16x32_bf16 v[110:113], v[146:149], v[196:199], v[110:113]
	v_mfma_f32_16x16x32_bf16 v[106:109], v[154:157], v[196:199], v[106:109]
	v_mfma_f32_16x16x32_bf16 v[94:97], v[146:149], v[204:207], v[94:97]
	v_mfma_f32_16x16x32_bf16 v[90:93], v[154:157], v[204:207], v[90:93]
	v_mfma_f32_16x16x32_bf16 v[78:81], v[146:149], v[212:215], v[78:81]
	v_mfma_f32_16x16x32_bf16 v[74:77], v[154:157], v[212:215], v[74:77]
	v_mfma_f32_16x16x32_bf16 v[126:129], v[150:153], v[192:195], v[126:129]
	v_mfma_f32_16x16x32_bf16 v[122:125], v[158:161], v[192:195], v[122:125]
	v_mfma_f32_16x16x32_bf16 v[110:113], v[150:153], v[200:203], v[110:113]
	v_mfma_f32_16x16x32_bf16 v[106:109], v[158:161], v[200:203], v[106:109]
	v_mfma_f32_16x16x32_bf16 v[94:97], v[150:153], v[208:211], v[94:97]
	v_mfma_f32_16x16x32_bf16 v[90:93], v[158:161], v[208:211], v[90:93]
	v_mfma_f32_16x16x32_bf16 v[78:81], v[150:153], v[216:219], v[78:81]
	v_mfma_f32_16x16x32_bf16 v[74:77], v[158:161], v[216:219], v[74:77]
	s_setprio 0
	s_setprio 1
	v_mfma_f32_16x16x32_bf16 v[118:121], v[162:165], v[188:191], v[118:121]
	v_mfma_f32_16x16x32_bf16 v[114:117], v[180:183], v[188:191], v[114:117]
	v_mfma_f32_16x16x32_bf16 v[102:105], v[162:165], v[196:199], v[102:105]
	v_mfma_f32_16x16x32_bf16 v[98:101], v[180:183], v[196:199], v[98:101]
	v_mfma_f32_16x16x32_bf16 v[86:89], v[162:165], v[204:207], v[86:89]
	v_mfma_f32_16x16x32_bf16 v[82:85], v[180:183], v[204:207], v[82:85]
	v_mfma_f32_16x16x32_bf16 v[70:73], v[162:165], v[212:215], v[70:73]
	v_mfma_f32_16x16x32_bf16 v[66:69], v[180:183], v[212:215], v[66:69]
	v_mfma_f32_16x16x32_bf16 v[118:121], v[172:175], v[192:195], v[118:121]
	v_mfma_f32_16x16x32_bf16 v[114:117], v[184:187], v[192:195], v[114:117]
	v_mfma_f32_16x16x32_bf16 v[102:105], v[172:175], v[200:203], v[102:105]
	v_mfma_f32_16x16x32_bf16 v[98:101], v[184:187], v[200:203], v[98:101]
	v_mfma_f32_16x16x32_bf16 v[86:89], v[172:175], v[208:211], v[86:89]
	v_mfma_f32_16x16x32_bf16 v[82:85], v[184:187], v[208:211], v[82:85]
	v_mfma_f32_16x16x32_bf16 v[70:73], v[172:175], v[216:219], v[70:73]
	v_mfma_f32_16x16x32_bf16 v[66:69], v[184:187], v[216:219], v[66:69]
	s_setprio 0
	s_barrier
; #define PG8_LAS __attribute__((address_space(3)))
; #define PG8_STAGE(bufoff, gbase, voff) do { _Pragma("unroll") for (int _i = 0; _i < 2; ++_i) \
;         __builtin_amdgcn_global_load_lds((const unsigned*)((const char*)(gbase) + (voff)[_i]), (PG8_LAS unsigned*)(lds + (bufoff) + ldsw + _i * 8192), 16, 0, 0); } while (0)
; #define PG8_LDA(dst, b, h) do { _Pragma("unroll") for (int m = 0; m < 4; ++m) _Pragma("unroll") for (int k = 0; k < 2; ++k) dst[m][k] = *(const PG8_LAS bf16x8*)(lds + PG8_SA(b, h) + aoff + m * 2048 + k * 1024); } while (0)
; #define PG8_MMA(ai, bj, At, Bt) do { __builtin_amdgcn_s_setprio(1); _Pragma("unroll") for (int m = 0; m < 4; ++m) _Pragma("unroll") for (int n = 0; n < 2; ++n) _Pragma("unroll") for (int k = 0; k < 2; ++k) \
;         acc[ai][bj][m][n] = __builtin_amdgcn_mfma_f32_16x16x32_bf16(Bt[n][k], At[m][k], acc[ai][bj][m][n], 0, 0, 0); __builtin_amdgcn_s_setprio(0); } while (0)
; #define PG8_WAIT_V(n) asm volatile("s_waitcnt vmcnt(" #n ")" ::: "memory")
; #define PG8_WAIT_L(n) asm volatile("s_waitcnt lgkmcnt(" #n ")" ::: "memory")
; #define PG8_BAR __builtin_amdgcn_s_barrier()
; #define PG8_SCHED __builtin_amdgcn_sched_barrier(0)
; template <class Epi, class Sched, bool ALIGN_EPI = true, bool SP2 = true, bool GS = false>
; __device__ __forceinline__ void gemm_phase(PG8_LAS unsigned char* lds, const Gemm g, const Sched& S, const Epi& E, const float* gs_ss = nullptr) {
;     ...
;             PG8_LDA(At, 1, 1); PG8_STAGE(PG8_SB(1, 0), b3, voffB); PG8_STAGE(PG8_SB(1, 1), b3 + hstep, voffB); PG8_STAGE(PG8_SA(1, 0), a3, voffA);
;             PG8_WAIT_V(8); PG8_WAIT_L(0); PG8_BAR; PG8_MMA(1, 0, At, B0); PG8_MMA(1, 1, At, B1); PG8_BAR; PG8_SCHED;
;     ...
;         if constexpr (ALIGN_EPI) { if (wr == 0) PG8_BAR; }
;         if constexpr (GS) E.gs(acc, cur, wr, wc, fr, fq, (const PG8_LAS float*)(lds + STAGE_BYTES + gpar * 4096)); else E(acc, cur, wr, wc, fr, fq);
;         if (!has_next) break;
	s_add_i32 s20, s67, s23
	v_lshl_add_u64 v[176:177], v[176:177], 0, s[26:27]
	s_mov_b32 m0, s20
	s_nop 0
	global_load_lds_dwordx4 v[176:177], off
	s_add_i32 m0, s20, 0x2000
	s_add_u32 s2, s2, 0x80080
	v_lshl_add_u64 v[176:177], v[220:221], 0, s[26:27]
	s_addc_u32 s3, s3, 0
	s_add_i32 s20, s69, s23
	global_load_lds_dwordx4 v[176:177], off
	v_lshl_add_u64 v[176:177], s[2:3], 0, v[132:133]
	s_mov_b32 m0, s20
	s_nop 0
	global_load_lds_dwordx4 v[176:177], off
	v_lshl_add_u64 v[176:177], s[2:3], 0, v[136:137]
	s_add_i32 m0, s20, 0x2000
	s_nop 0
	global_load_lds_dwordx4 v[176:177], off
	v_lshl_add_u64 v[176:177], v[236:237], 0, s[26:27]
	s_mov_b32 m0, s59
	s_nop 0
	global_load_lds_dwordx4 v[176:177], off
	v_lshl_add_u64 v[176:177], v[238:239], 0, s[26:27]
	s_mov_b32 m0, s60
	s_nop 0
	global_load_lds_dwordx4 v[176:177], off
	ds_read_b128 v[188:191], v171 offset:49152
	ds_read_b128 v[192:195], v171 offset:50176
	ds_read_b128 v[196:199], v171 offset:51200
	ds_read_b128 v[200:203], v171 offset:52224
	ds_read_b128 v[204:207], v171 offset:53248
	ds_read_b128 v[208:211], v171 offset:54272
	ds_read_b128 v[212:215], v171 offset:55296
	ds_read_b128 v[216:219], v171 offset:56320
	s_waitcnt vmcnt(8)
	s_waitcnt lgkmcnt(0)
	s_barrier
	s_setprio 1
	s_waitcnt lgkmcnt(0)
	v_mfma_f32_16x16x32_bf16 v[62:65], v[146:149], v[188:191], v[62:65]
	v_mfma_f32_16x16x32_bf16 v[58:61], v[154:157], v[188:191], v[58:61]
	v_mfma_f32_16x16x32_bf16 v[46:49], v[146:149], v[196:199], v[46:49]
	v_mfma_f32_16x16x32_bf16 v[42:45], v[154:157], v[196:199], v[42:45]
	v_mfma_f32_16x16x32_bf16 v[30:33], v[146:149], v[204:207], v[30:33]
	v_mfma_f32_16x16x32_bf16 v[26:29], v[154:157], v[204:207], v[26:29]
	v_mfma_f32_16x16x32_bf16 v[14:17], v[146:149], v[212:215], v[14:17]
	v_mfma_f32_16x16x32_bf16 v[10:13], v[154:157], v[212:215], v[10:13]
	v_mfma_f32_16x16x32_bf16 v[62:65], v[150:153], v[192:195], v[62:65]
	v_mfma_f32_16x16x32_bf16 v[58:61], v[158:161], v[192:195], v[58:61]
	v_mfma_f32_16x16x32_bf16 v[46:49], v[150:153], v[200:203], v[46:49]
	v_mfma_f32_16x16x32_bf16 v[42:45], v[158:161], v[200:203], v[42:45]
	v_mfma_f32_16x16x32_bf16 v[30:33], v[150:153], v[208:211], v[30:33]
	v_mfma_f32_16x16x32_bf16 v[26:29], v[158:161], v[208:211], v[26:29]
	v_mfma_f32_16x16x32_bf16 v[14:17], v[150:153], v[216:219], v[14:17]
	v_mfma_f32_16x16x32_bf16 v[10:13], v[158:161], v[216:219], v[10:13]
	s_setprio 0
	s_setprio 1
	v_mfma_f32_16x16x32_bf16 v[54:57], v[162:165], v[188:191], v[54:57]
	v_mfma_f32_16x16x32_bf16 v[50:53], v[180:183], v[188:191], v[50:53]
	v_mfma_f32_16x16x32_bf16 v[38:41], v[162:165], v[196:199], v[38:41]
	v_mfma_f32_16x16x32_bf16 v[34:37], v[180:183], v[196:199], v[34:37]
	v_mfma_f32_16x16x32_bf16 v[22:25], v[162:165], v[204:207], v[22:25]
	v_mfma_f32_16x16x32_bf16 v[18:21], v[180:183], v[204:207], v[18:21]
	v_mfma_f32_16x16x32_bf16 v[6:9], v[162:165], v[212:215], v[6:9]
	v_mfma_f32_16x16x32_bf16 v[2:5], v[180:183], v[212:215], v[2:5]
	v_mfma_f32_16x16x32_bf16 v[54:57], v[172:175], v[192:195], v[54:57]
	v_mfma_f32_16x16x32_bf16 v[50:53], v[184:187], v[192:195], v[50:53]
	v_mfma_f32_16x16x32_bf16 v[38:41], v[172:175], v[200:203], v[38:41]
	v_mfma_f32_16x16x32_bf16 v[34:37], v[184:187], v[200:203], v[34:37]
	v_mfma_f32_16x16x32_bf16 v[22:25], v[172:175], v[208:211], v[22:25]
	v_mfma_f32_16x16x32_bf16 v[18:21], v[184:187], v[208:211], v[18:21]
	v_mfma_f32_16x16x32_bf16 v[6:9], v[172:175], v[216:219], v[6:9]
	v_mfma_f32_16x16x32_bf16 v[2:5], v[184:187], v[216:219], v[2:5]
	s_setprio 0
	s_barrier
	s_add_i32 s65, s65, 2
	s_add_u32 s40, s40, 0x100
	s_addc_u32 s41, s41, 0
	s_add_u32 s42, s42, 0x100
	s_addc_u32 s43, s43, 0
	s_cmp_gt_u32 s65, 29
	s_cbranch_scc0 .LBB0_151
	s_and_b64 vcc, exec, s[46:47]
	s_cbranch_vccz .LBB0_154
	s_barrier

; #define PG8_STAGE(bufoff, gbase, voff) do { _Pragma("unroll") for (int _i = 0; _i < 2; ++_i) \
;         __builtin_amdgcn_global_load_lds((const unsigned*)((const char*)(gbase) + (voff)[_i]), (PG8_LAS unsigned*)(lds + (bufoff) + ldsw + _i * 8192), 16, 0, 0); } while (0)
; #define PG8_LDA(dst, b, h) do { _Pragma("unroll") for (int m = 0; m < 4; ++m) _Pragma("unroll") for (int k = 0; k < 2; ++k) dst[m][k] = *(const PG8_LAS bf16x8*)(lds + PG8_SA(b, h) + aoff + m * 2048 + k * 1024); } while (0)
; #define PG8_LDB(dst, b, h) do { _Pragma("unroll") for (int n = 0; n < 2; ++n) _Pragma("unroll") for (int k = 0; k < 2; ++k) dst[n][k] = *(const PG8_LAS bf16x8*)(lds + PG8_SB(b, h) + boff + n * 2048 + k * 1024); } while (0)
; #define PG8_MMA(ai, bj, At, Bt) do { __builtin_amdgcn_s_setprio(1); _Pragma("unroll") for (int m = 0; m < 4; ++m) _Pragma("unroll") for (int n = 0; n < 2; ++n) _Pragma("unroll") for (int k = 0; k < 2; ++k) \
;         acc[ai][bj][m][n] = __builtin_amdgcn_mfma_f32_16x16x32_bf16(Bt[n][k], At[m][k], acc[ai][bj][m][n], 0, 0, 0); __builtin_amdgcn_s_setprio(0); } while (0)
; #define PG8_WAIT_V(n) asm volatile("s_waitcnt vmcnt(" #n ")" ::: "memory")
; #define PG8_WAIT_L(n) asm volatile("s_waitcnt lgkmcnt(" #n ")" ::: "memory")
; #define PG8_BAR __builtin_amdgcn_s_barrier()
; #define PG8_SCHED __builtin_amdgcn_sched_barrier(0)
; template <class Epi, class Sched, bool ALIGN_EPI = true, bool SP2 = true, bool GS = false>
; __device__ __forceinline__ void gemm_phase(PG8_LAS unsigned char* lds, const Gemm g, const Sched& S, const Epi& E, const float* gs_ss = nullptr) {
;     ...
;             PG8_LDB(B0, 0, 0); PG8_LDB(B1, 0, 1); PG8_SCHED; PG8_LDA(At, 0, 0); PG8_STAGE(PG8_SA(1, 1), a1 + hstep, voffA);
;             PG8_WAIT_V(8); PG8_WAIT_L(0); PG8_BAR; PG8_MMA(0, 0, At, B0); PG8_MMA(0, 1, At, B1); PG8_BAR; PG8_SCHED;
;             PG8_LDA(At, 0, 1); PG8_STAGE(PG8_SB(0, 0), b2, voffB); PG8_STAGE(PG8_SB(0, 1), b2 + hstep, voffB); PG8_STAGE(PG8_SA(0, 0), a2, voffA);
;             PG8_WAIT_V(8); PG8_WAIT_L(0); PG8_BAR; PG8_MMA(1, 0, At, B0); PG8_MMA(1, 1, At, B1); PG8_BAR; PG8_SCHED;
.LBB0_314:
	s_add_u32 s2, s38, 0xfff80080
	s_addc_u32 s3, s39, -1
	s_cmp_eq_u32 s51, 28
	s_cselect_b32 s21, s13, s3
	s_cselect_b32 s20, s16, s2
	s_cselect_b32 s3, s17, s41
	s_cselect_b32 s2, s49, s40
	v_lshl_add_u64 v[170:171], s[38:39], 0, v[146:147]
	s_add_i32 m0, s24, 0xc000
	s_nop 0
	global_load_lds_dwordx4 v[170:171], off
	v_lshl_add_u64 v[170:171], s[38:39], 0, v[148:149]
	s_add_i32 m0, s24, 0xe000
	s_nop 0
	global_load_lds_dwordx4 v[170:171], off
	s_add_i32 s64, 0, 0x10000
	v_add_u32_e32 v0, s64, v173
	s_add_i32 s67, 0, 0x14000
	ds_read_b128 v[130:133], v0
	ds_read_b128 v[150:153], v0 offset:1024
	ds_read_b128 v[154:157], v0 offset:2048
	ds_read_b128 v[158:161], v0 offset:3072
	v_add_u32_e32 v0, s67, v173
	ds_read_b128 v[162:165], v0
	ds_read_b128 v[166:169], v0 offset:1024
	ds_read_b128 v[188:191], v0 offset:2048
	ds_read_b128 v[192:195], v0 offset:3072
	ds_read_b128 v[196:199], v177
	ds_read_b128 v[200:203], v177 offset:1024
	ds_read_b128 v[204:207], v177 offset:2048
	ds_read_b128 v[208:211], v177 offset:3072
	ds_read_b128 v[212:215], v177 offset:4096
	ds_read_b128 v[216:219], v177 offset:5120
	ds_read_b128 v[236:239], v177 offset:6144
	ds_read_b128 v[240:243], v177 offset:7168
	s_waitcnt vmcnt(8)
	s_waitcnt lgkmcnt(0)
	s_barrier
	s_setprio 1
	s_waitcnt lgkmcnt(0)
	v_mfma_f32_16x16x32_bf16 v[126:129], v[130:133], v[196:199], v[126:129]
	v_mfma_f32_16x16x32_bf16 v[122:125], v[154:157], v[196:199], v[122:125]
	v_mfma_f32_16x16x32_bf16 v[118:121], v[130:133], v[204:207], v[118:121]
	v_mfma_f32_16x16x32_bf16 v[110:113], v[154:157], v[204:207], v[110:113]
	v_mfma_f32_16x16x32_bf16 v[102:105], v[130:133], v[212:215], v[102:105]
	v_mfma_f32_16x16x32_bf16 v[94:97], v[154:157], v[212:215], v[94:97]
	v_mfma_f32_16x16x32_bf16 v[86:89], v[130:133], v[236:239], v[86:89]
	v_mfma_f32_16x16x32_bf16 v[78:81], v[154:157], v[236:239], v[78:81]
	v_mfma_f32_16x16x32_bf16 v[126:129], v[150:153], v[200:203], v[126:129]
	v_mfma_f32_16x16x32_bf16 v[122:125], v[158:161], v[200:203], v[122:125]
	v_mfma_f32_16x16x32_bf16 v[118:121], v[150:153], v[208:211], v[118:121]
	v_mfma_f32_16x16x32_bf16 v[110:113], v[158:161], v[208:211], v[110:113]
	v_mfma_f32_16x16x32_bf16 v[102:105], v[150:153], v[216:219], v[102:105]
	v_mfma_f32_16x16x32_bf16 v[94:97], v[158:161], v[216:219], v[94:97]
	v_mfma_f32_16x16x32_bf16 v[86:89], v[150:153], v[240:243], v[86:89]
	v_mfma_f32_16x16x32_bf16 v[78:81], v[158:161], v[240:243], v[78:81]
	s_setprio 0
	s_setprio 1
	v_mfma_f32_16x16x32_bf16 v[114:117], v[162:165], v[196:199], v[114:117]
	v_mfma_f32_16x16x32_bf16 v[106:109], v[188:191], v[196:199], v[106:109]
	v_mfma_f32_16x16x32_bf16 v[98:101], v[162:165], v[204:207], v[98:101]
	v_mfma_f32_16x16x32_bf16 v[90:93], v[188:191], v[204:207], v[90:93]
	v_mfma_f32_16x16x32_bf16 v[82:85], v[162:165], v[212:215], v[82:85]
	v_mfma_f32_16x16x32_bf16 v[74:77], v[188:191], v[212:215], v[74:77]
	v_mfma_f32_16x16x32_bf16 v[70:73], v[162:165], v[236:239], v[70:73]
	v_mfma_f32_16x16x32_bf16 v[66:69], v[188:191], v[236:239], v[66:69]
	v_mfma_f32_16x16x32_bf16 v[114:117], v[166:169], v[200:203], v[114:117]
	v_mfma_f32_16x16x32_bf16 v[106:109], v[192:195], v[200:203], v[106:109]
	v_mfma_f32_16x16x32_bf16 v[98:101], v[166:169], v[208:211], v[98:101]
	v_mfma_f32_16x16x32_bf16 v[90:93], v[192:195], v[208:211], v[90:93]
	v_mfma_f32_16x16x32_bf16 v[82:85], v[166:169], v[216:219], v[82:85]
	v_mfma_f32_16x16x32_bf16 v[74:77], v[192:195], v[216:219], v[74:77]
	v_mfma_f32_16x16x32_bf16 v[70:73], v[166:169], v[240:243], v[70:73]
	v_mfma_f32_16x16x32_bf16 v[66:69], v[192:195], v[240:243], v[66:69]
	s_setprio 0
	s_barrier
	s_add_i32 s64, s64, s23
	v_lshl_add_u64 v[170:171], s[2:3], 0, v[136:137]
	s_mov_b32 m0, s64
	s_nop 0
	global_load_lds_dwordx4 v[170:171], off
	s_add_i32 m0, s64, 0x2000
	s_add_u32 s64, s2, 0x80000
	v_lshl_add_u64 v[180:181], s[2:3], 0, v[140:141]
	s_addc_u32 s65, s3, 0
	s_add_i32 s67, s67, s23
	global_load_lds_dwordx4 v[180:181], off
	v_lshl_add_u64 v[182:183], s[64:65], 0, v[136:137]
	s_mov_b32 m0, s67
	v_lshl_add_u64 v[184:185], s[20:21], 0, v[138:139]
	global_load_lds_dwordx4 v[182:183], off
	v_lshl_add_u64 v[182:183], s[64:65], 0, v[140:141]
	s_add_i32 m0, s67, 0x2000
	s_nop 0
	global_load_lds_dwordx4 v[182:183], off
	v_lshl_add_u64 v[182:183], s[20:21], 0, v[134:135]
	s_mov_b32 m0, s24
	s_nop 0
	global_load_lds_dwordx4 v[182:183], off
	s_mov_b32 m0, s25
	s_nop 0
	global_load_lds_dwordx4 v[184:185], off
	ds_read_b128 v[196:199], v177 offset:16384
	ds_read_b128 v[200:203], v177 offset:17408
	ds_read_b128 v[204:207], v177 offset:18432
	ds_read_b128 v[208:211], v177 offset:19456
	ds_read_b128 v[212:215], v177 offset:20480
	ds_read_b128 v[216:219], v177 offset:21504
	ds_read_b128 v[236:239], v177 offset:22528
	ds_read_b128 v[240:243], v177 offset:23552
	s_waitcnt vmcnt(8)
	s_waitcnt lgkmcnt(0)
	s_barrier
; #define PG8_STAGE(bufoff, gbase, voff) do { _Pragma("unroll") for (int _i = 0; _i < 2; ++_i) \
;         __builtin_amdgcn_global_load_lds((const unsigned*)((const char*)(gbase) + (voff)[_i]), (PG8_LAS unsigned*)(lds + (bufoff) + ldsw + _i * 8192), 16, 0, 0); } while (0)
; #define PG8_LDA(dst, b, h) do { _Pragma("unroll") for (int m = 0; m < 4; ++m) _Pragma("unroll") for (int k = 0; k < 2; ++k) dst[m][k] = *(const PG8_LAS bf16x8*)(lds + PG8_SA(b, h) + aoff + m * 2048 + k * 1024); } while (0)
; #define PG8_LDB(dst, b, h) do { _Pragma("unroll") for (int n = 0; n < 2; ++n) _Pragma("unroll") for (int k = 0; k < 2; ++k) dst[n][k] = *(const PG8_LAS bf16x8*)(lds + PG8_SB(b, h) + boff + n * 2048 + k * 1024); } while (0)
; #define PG8_MMA(ai, bj, At, Bt) do { __builtin_amdgcn_s_setprio(1); _Pragma("unroll") for (int m = 0; m < 4; ++m) _Pragma("unroll") for (int n = 0; n < 2; ++n) _Pragma("unroll") for (int k = 0; k < 2; ++k) \
;         acc[ai][bj][m][n] = __builtin_amdgcn_mfma_f32_16x16x32_bf16(Bt[n][k], At[m][k], acc[ai][bj][m][n], 0, 0, 0); __builtin_amdgcn_s_setprio(0); } while (0)
; #define PG8_WAIT_V(n) asm volatile("s_waitcnt vmcnt(" #n ")" ::: "memory")
; #define PG8_WAIT_L(n) asm volatile("s_waitcnt lgkmcnt(" #n ")" ::: "memory")
; #define PG8_BAR __builtin_amdgcn_s_barrier()
; #define PG8_SCHED __builtin_amdgcn_sched_barrier(0)
; template <class Epi, class Sched, bool ALIGN_EPI = true, bool SP2 = true, bool GS = false>
; __device__ __forceinline__ void gemm_phase(PG8_LAS unsigned char* lds, const Gemm g, const Sched& S, const Epi& E, const float* gs_ss = nullptr) {
;     ...
;             PG8_WAIT_V(8); PG8_WAIT_L(0); PG8_BAR; PG8_MMA(1, 0, At, B0); PG8_MMA(1, 1, At, B1); PG8_BAR; PG8_SCHED;
;             PG8_LDB(B0, 1, 0); PG8_LDB(B1, 1, 1); PG8_SCHED; PG8_LDA(At, 1, 0); PG8_STAGE(PG8_SA(0, 1), a2 + hstep, voffA);
;             PG8_WAIT_V(8); PG8_WAIT_L(0); PG8_BAR; PG8_MMA(0, 0, At, B0); PG8_MMA(0, 1, At, B1); PG8_BAR; PG8_SCHED;
	s_setprio 1
	s_waitcnt lgkmcnt(0)
	v_mfma_f32_16x16x32_bf16 v[62:65], v[130:133], v[196:199], v[62:65]
	v_mfma_f32_16x16x32_bf16 v[58:61], v[154:157], v[196:199], v[58:61]
	v_mfma_f32_16x16x32_bf16 v[54:57], v[130:133], v[204:207], v[54:57]
	v_mfma_f32_16x16x32_bf16 v[46:49], v[154:157], v[204:207], v[46:49]
	v_mfma_f32_16x16x32_bf16 v[38:41], v[130:133], v[212:215], v[38:41]
	v_mfma_f32_16x16x32_bf16 v[30:33], v[154:157], v[212:215], v[30:33]
	v_mfma_f32_16x16x32_bf16 v[22:25], v[130:133], v[236:239], v[22:25]
	v_mfma_f32_16x16x32_bf16 v[14:17], v[154:157], v[236:239], v[14:17]
	v_mfma_f32_16x16x32_bf16 v[62:65], v[150:153], v[200:203], v[62:65]
	v_mfma_f32_16x16x32_bf16 v[58:61], v[158:161], v[200:203], v[58:61]
	v_mfma_f32_16x16x32_bf16 v[54:57], v[150:153], v[208:211], v[54:57]
	v_mfma_f32_16x16x32_bf16 v[46:49], v[158:161], v[208:211], v[46:49]
	v_mfma_f32_16x16x32_bf16 v[38:41], v[150:153], v[216:219], v[38:41]
	v_mfma_f32_16x16x32_bf16 v[30:33], v[158:161], v[216:219], v[30:33]
	v_mfma_f32_16x16x32_bf16 v[22:25], v[150:153], v[240:243], v[22:25]
	v_mfma_f32_16x16x32_bf16 v[14:17], v[158:161], v[240:243], v[14:17]
	s_setprio 0
	s_setprio 1
	v_mfma_f32_16x16x32_bf16 v[50:53], v[162:165], v[196:199], v[50:53]
	v_mfma_f32_16x16x32_bf16 v[42:45], v[188:191], v[196:199], v[42:45]
	v_mfma_f32_16x16x32_bf16 v[34:37], v[162:165], v[204:207], v[34:37]
	v_mfma_f32_16x16x32_bf16 v[26:29], v[188:191], v[204:207], v[26:29]
	v_mfma_f32_16x16x32_bf16 v[18:21], v[162:165], v[212:215], v[18:21]
	v_mfma_f32_16x16x32_bf16 v[10:13], v[188:191], v[212:215], v[10:13]
	v_mfma_f32_16x16x32_bf16 v[6:9], v[162:165], v[236:239], v[6:9]
	v_mfma_f32_16x16x32_bf16 v[2:5], v[188:191], v[236:239], v[2:5]
	v_mfma_f32_16x16x32_bf16 v[50:53], v[166:169], v[200:203], v[50:53]
	v_mfma_f32_16x16x32_bf16 v[42:45], v[192:195], v[200:203], v[42:45]
	v_mfma_f32_16x16x32_bf16 v[34:37], v[166:169], v[208:211], v[34:37]
	v_mfma_f32_16x16x32_bf16 v[26:29], v[192:195], v[208:211], v[26:29]
	v_mfma_f32_16x16x32_bf16 v[18:21], v[166:169], v[216:219], v[18:21]
	v_mfma_f32_16x16x32_bf16 v[10:13], v[192:195], v[216:219], v[10:13]
	v_mfma_f32_16x16x32_bf16 v[6:9], v[166:169], v[240:243], v[6:9]
	v_mfma_f32_16x16x32_bf16 v[2:5], v[192:195], v[240:243], v[2:5]
	s_setprio 0
	s_barrier
	s_add_u32 s20, s20, 0x80000
	s_addc_u32 s21, s21, 0
	s_mov_b32 m0, s30
	v_lshl_add_u64 v[186:187], s[20:21], 0, v[134:135]
	global_load_lds_dwordx4 v[186:187], off
	v_lshl_add_u64 v[186:187], s[20:21], 0, v[138:139]
	s_mov_b32 m0, s36
	s_nop 0
	global_load_lds_dwordx4 v[186:187], off
	s_add_i32 s64, 0, 0x18000
	v_add_u32_e32 v0, s64, v173
	s_add_i32 s65, 0, 0x1c000
	ds_read_b128 v[130:133], v0
	ds_read_b128 v[150:153], v0 offset:1024
	ds_read_b128 v[154:157], v0 offset:2048
	ds_read_b128 v[158:161], v0 offset:3072
	v_add_u32_e32 v0, s65, v173
	ds_read_b128 v[162:165], v0
	ds_read_b128 v[166:169], v0 offset:1024
	ds_read_b128 v[188:191], v0 offset:2048
	ds_read_b128 v[192:195], v0 offset:3072
	ds_read_b128 v[196:199], v177 offset:32768
	ds_read_b128 v[200:203], v177 offset:33792
	ds_read_b128 v[204:207], v177 offset:34816
	ds_read_b128 v[208:211], v177 offset:35840
	ds_read_b128 v[212:215], v177 offset:36864
	ds_read_b128 v[216:219], v177 offset:37888
	ds_read_b128 v[236:239], v177 offset:38912
	ds_read_b128 v[240:243], v177 offset:39936
	s_waitcnt vmcnt(8)
	s_waitcnt lgkmcnt(0)
	s_barrier
	s_setprio 1
	s_waitcnt lgkmcnt(0)
	v_mfma_f32_16x16x32_bf16 v[126:129], v[130:133], v[196:199], v[126:129]
	v_mfma_f32_16x16x32_bf16 v[122:125], v[154:157], v[196:199], v[122:125]
	v_mfma_f32_16x16x32_bf16 v[118:121], v[130:133], v[204:207], v[118:121]
	v_mfma_f32_16x16x32_bf16 v[110:113], v[154:157], v[204:207], v[110:113]
	v_mfma_f32_16x16x32_bf16 v[102:105], v[130:133], v[212:215], v[102:105]
	v_mfma_f32_16x16x32_bf16 v[94:97], v[154:157], v[212:215], v[94:97]
	v_mfma_f32_16x16x32_bf16 v[86:89], v[130:133], v[236:239], v[86:89]
	v_mfma_f32_16x16x32_bf16 v[78:81], v[154:157], v[236:239], v[78:81]
	v_mfma_f32_16x16x32_bf16 v[126:129], v[150:153], v[200:203], v[126:129]
	v_mfma_f32_16x16x32_bf16 v[122:125], v[158:161], v[200:203], v[122:125]
	v_mfma_f32_16x16x32_bf16 v[118:121], v[150:153], v[208:211], v[118:121]
	v_mfma_f32_16x16x32_bf16 v[110:113], v[158:161], v[208:211], v[110:113]
	v_mfma_f32_16x16x32_bf16 v[102:105], v[150:153], v[216:219], v[102:105]
	v_mfma_f32_16x16x32_bf16 v[94:97], v[158:161], v[216:219], v[94:97]
	v_mfma_f32_16x16x32_bf16 v[86:89], v[150:153], v[240:243], v[86:89]
	v_mfma_f32_16x16x32_bf16 v[78:81], v[158:161], v[240:243], v[78:81]
	s_setprio 0
	s_setprio 1
	v_mfma_f32_16x16x32_bf16 v[114:117], v[162:165], v[196:199], v[114:117]
	v_mfma_f32_16x16x32_bf16 v[106:109], v[188:191], v[196:199], v[106:109]
	v_mfma_f32_16x16x32_bf16 v[98:101], v[162:165], v[204:207], v[98:101]
	v_mfma_f32_16x16x32_bf16 v[90:93], v[188:191], v[204:207], v[90:93]
	v_mfma_f32_16x16x32_bf16 v[82:85], v[162:165], v[212:215], v[82:85]
	v_mfma_f32_16x16x32_bf16 v[74:77], v[188:191], v[212:215], v[74:77]
	v_mfma_f32_16x16x32_bf16 v[70:73], v[162:165], v[236:239], v[70:73]
	v_mfma_f32_16x16x32_bf16 v[66:69], v[188:191], v[236:239], v[66:69]
	v_mfma_f32_16x16x32_bf16 v[114:117], v[166:169], v[200:203], v[114:117]
	v_mfma_f32_16x16x32_bf16 v[106:109], v[192:195], v[200:203], v[106:109]
	v_mfma_f32_16x16x32_bf16 v[98:101], v[166:169], v[208:211], v[98:101]
	v_mfma_f32_16x16x32_bf16 v[90:93], v[192:195], v[208:211], v[90:93]
	v_mfma_f32_16x16x32_bf16 v[82:85], v[166:169], v[216:219], v[82:85]
	v_mfma_f32_16x16x32_bf16 v[74:77], v[192:195], v[216:219], v[74:77]
	v_mfma_f32_16x16x32_bf16 v[70:73], v[166:169], v[240:243], v[70:73]
	v_mfma_f32_16x16x32_bf16 v[66:69], v[192:195], v[240:243], v[66:69]
	s_setprio 0
	s_barrier
; #define PG8_LAS __attribute__((address_space(3)))
; #define PG8_STAGE(bufoff, gbase, voff) do { _Pragma("unroll") for (int _i = 0; _i < 2; ++_i) \
;         __builtin_amdgcn_global_load_lds((const unsigned*)((const char*)(gbase) + (voff)[_i]), (PG8_LAS unsigned*)(lds + (bufoff) + ldsw + _i * 8192), 16, 0, 0); } while (0)
; #define PG8_LDA(dst, b, h) do { _Pragma("unroll") for (int m = 0; m < 4; ++m) _Pragma("unroll") for (int k = 0; k < 2; ++k) dst[m][k] = *(const PG8_LAS bf16x8*)(lds + PG8_SA(b, h) + aoff + m * 2048 + k * 1024); } while (0)
; #define PG8_MMA(ai, bj, At, Bt) do { __builtin_amdgcn_s_setprio(1); _Pragma("unroll") for (int m = 0; m < 4; ++m) _Pragma("unroll") for (int n = 0; n < 2; ++n) _Pragma("unroll") for (int k = 0; k < 2; ++k) \
;         acc[ai][bj][m][n] = __builtin_amdgcn_mfma_f32_16x16x32_bf16(Bt[n][k], At[m][k], acc[ai][bj][m][n], 0, 0, 0); __builtin_amdgcn_s_setprio(0); } while (0)
; #define PG8_WAIT_V(n) asm volatile("s_waitcnt vmcnt(" #n ")" ::: "memory")
; #define PG8_WAIT_L(n) asm volatile("s_waitcnt lgkmcnt(" #n ")" ::: "memory")
; #define PG8_BAR __builtin_amdgcn_s_barrier()
; #define PG8_SCHED __builtin_amdgcn_sched_barrier(0)
; template <class Epi, class Sched, bool ALIGN_EPI = true, bool SP2 = true, bool GS = false>
; __device__ __forceinline__ void gemm_phase(PG8_LAS unsigned char* lds, const Gemm g, const Sched& S, const Epi& E, const float* gs_ss = nullptr) {
;     ...
;             PG8_LDA(At, 1, 1); PG8_STAGE(PG8_SB(1, 0), b3, voffB); PG8_STAGE(PG8_SB(1, 1), b3 + hstep, voffB); PG8_STAGE(PG8_SA(1, 0), a3, voffA);
;             PG8_WAIT_V(8); PG8_WAIT_L(0); PG8_BAR; PG8_MMA(1, 0, At, B0); PG8_MMA(1, 1, At, B1); PG8_BAR; PG8_SCHED;
;     ...
;         if constexpr (ALIGN_EPI) { if (wr == 0) PG8_BAR; }
;         if constexpr (GS) E.gs(acc, cur, wr, wc, fr, fq, (const PG8_LAS float*)(lds + STAGE_BYTES + gpar * 4096)); else E(acc, cur, wr, wc, fr, fq);
;         if (!has_next) break;
	s_add_i32 s20, s64, s23
	v_lshl_add_u64 v[170:171], v[170:171], 0, s[26:27]
	s_mov_b32 m0, s20
	s_nop 0
	global_load_lds_dwordx4 v[170:171], off
	s_add_i32 m0, s20, 0x2000
	s_add_u32 s2, s2, 0x80080
	v_lshl_add_u64 v[170:171], v[180:181], 0, s[26:27]
	s_addc_u32 s3, s3, 0
	s_add_i32 s20, s65, s23
	global_load_lds_dwordx4 v[170:171], off
	v_lshl_add_u64 v[170:171], s[2:3], 0, v[136:137]
	s_mov_b32 m0, s20
	s_nop 0
	global_load_lds_dwordx4 v[170:171], off
	v_lshl_add_u64 v[170:171], s[2:3], 0, v[140:141]
	s_add_i32 m0, s20, 0x2000
	s_nop 0
	global_load_lds_dwordx4 v[170:171], off
	v_lshl_add_u64 v[170:171], v[182:183], 0, s[26:27]
	s_mov_b32 m0, s59
	s_nop 0
	global_load_lds_dwordx4 v[170:171], off
	v_lshl_add_u64 v[170:171], v[184:185], 0, s[26:27]
	s_mov_b32 m0, s60
	s_nop 0
	global_load_lds_dwordx4 v[170:171], off
	ds_read_b128 v[196:199], v177 offset:49152
	ds_read_b128 v[200:203], v177 offset:50176
	ds_read_b128 v[204:207], v177 offset:51200
	ds_read_b128 v[208:211], v177 offset:52224
	ds_read_b128 v[212:215], v177 offset:53248
	ds_read_b128 v[216:219], v177 offset:54272
	ds_read_b128 v[236:239], v177 offset:55296
	ds_read_b128 v[240:243], v177 offset:56320
	s_waitcnt vmcnt(8)
	s_waitcnt lgkmcnt(0)
	s_barrier
	s_setprio 1
	s_waitcnt lgkmcnt(0)
	v_mfma_f32_16x16x32_bf16 v[62:65], v[130:133], v[196:199], v[62:65]
	v_mfma_f32_16x16x32_bf16 v[58:61], v[154:157], v[196:199], v[58:61]
	v_mfma_f32_16x16x32_bf16 v[54:57], v[130:133], v[204:207], v[54:57]
	v_mfma_f32_16x16x32_bf16 v[46:49], v[154:157], v[204:207], v[46:49]
	v_mfma_f32_16x16x32_bf16 v[38:41], v[130:133], v[212:215], v[38:41]
	v_mfma_f32_16x16x32_bf16 v[30:33], v[154:157], v[212:215], v[30:33]
	v_mfma_f32_16x16x32_bf16 v[22:25], v[130:133], v[236:239], v[22:25]
	v_mfma_f32_16x16x32_bf16 v[14:17], v[154:157], v[236:239], v[14:17]
	v_mfma_f32_16x16x32_bf16 v[62:65], v[150:153], v[200:203], v[62:65]
	v_mfma_f32_16x16x32_bf16 v[58:61], v[158:161], v[200:203], v[58:61]
	v_mfma_f32_16x16x32_bf16 v[54:57], v[150:153], v[208:211], v[54:57]
	v_mfma_f32_16x16x32_bf16 v[46:49], v[158:161], v[208:211], v[46:49]
	v_mfma_f32_16x16x32_bf16 v[38:41], v[150:153], v[216:219], v[38:41]
	v_mfma_f32_16x16x32_bf16 v[30:33], v[158:161], v[216:219], v[30:33]
	v_mfma_f32_16x16x32_bf16 v[22:25], v[150:153], v[240:243], v[22:25]
	v_mfma_f32_16x16x32_bf16 v[14:17], v[158:161], v[240:243], v[14:17]
	s_setprio 0
	s_setprio 1
	v_mfma_f32_16x16x32_bf16 v[50:53], v[162:165], v[196:199], v[50:53]
	v_mfma_f32_16x16x32_bf16 v[42:45], v[188:191], v[196:199], v[42:45]
	v_mfma_f32_16x16x32_bf16 v[34:37], v[162:165], v[204:207], v[34:37]
	v_mfma_f32_16x16x32_bf16 v[26:29], v[188:191], v[204:207], v[26:29]
	v_mfma_f32_16x16x32_bf16 v[18:21], v[162:165], v[212:215], v[18:21]
	v_mfma_f32_16x16x32_bf16 v[10:13], v[188:191], v[212:215], v[10:13]
	v_mfma_f32_16x16x32_bf16 v[6:9], v[162:165], v[236:239], v[6:9]
	v_mfma_f32_16x16x32_bf16 v[2:5], v[188:191], v[236:239], v[2:5]
	v_mfma_f32_16x16x32_bf16 v[50:53], v[166:169], v[200:203], v[50:53]
	v_mfma_f32_16x16x32_bf16 v[42:45], v[192:195], v[200:203], v[42:45]
	v_mfma_f32_16x16x32_bf16 v[34:37], v[166:169], v[208:211], v[34:37]
	v_mfma_f32_16x16x32_bf16 v[26:29], v[192:195], v[208:211], v[26:29]
	v_mfma_f32_16x16x32_bf16 v[18:21], v[166:169], v[216:219], v[18:21]
	v_mfma_f32_16x16x32_bf16 v[10:13], v[192:195], v[216:219], v[10:13]
	v_mfma_f32_16x16x32_bf16 v[6:9], v[166:169], v[240:243], v[6:9]
	v_mfma_f32_16x16x32_bf16 v[2:5], v[192:195], v[240:243], v[2:5]
	s_setprio 0
	s_barrier
	s_add_i32 s51, s51, 2
	s_add_u32 s38, s38, 0x100
	s_addc_u32 s39, s39, 0
	s_add_u32 s40, s40, 0x100
	s_addc_u32 s41, s41, 0
	s_cmp_gt_u32 s51, 29
	s_cbranch_scc0 .LBB0_314
	s_and_b64 vcc, exec, s[42:43]
	s_cbranch_vccz .LBB0_319
	s_barrier
	s_lshl_b32 s16, s12, 8
	s_cmp_lt_i32 s46, 14
	s_mov_b64 s[2:3], -1
	s_cbranch_scc1 .LBB0_320

; #define PG8_STAGE(bufoff, gbase, voff) do { _Pragma("unroll") for (int _i = 0; _i < 2; ++_i) \
;         __builtin_amdgcn_global_load_lds((const unsigned*)((const char*)(gbase) + (voff)[_i]), (PG8_LAS unsigned*)(lds + (bufoff) + ldsw + _i * 8192), 16, 0, 0); } while (0)
; #define PG8_LDA(dst, b, h) do { _Pragma("unroll") for (int m = 0; m < 4; ++m) _Pragma("unroll") for (int k = 0; k < 2; ++k) dst[m][k] = *(const PG8_LAS bf16x8*)(lds + PG8_SA(b, h) + aoff + m * 2048 + k * 1024); } while (0)
; #define PG8_LDB(dst, b, h) do { _Pragma("unroll") for (int n = 0; n < 2; ++n) _Pragma("unroll") for (int k = 0; k < 2; ++k) dst[n][k] = *(const PG8_LAS bf16x8*)(lds + PG8_SB(b, h) + boff + n * 2048 + k * 1024); } while (0)
; #define PG8_MMA(ai, bj, At, Bt) do { __builtin_amdgcn_s_setprio(1); _Pragma("unroll") for (int m = 0; m < 4; ++m) _Pragma("unroll") for (int n = 0; n < 2; ++n) _Pragma("unroll") for (int k = 0; k < 2; ++k) \
;         acc[ai][bj][m][n] = __builtin_amdgcn_mfma_f32_16x16x32_bf16(Bt[n][k], At[m][k], acc[ai][bj][m][n], 0, 0, 0); __builtin_amdgcn_s_setprio(0); } while (0)
; #define PG8_WAIT_V(n) asm volatile("s_waitcnt vmcnt(" #n ")" ::: "memory")
; #define PG8_WAIT_L(n) asm volatile("s_waitcnt lgkmcnt(" #n ")" ::: "memory")
; #define PG8_BAR __builtin_amdgcn_s_barrier()
; #define PG8_SCHED __builtin_amdgcn_sched_barrier(0)
; template <class Epi, class Sched, bool ALIGN_EPI = true, bool SP2 = true, bool GS = false>
; __device__ __forceinline__ void gemm_phase(PG8_LAS unsigned char* lds, const Gemm g, const Sched& S, const Epi& E, const float* gs_ss = nullptr) {
;     ...
;             PG8_LDB(B0, 0, 0); PG8_LDB(B1, 0, 1); PG8_SCHED; PG8_LDA(At, 0, 0); PG8_STAGE(PG8_SA(1, 1), a1 + hstep, voffA);
;             PG8_WAIT_V(8); PG8_WAIT_L(0); PG8_BAR; PG8_MMA(0, 0, At, B0); PG8_MMA(0, 1, At, B1); PG8_BAR; PG8_SCHED;
;             PG8_LDA(At, 0, 1); PG8_STAGE(PG8_SB(0, 0), b2, voffB); PG8_STAGE(PG8_SB(0, 1), b2 + hstep, voffB); PG8_STAGE(PG8_SA(0, 0), a2, voffA);
;             PG8_WAIT_V(8); PG8_WAIT_L(0); PG8_BAR; PG8_MMA(1, 0, At, B0); PG8_MMA(1, 1, At, B1); PG8_BAR; PG8_SCHED;
.LBB0_788:
	s_add_u32 s2, s34, 0xfffe0080
	s_addc_u32 s3, s35, -1
	s_cmp_eq_u32 s41, 4
	s_cselect_b32 s21, s16, s3
	s_cselect_b32 s20, s17, s2
	s_cselect_b32 s3, s13, s40
	s_cselect_b32 s2, s18, s29
	v_lshl_add_u64 v[180:181], s[34:35], 0, v[196:197]
	s_add_i32 m0, s37, 0xc000
	s_nop 0
	global_load_lds_dwordx4 v[180:181], off
	v_lshl_add_u64 v[180:181], s[34:35], 0, v[198:199]
	s_add_i32 m0, s37, 0xe000
	s_nop 0
	global_load_lds_dwordx4 v[180:181], off
	s_add_i32 s42, 0, 0x10000
	v_add_u32_e32 v0, s42, v183
	s_add_i32 s57, 0, 0x14000
	ds_read_b128 v[18:21], v0
	ds_read_b128 v[26:29], v0 offset:1024
	ds_read_b128 v[30:33], v0 offset:2048
	ds_read_b128 v[38:41], v0 offset:3072
	v_add_u32_e32 v0, s57, v183
	ds_read_b128 v[42:45], v0
	ds_read_b128 v[46:49], v0 offset:1024
	ds_read_b128 v[58:61], v0 offset:2048
	ds_read_b128 v[70:73], v0 offset:3072
	ds_read_b128 v[82:85], v219
	ds_read_b128 v[94:97], v219 offset:1024
	ds_read_b128 v[106:109], v219 offset:2048
	ds_read_b128 v[118:121], v219 offset:3072
	ds_read_b128 v[184:187], v219 offset:4096
	ds_read_b128 v[200:203], v219 offset:5120
	ds_read_b128 v[204:207], v219 offset:6144
	ds_read_b128 v[208:211], v219 offset:7168
	s_waitcnt vmcnt(8)
	s_waitcnt lgkmcnt(0)
	s_barrier
	s_setprio 1
	s_waitcnt lgkmcnt(0)
	v_mfma_f32_16x16x32_bf16 v[174:177], v[18:21], v[82:85], v[174:177]
	v_mfma_f32_16x16x32_bf16 v[170:173], v[30:33], v[82:85], v[170:173]
	v_mfma_f32_16x16x32_bf16 v[158:161], v[18:21], v[106:109], v[158:161]
	v_mfma_f32_16x16x32_bf16 v[154:157], v[30:33], v[106:109], v[154:157]
	v_mfma_f32_16x16x32_bf16 v[142:145], v[18:21], v[184:187], v[142:145]
	v_mfma_f32_16x16x32_bf16 v[138:141], v[30:33], v[184:187], v[138:141]
	v_mfma_f32_16x16x32_bf16 v[126:129], v[18:21], v[204:207], v[126:129]
	v_mfma_f32_16x16x32_bf16 v[122:125], v[30:33], v[204:207], v[122:125]
	v_mfma_f32_16x16x32_bf16 v[174:177], v[26:29], v[94:97], v[174:177]
	v_mfma_f32_16x16x32_bf16 v[170:173], v[38:41], v[94:97], v[170:173]
	v_mfma_f32_16x16x32_bf16 v[158:161], v[26:29], v[118:121], v[158:161]
	v_mfma_f32_16x16x32_bf16 v[154:157], v[38:41], v[118:121], v[154:157]
	v_mfma_f32_16x16x32_bf16 v[142:145], v[26:29], v[200:203], v[142:145]
	v_mfma_f32_16x16x32_bf16 v[138:141], v[38:41], v[200:203], v[138:141]
	v_mfma_f32_16x16x32_bf16 v[126:129], v[26:29], v[208:211], v[126:129]
	v_mfma_f32_16x16x32_bf16 v[122:125], v[38:41], v[208:211], v[122:125]
	s_setprio 0
	s_setprio 1
	v_mfma_f32_16x16x32_bf16 v[166:169], v[42:45], v[82:85], v[166:169]
	v_mfma_f32_16x16x32_bf16 v[82:85], v[58:61], v[82:85], v[162:165]
	v_mfma_f32_16x16x32_bf16 v[166:169], v[46:49], v[94:97], v[166:169]
	v_mfma_f32_16x16x32_bf16 v[82:85], v[70:73], v[94:97], v[82:85]
	v_mfma_f32_16x16x32_bf16 v[94:97], v[42:45], v[106:109], v[150:153]
	v_mfma_f32_16x16x32_bf16 v[106:109], v[58:61], v[106:109], v[146:149]
	v_mfma_f32_16x16x32_bf16 v[130:133], v[58:61], v[184:187], v[130:133]
	v_mfma_f32_16x16x32_bf16 v[114:117], v[42:45], v[204:207], v[114:117]
	v_mfma_f32_16x16x32_bf16 v[110:113], v[58:61], v[204:207], v[110:113]
	v_mfma_f32_16x16x32_bf16 v[94:97], v[46:49], v[118:121], v[94:97]
	v_mfma_f32_16x16x32_bf16 v[106:109], v[70:73], v[118:121], v[106:109]
	v_mfma_f32_16x16x32_bf16 v[118:121], v[42:45], v[184:187], v[134:137]
	v_mfma_f32_16x16x32_bf16 v[130:133], v[70:73], v[200:203], v[130:133]
	v_mfma_f32_16x16x32_bf16 v[114:117], v[46:49], v[208:211], v[114:117]
	v_mfma_f32_16x16x32_bf16 v[110:113], v[70:73], v[208:211], v[110:113]
	v_mfma_f32_16x16x32_bf16 v[118:121], v[46:49], v[200:203], v[118:121]
	s_setprio 0
	s_barrier
	s_add_i32 s42, s42, s25
	v_lshl_add_u64 v[180:181], s[2:3], 0, v[190:191]
	s_mov_b32 m0, s42
	s_nop 0
	global_load_lds_dwordx4 v[180:181], off
	s_add_i32 m0, s42, 0x2000
	s_add_u32 s42, s2, 0x20000
	v_lshl_add_u64 v[216:217], s[2:3], 0, v[194:195]
	s_addc_u32 s43, s3, 0
	s_add_i32 s57, s57, s25
	global_load_lds_dwordx4 v[216:217], off
	v_lshl_add_u64 v[212:213], s[42:43], 0, v[190:191]
	s_mov_b32 m0, s57
	v_lshl_add_u64 v[220:221], s[20:21], 0, v[188:189]
	global_load_lds_dwordx4 v[212:213], off
	v_lshl_add_u64 v[212:213], s[42:43], 0, v[194:195]
	s_add_i32 m0, s57, 0x2000
	v_lshl_add_u64 v[244:245], s[20:21], 0, v[192:193]
	global_load_lds_dwordx4 v[212:213], off
	s_mov_b32 m0, s37
	s_nop 0
	global_load_lds_dwordx4 v[220:221], off
	s_mov_b32 m0, s59
	s_nop 0
	global_load_lds_dwordx4 v[244:245], off
	ds_read_b128 v[134:137], v219 offset:16384
	ds_read_b128 v[146:149], v219 offset:17408
	ds_read_b128 v[150:153], v219 offset:18432
	ds_read_b128 v[162:165], v219 offset:19456
	ds_read_b128 v[184:187], v219 offset:20480
	ds_read_b128 v[200:203], v219 offset:21504
	ds_read_b128 v[204:207], v219 offset:22528
	ds_read_b128 v[208:211], v219 offset:23552
	s_waitcnt vmcnt(8)
	s_waitcnt lgkmcnt(0)
	s_barrier
; #define PG8_STAGE(bufoff, gbase, voff) do { _Pragma("unroll") for (int _i = 0; _i < 2; ++_i) \
;         __builtin_amdgcn_global_load_lds((const unsigned*)((const char*)(gbase) + (voff)[_i]), (PG8_LAS unsigned*)(lds + (bufoff) + ldsw + _i * 8192), 16, 0, 0); } while (0)
; #define PG8_LDA(dst, b, h) do { _Pragma("unroll") for (int m = 0; m < 4; ++m) _Pragma("unroll") for (int k = 0; k < 2; ++k) dst[m][k] = *(const PG8_LAS bf16x8*)(lds + PG8_SA(b, h) + aoff + m * 2048 + k * 1024); } while (0)
; #define PG8_LDB(dst, b, h) do { _Pragma("unroll") for (int n = 0; n < 2; ++n) _Pragma("unroll") for (int k = 0; k < 2; ++k) dst[n][k] = *(const PG8_LAS bf16x8*)(lds + PG8_SB(b, h) + boff + n * 2048 + k * 1024); } while (0)
; #define PG8_MMA(ai, bj, At, Bt) do { __builtin_amdgcn_s_setprio(1); _Pragma("unroll") for (int m = 0; m < 4; ++m) _Pragma("unroll") for (int n = 0; n < 2; ++n) _Pragma("unroll") for (int k = 0; k < 2; ++k) \
;         acc[ai][bj][m][n] = __builtin_amdgcn_mfma_f32_16x16x32_bf16(Bt[n][k], At[m][k], acc[ai][bj][m][n], 0, 0, 0); __builtin_amdgcn_s_setprio(0); } while (0)
; #define PG8_WAIT_V(n) asm volatile("s_waitcnt vmcnt(" #n ")" ::: "memory")
; #define PG8_WAIT_L(n) asm volatile("s_waitcnt lgkmcnt(" #n ")" ::: "memory")
; #define PG8_BAR __builtin_amdgcn_s_barrier()
; #define PG8_SCHED __builtin_amdgcn_sched_barrier(0)
; template <class Epi, class Sched, bool ALIGN_EPI = true, bool SP2 = true, bool GS = false>
; __device__ __forceinline__ void gemm_phase(PG8_LAS unsigned char* lds, const Gemm g, const Sched& S, const Epi& E, const float* gs_ss = nullptr) {
;     ...
;             PG8_WAIT_V(8); PG8_WAIT_L(0); PG8_BAR; PG8_MMA(1, 0, At, B0); PG8_MMA(1, 1, At, B1); PG8_BAR; PG8_SCHED;
;             PG8_LDB(B0, 1, 0); PG8_LDB(B1, 1, 1); PG8_SCHED; PG8_LDA(At, 1, 0); PG8_STAGE(PG8_SA(0, 1), a2 + hstep, voffA);
;             PG8_WAIT_V(8); PG8_WAIT_L(0); PG8_BAR; PG8_MMA(0, 0, At, B0); PG8_MMA(0, 1, At, B1); PG8_BAR; PG8_SCHED;
	s_setprio 1
	s_waitcnt lgkmcnt(0)
	v_mfma_f32_16x16x32_bf16 v[102:105], v[18:21], v[134:137], v[102:105]
	v_mfma_f32_16x16x32_bf16 v[98:101], v[30:33], v[134:137], v[98:101]
	v_mfma_f32_16x16x32_bf16 v[78:81], v[18:21], v[150:153], v[78:81]
	v_mfma_f32_16x16x32_bf16 v[74:77], v[30:33], v[150:153], v[74:77]
	v_mfma_f32_16x16x32_bf16 v[54:57], v[18:21], v[184:187], v[54:57]
	v_mfma_f32_16x16x32_bf16 v[50:53], v[30:33], v[184:187], v[50:53]
	v_mfma_f32_16x16x32_bf16 v[14:17], v[18:21], v[204:207], v[14:17]
	v_mfma_f32_16x16x32_bf16 v[10:13], v[30:33], v[204:207], v[10:13]
	v_mfma_f32_16x16x32_bf16 v[102:105], v[26:29], v[146:149], v[102:105]
	v_mfma_f32_16x16x32_bf16 v[98:101], v[38:41], v[146:149], v[98:101]
	v_mfma_f32_16x16x32_bf16 v[78:81], v[26:29], v[162:165], v[78:81]
	v_mfma_f32_16x16x32_bf16 v[74:77], v[38:41], v[162:165], v[74:77]
	v_mfma_f32_16x16x32_bf16 v[54:57], v[26:29], v[200:203], v[54:57]
	v_mfma_f32_16x16x32_bf16 v[50:53], v[38:41], v[200:203], v[50:53]
	v_mfma_f32_16x16x32_bf16 v[14:17], v[26:29], v[208:211], v[14:17]
	v_mfma_f32_16x16x32_bf16 v[10:13], v[38:41], v[208:211], v[10:13]
	s_setprio 0
	s_setprio 1
	v_mfma_f32_16x16x32_bf16 v[34:37], v[42:45], v[184:187], v[34:37]
	v_mfma_f32_16x16x32_bf16 v[22:25], v[58:61], v[184:187], v[22:25]
	v_mfma_f32_16x16x32_bf16 v[6:9], v[42:45], v[204:207], v[6:9]
	v_mfma_f32_16x16x32_bf16 v[2:5], v[58:61], v[204:207], v[2:5]
	v_mfma_f32_16x16x32_bf16 v[18:21], v[42:45], v[134:137], v[90:93]
	v_mfma_f32_16x16x32_bf16 v[26:29], v[58:61], v[134:137], v[86:89]
	v_mfma_f32_16x16x32_bf16 v[30:33], v[42:45], v[150:153], v[66:69]
	v_mfma_f32_16x16x32_bf16 v[38:41], v[58:61], v[150:153], v[62:65]
	v_mfma_f32_16x16x32_bf16 v[34:37], v[46:49], v[200:203], v[34:37]
	v_mfma_f32_16x16x32_bf16 v[22:25], v[70:73], v[200:203], v[22:25]
	v_mfma_f32_16x16x32_bf16 v[6:9], v[46:49], v[208:211], v[6:9]
	v_mfma_f32_16x16x32_bf16 v[2:5], v[70:73], v[208:211], v[2:5]
	v_mfma_f32_16x16x32_bf16 v[18:21], v[46:49], v[146:149], v[18:21]
	v_mfma_f32_16x16x32_bf16 v[26:29], v[70:73], v[146:149], v[26:29]
	v_mfma_f32_16x16x32_bf16 v[30:33], v[46:49], v[162:165], v[30:33]
	v_mfma_f32_16x16x32_bf16 v[38:41], v[70:73], v[162:165], v[38:41]
	s_setprio 0
	s_barrier
	s_add_u32 s20, s20, 0x20000
	s_addc_u32 s21, s21, 0
	s_mov_b32 m0, s69
	v_lshl_add_u64 v[146:147], s[20:21], 0, v[188:189]
	global_load_lds_dwordx4 v[146:147], off
	v_lshl_add_u64 v[146:147], s[20:21], 0, v[192:193]
	s_mov_b32 m0, s64
	s_nop 0
	global_load_lds_dwordx4 v[146:147], off
	s_add_i32 s42, 0, 0x18000
	v_add_u32_e32 v0, s42, v183
	s_add_i32 s43, 0, 0x1c000
	ds_read_b128 v[42:45], v0
	ds_read_b128 v[46:49], v0 offset:1024
	ds_read_b128 v[58:61], v0 offset:2048
	ds_read_b128 v[62:65], v0 offset:3072
	v_add_u32_e32 v0, s43, v183
	ds_read_b128 v[70:73], v0
	ds_read_b128 v[184:187], v0 offset:1024
	ds_read_b128 v[200:203], v0 offset:2048
	ds_read_b128 v[204:207], v0 offset:3072
	ds_read_b128 v[66:69], v219 offset:32768
	ds_read_b128 v[86:89], v219 offset:33792
	ds_read_b128 v[90:93], v219 offset:34816
	ds_read_b128 v[134:137], v219 offset:35840
	ds_read_b128 v[208:211], v219 offset:36864
	ds_read_b128 v[212:215], v219 offset:37888
	ds_read_b128 v[236:239], v219 offset:38912
	ds_read_b128 v[240:243], v219 offset:39936
	s_waitcnt vmcnt(8)
	s_waitcnt lgkmcnt(0)
	s_barrier
	s_setprio 1
	s_waitcnt lgkmcnt(0)
	v_mfma_f32_16x16x32_bf16 v[146:149], v[42:45], v[66:69], v[174:177]
	v_mfma_f32_16x16x32_bf16 v[174:177], v[46:49], v[86:89], v[146:149]
	v_mfma_f32_16x16x32_bf16 v[146:149], v[58:61], v[66:69], v[170:173]
	v_mfma_f32_16x16x32_bf16 v[170:173], v[62:65], v[86:89], v[146:149]
	v_mfma_f32_16x16x32_bf16 v[146:149], v[42:45], v[90:93], v[158:161]
	v_mfma_f32_16x16x32_bf16 v[158:161], v[46:49], v[134:137], v[146:149]
	v_mfma_f32_16x16x32_bf16 v[146:149], v[58:61], v[90:93], v[154:157]
	v_mfma_f32_16x16x32_bf16 v[142:145], v[42:45], v[208:211], v[142:145]
	v_mfma_f32_16x16x32_bf16 v[138:141], v[58:61], v[208:211], v[138:141]
	v_mfma_f32_16x16x32_bf16 v[126:129], v[42:45], v[236:239], v[126:129]
	v_mfma_f32_16x16x32_bf16 v[122:125], v[58:61], v[236:239], v[122:125]
	v_mfma_f32_16x16x32_bf16 v[154:157], v[62:65], v[134:137], v[146:149]
	v_mfma_f32_16x16x32_bf16 v[142:145], v[46:49], v[212:215], v[142:145]
	v_mfma_f32_16x16x32_bf16 v[138:141], v[62:65], v[212:215], v[138:141]
	v_mfma_f32_16x16x32_bf16 v[126:129], v[46:49], v[240:243], v[126:129]
	v_mfma_f32_16x16x32_bf16 v[122:125], v[62:65], v[240:243], v[122:125]
	s_setprio 0
	s_setprio 1
	v_mfma_f32_16x16x32_bf16 v[146:149], v[70:73], v[66:69], v[166:169]
	v_mfma_f32_16x16x32_bf16 v[66:69], v[200:203], v[66:69], v[82:85]
	v_mfma_f32_16x16x32_bf16 v[162:165], v[204:207], v[86:89], v[66:69]
	v_mfma_f32_16x16x32_bf16 v[66:69], v[70:73], v[90:93], v[94:97]
	v_mfma_f32_16x16x32_bf16 v[150:153], v[184:187], v[134:137], v[66:69]
	v_mfma_f32_16x16x32_bf16 v[66:69], v[200:203], v[90:93], v[106:109]
	v_mfma_f32_16x16x32_bf16 v[166:169], v[184:187], v[86:89], v[146:149]
	v_mfma_f32_16x16x32_bf16 v[146:149], v[204:207], v[134:137], v[66:69]
	v_mfma_f32_16x16x32_bf16 v[66:69], v[70:73], v[208:211], v[118:121]
	v_mfma_f32_16x16x32_bf16 v[134:137], v[184:187], v[212:215], v[66:69]
	v_mfma_f32_16x16x32_bf16 v[66:69], v[200:203], v[208:211], v[130:133]
	v_mfma_f32_16x16x32_bf16 v[130:133], v[204:207], v[212:215], v[66:69]
	v_mfma_f32_16x16x32_bf16 v[66:69], v[70:73], v[236:239], v[114:117]
	v_mfma_f32_16x16x32_bf16 v[114:117], v[184:187], v[240:243], v[66:69]
	v_mfma_f32_16x16x32_bf16 v[66:69], v[200:203], v[236:239], v[110:113]
	v_mfma_f32_16x16x32_bf16 v[110:113], v[204:207], v[240:243], v[66:69]
	s_setprio 0
	s_barrier
; #define PG8_LAS __attribute__((address_space(3)))
; #define PG8_STAGE(bufoff, gbase, voff) do { _Pragma("unroll") for (int _i = 0; _i < 2; ++_i) \
;         __builtin_amdgcn_global_load_lds((const unsigned*)((const char*)(gbase) + (voff)[_i]), (PG8_LAS unsigned*)(lds + (bufoff) + ldsw + _i * 8192), 16, 0, 0); } while (0)
; #define PG8_LDA(dst, b, h) do { _Pragma("unroll") for (int m = 0; m < 4; ++m) _Pragma("unroll") for (int k = 0; k < 2; ++k) dst[m][k] = *(const PG8_LAS bf16x8*)(lds + PG8_SA(b, h) + aoff + m * 2048 + k * 1024); } while (0)
; #define PG8_MMA(ai, bj, At, Bt) do { __builtin_amdgcn_s_setprio(1); _Pragma("unroll") for (int m = 0; m < 4; ++m) _Pragma("unroll") for (int n = 0; n < 2; ++n) _Pragma("unroll") for (int k = 0; k < 2; ++k) \
;         acc[ai][bj][m][n] = __builtin_amdgcn_mfma_f32_16x16x32_bf16(Bt[n][k], At[m][k], acc[ai][bj][m][n], 0, 0, 0); __builtin_amdgcn_s_setprio(0); } while (0)
; #define PG8_WAIT_V(n) asm volatile("s_waitcnt vmcnt(" #n ")" ::: "memory")
; #define PG8_WAIT_L(n) asm volatile("s_waitcnt lgkmcnt(" #n ")" ::: "memory")
; #define PG8_BAR __builtin_amdgcn_s_barrier()
; #define PG8_SCHED __builtin_amdgcn_sched_barrier(0)
; template <class Epi, class Sched, bool ALIGN_EPI = true, bool SP2 = true, bool GS = false>
; __device__ __forceinline__ void gemm_phase(PG8_LAS unsigned char* lds, const Gemm g, const Sched& S, const Epi& E, const float* gs_ss = nullptr) {
;     ...
;             PG8_LDA(At, 1, 1); PG8_STAGE(PG8_SB(1, 0), b3, voffB); PG8_STAGE(PG8_SB(1, 1), b3 + hstep, voffB); PG8_STAGE(PG8_SA(1, 0), a3, voffA);
;             PG8_WAIT_V(8); PG8_WAIT_L(0); PG8_BAR; PG8_MMA(1, 0, At, B0); PG8_MMA(1, 1, At, B1); PG8_BAR; PG8_SCHED;
;     ...
;         if constexpr (ALIGN_EPI) { if (wr == 0) PG8_BAR; }
;         if constexpr (GS) E.gs(acc, cur, wr, wc, fr, fq, (const PG8_LAS float*)(lds + STAGE_BYTES + gpar * 4096)); else E(acc, cur, wr, wc, fr, fq);
;         if (!has_next) break;
	s_add_i32 s20, s42, s25
	v_lshl_add_u64 v[86:87], v[180:181], 0, s[26:27]
	s_mov_b32 m0, s20
	s_nop 1
	global_load_lds_dwordx4 v[86:87], off
	s_add_i32 m0, s20, 0x2000
	s_add_u32 s2, s2, 0x20080
	v_lshl_add_u64 v[86:87], v[216:217], 0, s[26:27]
	s_addc_u32 s3, s3, 0
	s_add_i32 s20, s43, s25
	global_load_lds_dwordx4 v[86:87], off
	v_lshl_add_u64 v[86:87], s[2:3], 0, v[190:191]
	s_mov_b32 m0, s20
	s_nop 0
	global_load_lds_dwordx4 v[86:87], off
	v_lshl_add_u64 v[86:87], s[2:3], 0, v[194:195]
	s_add_i32 m0, s20, 0x2000
	s_nop 0
	global_load_lds_dwordx4 v[86:87], off
	v_lshl_add_u64 v[86:87], v[220:221], 0, s[26:27]
	s_mov_b32 m0, s30
	s_nop 0
	global_load_lds_dwordx4 v[86:87], off
	v_lshl_add_u64 v[86:87], v[244:245], 0, s[26:27]
	s_mov_b32 m0, s14
	s_nop 0
	global_load_lds_dwordx4 v[86:87], off
	ds_read_b128 v[66:69], v219 offset:49152
	ds_read_b128 v[82:85], v219 offset:50176
	ds_read_b128 v[94:97], v219 offset:51200
	ds_read_b128 v[106:109], v219 offset:52224
	ds_read_b128 v[118:121], v219 offset:53248
	ds_read_b128 v[208:211], v219 offset:54272
	ds_read_b128 v[212:215], v219 offset:55296
	ds_read_b128 v[236:239], v219 offset:56320
	s_waitcnt vmcnt(8)
	s_waitcnt lgkmcnt(0)
	s_barrier
	s_setprio 1
	s_waitcnt lgkmcnt(0)
	v_mfma_f32_16x16x32_bf16 v[86:89], v[42:45], v[66:69], v[102:105]
	v_mfma_f32_16x16x32_bf16 v[102:105], v[46:49], v[82:85], v[86:89]
	v_mfma_f32_16x16x32_bf16 v[86:89], v[58:61], v[66:69], v[98:101]
	v_mfma_f32_16x16x32_bf16 v[78:81], v[42:45], v[94:97], v[78:81]
	v_mfma_f32_16x16x32_bf16 v[74:77], v[58:61], v[94:97], v[74:77]
	v_mfma_f32_16x16x32_bf16 v[54:57], v[42:45], v[118:121], v[54:57]
	v_mfma_f32_16x16x32_bf16 v[50:53], v[58:61], v[118:121], v[50:53]
	v_mfma_f32_16x16x32_bf16 v[14:17], v[42:45], v[212:215], v[14:17]
	v_mfma_f32_16x16x32_bf16 v[10:13], v[58:61], v[212:215], v[10:13]
	v_mfma_f32_16x16x32_bf16 v[98:101], v[62:65], v[82:85], v[86:89]
	v_mfma_f32_16x16x32_bf16 v[78:81], v[46:49], v[106:109], v[78:81]
	v_mfma_f32_16x16x32_bf16 v[74:77], v[62:65], v[106:109], v[74:77]
	v_mfma_f32_16x16x32_bf16 v[54:57], v[46:49], v[208:211], v[54:57]
	v_mfma_f32_16x16x32_bf16 v[50:53], v[62:65], v[208:211], v[50:53]
	v_mfma_f32_16x16x32_bf16 v[14:17], v[46:49], v[236:239], v[14:17]
	v_mfma_f32_16x16x32_bf16 v[10:13], v[62:65], v[236:239], v[10:13]
	s_setprio 0
	s_setprio 1
	v_mfma_f32_16x16x32_bf16 v[18:21], v[70:73], v[66:69], v[18:21]
	v_mfma_f32_16x16x32_bf16 v[90:93], v[184:187], v[82:85], v[18:21]
	v_mfma_f32_16x16x32_bf16 v[18:21], v[200:203], v[66:69], v[26:29]
	v_mfma_f32_16x16x32_bf16 v[86:89], v[204:207], v[82:85], v[18:21]
	v_mfma_f32_16x16x32_bf16 v[18:21], v[70:73], v[94:97], v[30:33]
	v_mfma_f32_16x16x32_bf16 v[66:69], v[184:187], v[106:109], v[18:21]
	v_mfma_f32_16x16x32_bf16 v[18:21], v[200:203], v[94:97], v[38:41]
	v_mfma_f32_16x16x32_bf16 v[62:65], v[204:207], v[106:109], v[18:21]
	v_mfma_f32_16x16x32_bf16 v[18:21], v[70:73], v[118:121], v[34:37]
	v_mfma_f32_16x16x32_bf16 v[34:37], v[184:187], v[208:211], v[18:21]
	v_mfma_f32_16x16x32_bf16 v[18:21], v[200:203], v[118:121], v[22:25]
	v_mfma_f32_16x16x32_bf16 v[6:9], v[70:73], v[212:215], v[6:9]
	v_mfma_f32_16x16x32_bf16 v[2:5], v[200:203], v[212:215], v[2:5]
	v_mfma_f32_16x16x32_bf16 v[22:25], v[204:207], v[208:211], v[18:21]
	v_mfma_f32_16x16x32_bf16 v[6:9], v[184:187], v[236:239], v[6:9]
	v_mfma_f32_16x16x32_bf16 v[2:5], v[204:207], v[236:239], v[2:5]
	s_setprio 0
	s_barrier
	s_add_i32 s41, s41, 2
	s_add_u32 s34, s34, 0x100
	s_addc_u32 s35, s35, 0
	s_add_u32 s29, s29, 0x100
	s_addc_u32 s40, s40, 0
	s_cmp_gt_u32 s41, 5
	s_cbranch_scc0 .LBB0_788
	s_and_b64 vcc, exec, s[54:55]
	s_cbranch_vccz .LBB0_791
	s_barrier

; #define PG8_STAGE(bufoff, gbase, voff) do { _Pragma("unroll") for (int _i = 0; _i < 2; ++_i) \
;         __builtin_amdgcn_global_load_lds((const unsigned*)((const char*)(gbase) + (voff)[_i]), (PG8_LAS unsigned*)(lds + (bufoff) + ldsw + _i * 8192), 16, 0, 0); } while (0)
; #define PG8_LDA(dst, b, h) do { _Pragma("unroll") for (int m = 0; m < 4; ++m) _Pragma("unroll") for (int k = 0; k < 2; ++k) dst[m][k] = *(const PG8_LAS bf16x8*)(lds + PG8_SA(b, h) + aoff + m * 2048 + k * 1024); } while (0)
; #define PG8_LDB(dst, b, h) do { _Pragma("unroll") for (int n = 0; n < 2; ++n) _Pragma("unroll") for (int k = 0; k < 2; ++k) dst[n][k] = *(const PG8_LAS bf16x8*)(lds + PG8_SB(b, h) + boff + n * 2048 + k * 1024); } while (0)
; #define PG8_MMA(ai, bj, At, Bt) do { __builtin_amdgcn_s_setprio(1); _Pragma("unroll") for (int m = 0; m < 4; ++m) _Pragma("unroll") for (int n = 0; n < 2; ++n) _Pragma("unroll") for (int k = 0; k < 2; ++k) \
;         acc[ai][bj][m][n] = __builtin_amdgcn_mfma_f32_16x16x32_bf16(Bt[n][k], At[m][k], acc[ai][bj][m][n], 0, 0, 0); __builtin_amdgcn_s_setprio(0); } while (0)
; #define PG8_WAIT_V(n) asm volatile("s_waitcnt vmcnt(" #n ")" ::: "memory")
; #define PG8_WAIT_L(n) asm volatile("s_waitcnt lgkmcnt(" #n ")" ::: "memory")
; template <class Epi, class Sched, bool ALIGN_EPI = true, bool SP2 = true, bool GS = false>
; __device__ __forceinline__ void gemm_phase(PG8_LAS unsigned char* lds, const Gemm g, const Sched& S, const Epi& E, const float* gs_ss = nullptr) {
;     ...
;         for (int t = 0; t < nt; t += 2) {
;             const bool last = (t == nt - 2);
;             const char* a1 = cA + (size_t)(t + 1) * kstep;
;             const char* a2 = last ? nA : cA + (size_t)(t + 2) * kstep; const char* b2 = last ? nB : cB + (size_t)(t + 2) * kstep;
;             const char* a3 = a2 + kstep; const char* b3 = b2 + kstep;
;             if constexpr (SP2) {
;             PG8_LDB(B0, 0, 0); PG8_LDB(B1, 0, 1); PG8_SCHED; PG8_LDA(At, 0, 0); PG8_STAGE(PG8_SA(1, 1), a1 + hstep, voffA);
;             PG8_WAIT_V(8); PG8_WAIT_L(0); PG8_BAR; PG8_MMA(0, 0, At, B0); PG8_MMA(0, 1, At, B1); PG8_BAR; PG8_SCHED;
;             PG8_LDA(At, 0, 1); PG8_STAGE(PG8_SB(0, 0), b2, voffB); PG8_STAGE(PG8_SB(0, 1), b2 + hstep, voffB); PG8_STAGE(PG8_SA(0, 0), a2, voffA);
;             PG8_WAIT_V(8); PG8_WAIT_L(0); PG8_BAR; PG8_MMA(1, 0, At, B0); PG8_MMA(1, 1, At, B1); PG8_BAR; PG8_SCHED;
.LBB0_990:
	s_add_i32 s73, s73, 2
	s_add_u32 s2, s60, s62
	s_addc_u32 s3, s61, s63
	s_add_u32 s20, s2, 0x100
	s_addc_u32 s21, s3, 0
	s_add_u32 s74, s71, s62
	s_addc_u32 s75, s72, s63
	s_cmpk_eq_i32 s62, 0xf00
	s_cselect_b64 vcc, -1, 0
	s_and_b64 s[2:3], vcc, exec
	s_cselect_b32 s21, s53, s21
	s_cselect_b32 s20, s67, s20
	s_cselect_b32 s3, s51, s75
	s_cselect_b32 s2, s70, s74
	v_lshl_add_u64 v[2:3], v[132:133], 0, s[62:63]
	s_add_i32 m0, s13, 0xc000
	s_nop 0
	global_load_lds_dwordx4 v[2:3], off
	v_lshl_add_u64 v[2:3], v[134:135], 0, s[62:63]
	s_add_i32 m0, s13, 0xe000
	s_nop 0
	global_load_lds_dwordx4 v[2:3], off
	s_add_i32 s76, 0, 0x10000
	v_add_u32_e32 v0, s76, v195
	s_add_i32 s77, 0, 0x14000
	ds_read_b128 v[154:157], v0
	ds_read_b128 v[158:161], v0 offset:1024
	ds_read_b128 v[162:165], v0 offset:2048
	ds_read_b128 v[166:169], v0 offset:3072
	v_add_u32_e32 v0, s77, v195
	ds_read_b128 v[170:173], v0
	ds_read_b128 v[174:177], v0 offset:1024
	ds_read_b128 v[184:187], v0 offset:2048
	ds_read_b128 v[188:191], v0 offset:3072
	ds_read_b128 v[198:201], v197
	ds_read_b128 v[202:205], v197 offset:1024
	ds_read_b128 v[206:209], v197 offset:2048
	ds_read_b128 v[210:213], v197 offset:3072
	ds_read_b128 v[214:217], v197 offset:4096
	ds_read_b128 v[218:221], v197 offset:5120
	ds_read_b128 v[236:239], v197 offset:6144
	ds_read_b128 v[240:243], v197 offset:7168
	s_waitcnt vmcnt(8)
	s_waitcnt lgkmcnt(0)
	s_barrier
	s_setprio 1
	s_waitcnt lgkmcnt(0)
	v_mfma_f32_16x16x32_bf16 v[128:131], v[154:157], v[198:201], v[128:131]
	v_mfma_f32_16x16x32_bf16 v[124:127], v[162:165], v[198:201], v[124:127]
	v_mfma_f32_16x16x32_bf16 v[112:115], v[154:157], v[206:209], v[112:115]
	v_mfma_f32_16x16x32_bf16 v[108:111], v[162:165], v[206:209], v[108:111]
	v_mfma_f32_16x16x32_bf16 v[96:99], v[154:157], v[214:217], v[96:99]
	v_mfma_f32_16x16x32_bf16 v[92:95], v[162:165], v[214:217], v[92:95]
	v_mfma_f32_16x16x32_bf16 v[80:83], v[154:157], v[236:239], v[80:83]
	v_mfma_f32_16x16x32_bf16 v[76:79], v[162:165], v[236:239], v[76:79]
	v_mfma_f32_16x16x32_bf16 v[128:131], v[158:161], v[202:205], v[128:131]
	v_mfma_f32_16x16x32_bf16 v[124:127], v[166:169], v[202:205], v[124:127]
	v_mfma_f32_16x16x32_bf16 v[112:115], v[158:161], v[210:213], v[112:115]
	v_mfma_f32_16x16x32_bf16 v[108:111], v[166:169], v[210:213], v[108:111]
	v_mfma_f32_16x16x32_bf16 v[96:99], v[158:161], v[218:221], v[96:99]
	v_mfma_f32_16x16x32_bf16 v[92:95], v[166:169], v[218:221], v[92:95]
	v_mfma_f32_16x16x32_bf16 v[80:83], v[158:161], v[240:243], v[80:83]
	v_mfma_f32_16x16x32_bf16 v[76:79], v[166:169], v[240:243], v[76:79]
	s_setprio 0
	s_setprio 1
	v_mfma_f32_16x16x32_bf16 v[120:123], v[170:173], v[198:201], v[120:123]
	v_mfma_f32_16x16x32_bf16 v[116:119], v[184:187], v[198:201], v[116:119]
	v_mfma_f32_16x16x32_bf16 v[104:107], v[170:173], v[206:209], v[104:107]
	v_mfma_f32_16x16x32_bf16 v[100:103], v[184:187], v[206:209], v[100:103]
	v_mfma_f32_16x16x32_bf16 v[88:91], v[170:173], v[214:217], v[88:91]
	v_mfma_f32_16x16x32_bf16 v[84:87], v[184:187], v[214:217], v[84:87]
	v_mfma_f32_16x16x32_bf16 v[72:75], v[170:173], v[236:239], v[72:75]
	v_mfma_f32_16x16x32_bf16 v[68:71], v[184:187], v[236:239], v[68:71]
	v_mfma_f32_16x16x32_bf16 v[120:123], v[174:177], v[202:205], v[120:123]
	v_mfma_f32_16x16x32_bf16 v[116:119], v[188:191], v[202:205], v[116:119]
	v_mfma_f32_16x16x32_bf16 v[104:107], v[174:177], v[210:213], v[104:107]
	v_mfma_f32_16x16x32_bf16 v[100:103], v[188:191], v[210:213], v[100:103]
	v_mfma_f32_16x16x32_bf16 v[88:91], v[174:177], v[218:221], v[88:91]
	v_mfma_f32_16x16x32_bf16 v[84:87], v[188:191], v[218:221], v[84:87]
	v_mfma_f32_16x16x32_bf16 v[72:75], v[174:177], v[240:243], v[72:75]
	v_mfma_f32_16x16x32_bf16 v[68:71], v[188:191], v[240:243], v[68:71]
	s_setprio 0
	s_barrier
	s_add_i32 s74, s76, s14
	v_lshl_add_u64 v[138:139], s[2:3], 0, v[142:143]
	s_mov_b32 m0, s74
	s_nop 0
	global_load_lds_dwordx4 v[138:139], off
	s_add_i32 m0, s74, 0x2000
	s_add_u32 s74, s2, 0x80000
	v_lshl_add_u64 v[180:181], s[2:3], 0, v[146:147]
	s_addc_u32 s75, s3, 0
	s_add_i32 s76, s77, s14
	global_load_lds_dwordx4 v[180:181], off
	v_lshl_add_u64 v[2:3], s[74:75], 0, v[142:143]
	s_mov_b32 m0, s76
	v_lshl_add_u64 v[244:245], s[20:21], 0, v[140:141]
	global_load_lds_dwordx4 v[2:3], off
	v_lshl_add_u64 v[2:3], s[74:75], 0, v[146:147]
	s_add_i32 m0, s76, 0x2000
	v_lshl_add_u64 v[246:247], s[20:21], 0, v[144:145]
	global_load_lds_dwordx4 v[2:3], off
	s_mov_b32 m0, s13
	s_nop 0
	global_load_lds_dwordx4 v[244:245], off
	s_mov_b32 m0, s25
	s_nop 0
	global_load_lds_dwordx4 v[246:247], off
	ds_read_b128 v[198:201], v197 offset:16384
	ds_read_b128 v[202:205], v197 offset:17408
	ds_read_b128 v[206:209], v197 offset:18432
	ds_read_b128 v[210:213], v197 offset:19456
	ds_read_b128 v[214:217], v197 offset:20480
	ds_read_b128 v[218:221], v197 offset:21504
	ds_read_b128 v[236:239], v197 offset:22528
	ds_read_b128 v[240:243], v197 offset:23552
	s_waitcnt vmcnt(8)
	s_waitcnt lgkmcnt(0)
	s_barrier
; #define PG8_STAGE(bufoff, gbase, voff) do { _Pragma("unroll") for (int _i = 0; _i < 2; ++_i) \
;         __builtin_amdgcn_global_load_lds((const unsigned*)((const char*)(gbase) + (voff)[_i]), (PG8_LAS unsigned*)(lds + (bufoff) + ldsw + _i * 8192), 16, 0, 0); } while (0)
; #define PG8_LDA(dst, b, h) do { _Pragma("unroll") for (int m = 0; m < 4; ++m) _Pragma("unroll") for (int k = 0; k < 2; ++k) dst[m][k] = *(const PG8_LAS bf16x8*)(lds + PG8_SA(b, h) + aoff + m * 2048 + k * 1024); } while (0)
; #define PG8_LDB(dst, b, h) do { _Pragma("unroll") for (int n = 0; n < 2; ++n) _Pragma("unroll") for (int k = 0; k < 2; ++k) dst[n][k] = *(const PG8_LAS bf16x8*)(lds + PG8_SB(b, h) + boff + n * 2048 + k * 1024); } while (0)
; #define PG8_MMA(ai, bj, At, Bt) do { __builtin_amdgcn_s_setprio(1); _Pragma("unroll") for (int m = 0; m < 4; ++m) _Pragma("unroll") for (int n = 0; n < 2; ++n) _Pragma("unroll") for (int k = 0; k < 2; ++k) \
;         acc[ai][bj][m][n] = __builtin_amdgcn_mfma_f32_16x16x32_bf16(Bt[n][k], At[m][k], acc[ai][bj][m][n], 0, 0, 0); __builtin_amdgcn_s_setprio(0); } while (0)
; #define PG8_WAIT_V(n) asm volatile("s_waitcnt vmcnt(" #n ")" ::: "memory")
; #define PG8_WAIT_L(n) asm volatile("s_waitcnt lgkmcnt(" #n ")" ::: "memory")
; #define PG8_BAR __builtin_amdgcn_s_barrier()
; #define PG8_SCHED __builtin_amdgcn_sched_barrier(0)
; template <class Epi, class Sched, bool ALIGN_EPI = true, bool SP2 = true, bool GS = false>
; __device__ __forceinline__ void gemm_phase(PG8_LAS unsigned char* lds, const Gemm g, const Sched& S, const Epi& E, const float* gs_ss = nullptr) {
;     ...
;             PG8_WAIT_V(8); PG8_WAIT_L(0); PG8_BAR; PG8_MMA(1, 0, At, B0); PG8_MMA(1, 1, At, B1); PG8_BAR; PG8_SCHED;
;             PG8_LDB(B0, 1, 0); PG8_LDB(B1, 1, 1); PG8_SCHED; PG8_LDA(At, 1, 0); PG8_STAGE(PG8_SA(0, 1), a2 + hstep, voffA);
;             PG8_WAIT_V(8); PG8_WAIT_L(0); PG8_BAR; PG8_MMA(0, 0, At, B0); PG8_MMA(0, 1, At, B1); PG8_BAR; PG8_SCHED;
	s_setprio 1
	s_waitcnt lgkmcnt(0)
	v_mfma_f32_16x16x32_bf16 v[64:67], v[154:157], v[198:201], v[64:67]
	v_mfma_f32_16x16x32_bf16 v[60:63], v[162:165], v[198:201], v[60:63]
	v_mfma_f32_16x16x32_bf16 v[48:51], v[154:157], v[206:209], v[48:51]
	v_mfma_f32_16x16x32_bf16 v[44:47], v[162:165], v[206:209], v[44:47]
	v_mfma_f32_16x16x32_bf16 v[32:35], v[154:157], v[214:217], v[32:35]
	v_mfma_f32_16x16x32_bf16 v[28:31], v[162:165], v[214:217], v[28:31]
	v_mfma_f32_16x16x32_bf16 v[16:19], v[154:157], v[236:239], v[16:19]
	v_mfma_f32_16x16x32_bf16 v[12:15], v[162:165], v[236:239], v[12:15]
	v_mfma_f32_16x16x32_bf16 v[64:67], v[158:161], v[202:205], v[64:67]
	v_mfma_f32_16x16x32_bf16 v[60:63], v[166:169], v[202:205], v[60:63]
	v_mfma_f32_16x16x32_bf16 v[48:51], v[158:161], v[210:213], v[48:51]
	v_mfma_f32_16x16x32_bf16 v[44:47], v[166:169], v[210:213], v[44:47]
	v_mfma_f32_16x16x32_bf16 v[32:35], v[158:161], v[218:221], v[32:35]
	v_mfma_f32_16x16x32_bf16 v[28:31], v[166:169], v[218:221], v[28:31]
	v_mfma_f32_16x16x32_bf16 v[16:19], v[158:161], v[240:243], v[16:19]
	v_mfma_f32_16x16x32_bf16 v[12:15], v[166:169], v[240:243], v[12:15]
	s_setprio 0
	s_setprio 1
	v_mfma_f32_16x16x32_bf16 v[56:59], v[170:173], v[198:201], v[56:59]
	v_mfma_f32_16x16x32_bf16 v[52:55], v[184:187], v[198:201], v[52:55]
	v_mfma_f32_16x16x32_bf16 v[40:43], v[170:173], v[206:209], v[40:43]
	v_mfma_f32_16x16x32_bf16 v[36:39], v[184:187], v[206:209], v[36:39]
	v_mfma_f32_16x16x32_bf16 v[24:27], v[170:173], v[214:217], v[24:27]
	v_mfma_f32_16x16x32_bf16 v[20:23], v[184:187], v[214:217], v[20:23]
	v_mfma_f32_16x16x32_bf16 v[8:11], v[170:173], v[236:239], v[8:11]
	v_mfma_f32_16x16x32_bf16 v[2:5], v[184:187], v[236:239], v[4:7]
	v_mfma_f32_16x16x32_bf16 v[56:59], v[174:177], v[202:205], v[56:59]
	v_mfma_f32_16x16x32_bf16 v[52:55], v[188:191], v[202:205], v[52:55]
	v_mfma_f32_16x16x32_bf16 v[40:43], v[174:177], v[210:213], v[40:43]
	v_mfma_f32_16x16x32_bf16 v[36:39], v[188:191], v[210:213], v[36:39]
	v_mfma_f32_16x16x32_bf16 v[24:27], v[174:177], v[218:221], v[24:27]
	v_mfma_f32_16x16x32_bf16 v[20:23], v[188:191], v[218:221], v[20:23]
	v_mfma_f32_16x16x32_bf16 v[8:11], v[174:177], v[240:243], v[8:11]
	v_mfma_f32_16x16x32_bf16 v[2:5], v[188:191], v[240:243], v[2:5]
	s_setprio 0
	s_barrier
	s_add_u32 s20, s20, 0x80000
	s_addc_u32 s21, s21, 0
	s_mov_b32 m0, s30
	v_lshl_add_u64 v[6:7], s[20:21], 0, v[140:141]
	global_load_lds_dwordx4 v[6:7], off
	v_lshl_add_u64 v[6:7], s[20:21], 0, v[144:145]
	s_mov_b32 m0, s36
	s_nop 0
	global_load_lds_dwordx4 v[6:7], off
	s_add_i32 s74, 0, 0x18000
	v_add_u32_e32 v0, s74, v195
	s_add_i32 s75, 0, 0x1c000
	ds_read_b128 v[154:157], v0
	ds_read_b128 v[158:161], v0 offset:1024
	ds_read_b128 v[162:165], v0 offset:2048
	ds_read_b128 v[166:169], v0 offset:3072
	v_add_u32_e32 v0, s75, v195
	ds_read_b128 v[170:173], v0
	ds_read_b128 v[174:177], v0 offset:1024
	ds_read_b128 v[184:187], v0 offset:2048
	ds_read_b128 v[188:191], v0 offset:3072
	ds_read_b128 v[198:201], v197 offset:32768
	ds_read_b128 v[202:205], v197 offset:33792
	ds_read_b128 v[206:209], v197 offset:34816
	ds_read_b128 v[210:213], v197 offset:35840
	ds_read_b128 v[214:217], v197 offset:36864
	ds_read_b128 v[218:221], v197 offset:37888
	ds_read_b128 v[236:239], v197 offset:38912
	ds_read_b128 v[240:243], v197 offset:39936
	s_waitcnt vmcnt(8)
	s_waitcnt lgkmcnt(0)
	s_barrier
	s_setprio 1
	s_waitcnt lgkmcnt(0)
	v_mfma_f32_16x16x32_bf16 v[128:131], v[154:157], v[198:201], v[128:131]
	v_mfma_f32_16x16x32_bf16 v[124:127], v[162:165], v[198:201], v[124:127]
	v_mfma_f32_16x16x32_bf16 v[112:115], v[154:157], v[206:209], v[112:115]
	v_mfma_f32_16x16x32_bf16 v[108:111], v[162:165], v[206:209], v[108:111]
	v_mfma_f32_16x16x32_bf16 v[96:99], v[154:157], v[214:217], v[96:99]
	v_mfma_f32_16x16x32_bf16 v[92:95], v[162:165], v[214:217], v[92:95]
	v_mfma_f32_16x16x32_bf16 v[80:83], v[154:157], v[236:239], v[80:83]
	v_mfma_f32_16x16x32_bf16 v[76:79], v[162:165], v[236:239], v[76:79]
	v_mfma_f32_16x16x32_bf16 v[128:131], v[158:161], v[202:205], v[128:131]
	v_mfma_f32_16x16x32_bf16 v[124:127], v[166:169], v[202:205], v[124:127]
	v_mfma_f32_16x16x32_bf16 v[112:115], v[158:161], v[210:213], v[112:115]
	v_mfma_f32_16x16x32_bf16 v[108:111], v[166:169], v[210:213], v[108:111]
	v_mfma_f32_16x16x32_bf16 v[96:99], v[158:161], v[218:221], v[96:99]
	v_mfma_f32_16x16x32_bf16 v[92:95], v[166:169], v[218:221], v[92:95]
	v_mfma_f32_16x16x32_bf16 v[80:83], v[158:161], v[240:243], v[80:83]
	v_mfma_f32_16x16x32_bf16 v[76:79], v[166:169], v[240:243], v[76:79]
	s_setprio 0
	s_setprio 1
	v_mfma_f32_16x16x32_bf16 v[120:123], v[170:173], v[198:201], v[120:123]
	v_mfma_f32_16x16x32_bf16 v[116:119], v[184:187], v[198:201], v[116:119]
	v_mfma_f32_16x16x32_bf16 v[104:107], v[170:173], v[206:209], v[104:107]
	v_mfma_f32_16x16x32_bf16 v[100:103], v[184:187], v[206:209], v[100:103]
	v_mfma_f32_16x16x32_bf16 v[88:91], v[170:173], v[214:217], v[88:91]
	v_mfma_f32_16x16x32_bf16 v[84:87], v[184:187], v[214:217], v[84:87]
	v_mfma_f32_16x16x32_bf16 v[72:75], v[170:173], v[236:239], v[72:75]
	v_mfma_f32_16x16x32_bf16 v[68:71], v[184:187], v[236:239], v[68:71]
	v_mfma_f32_16x16x32_bf16 v[120:123], v[174:177], v[202:205], v[120:123]
	v_mfma_f32_16x16x32_bf16 v[116:119], v[188:191], v[202:205], v[116:119]
	v_mfma_f32_16x16x32_bf16 v[104:107], v[174:177], v[210:213], v[104:107]
	v_mfma_f32_16x16x32_bf16 v[100:103], v[188:191], v[210:213], v[100:103]
	v_mfma_f32_16x16x32_bf16 v[88:91], v[174:177], v[218:221], v[88:91]
	v_mfma_f32_16x16x32_bf16 v[84:87], v[188:191], v[218:221], v[84:87]
	v_mfma_f32_16x16x32_bf16 v[72:75], v[174:177], v[240:243], v[72:75]
	v_mfma_f32_16x16x32_bf16 v[68:71], v[188:191], v[240:243], v[68:71]
	s_setprio 0
	s_barrier
; #define PG8_STAGE(bufoff, gbase, voff) do { _Pragma("unroll") for (int _i = 0; _i < 2; ++_i) \
;         __builtin_amdgcn_global_load_lds((const unsigned*)((const char*)(gbase) + (voff)[_i]), (PG8_LAS unsigned*)(lds + (bufoff) + ldsw + _i * 8192), 16, 0, 0); } while (0)
; #define PG8_LDA(dst, b, h) do { _Pragma("unroll") for (int m = 0; m < 4; ++m) _Pragma("unroll") for (int k = 0; k < 2; ++k) dst[m][k] = *(const PG8_LAS bf16x8*)(lds + PG8_SA(b, h) + aoff + m * 2048 + k * 1024); } while (0)
; template <class Epi, class Sched, bool ALIGN_EPI = true, bool SP2 = true, bool GS = false>
; __device__ __forceinline__ void gemm_phase(PG8_LAS unsigned char* lds, const Gemm g, const Sched& S, const Epi& E, const float* gs_ss = nullptr) {
;     ...
;             PG8_LDA(At, 1, 1); PG8_STAGE(PG8_SB(1, 0), b3, voffB); PG8_STAGE(PG8_SB(1, 1), b3 + hstep, voffB); PG8_STAGE(PG8_SA(1, 0), a3, voffA);
;             PG8_WAIT_V(8); PG8_WAIT_L(0); PG8_BAR; PG8_MMA(1, 0, At, B0); PG8_MMA(1, 1, At, B1); PG8_BAR; PG8_SCHED;
;             } else {
;             PG8_LDB(B0, 0, 0); PG8_SCHED; PG8_LDA(At, 0, 0); PG8_STAGE(PG8_SA(1, 1), a1 + hstep, voffA);
;             PG8_WAIT_L(8); PG8_BAR; PG8_WAIT_L(0); PG8_MMA(0, 0, At, B0); PG8_BAR; PG8_SCHED;
;             PG8_LDB(B1, 0, 1); PG8_STAGE(PG8_SB(0, 0), b2, voffB);
;             PG8_BAR; PG8_WAIT_L(0); PG8_MMA(0, 1, At, B1); PG8_BAR;
;             PG8_LDA(At, 0, 1); PG8_STAGE(PG8_SA(0, 0), a2, voffA);
;             PG8_BAR; PG8_WAIT_L(0); PG8_MMA(1, 0, At, B0); PG8_BAR; PG8_SCHED;
;             PG8_STAGE(PG8_SB(0, 1), b2 + hstep, voffB);
;             PG8_WAIT_V(6); PG8_BAR; PG8_MMA(1, 1, At, B1); PG8_BAR;
;             PG8_LDB(B0, 1, 0); PG8_SCHED; PG8_LDA(At, 1, 0); PG8_STAGE(PG8_SA(0, 1), a2 + hstep, voffA);
;             PG8_WAIT_L(8); PG8_BAR; PG8_WAIT_L(0); PG8_MMA(0, 0, At, B0); PG8_BAR; PG8_SCHED;
;             PG8_LDB(B1, 1, 1); PG8_STAGE(PG8_SB(1, 0), b3, voffB);
;             PG8_BAR; PG8_WAIT_L(0); PG8_MMA(0, 1, At, B1); PG8_BAR;
;             PG8_LDA(At, 1, 1); PG8_STAGE(PG8_SA(1, 0), a3, voffA);
;             PG8_BAR; PG8_WAIT_L(0); PG8_MMA(1, 0, At, B0); PG8_BAR; PG8_SCHED;
;             PG8_STAGE(PG8_SB(1, 1), b3 + hstep, voffB);
;             PG8_WAIT_V(6); PG8_BAR; PG8_MMA(1, 1, At, B1); PG8_BAR;
;                     }
;             if constexpr (GS) { if ((t & 7) == 6 && !last) { PG8_GS_SCALE(t >> 3, gpar); } }
	s_add_i32 s20, s74, s14
	v_lshl_add_u64 v[6:7], v[138:139], 0, s[26:27]
	s_mov_b32 m0, s20
	s_nop 0
	global_load_lds_dwordx4 v[6:7], off
	s_add_i32 m0, s20, 0x2000
	s_add_u32 s2, s2, 0x80080
	v_lshl_add_u64 v[6:7], v[180:181], 0, s[26:27]
	s_addc_u32 s3, s3, 0
	s_add_i32 s20, s75, s14
	global_load_lds_dwordx4 v[6:7], off
	v_lshl_add_u64 v[6:7], s[2:3], 0, v[142:143]
	s_mov_b32 m0, s20
	s_nop 0
	global_load_lds_dwordx4 v[6:7], off
	v_lshl_add_u64 v[6:7], s[2:3], 0, v[146:147]
	s_add_i32 m0, s20, 0x2000
	s_nop 0
	global_load_lds_dwordx4 v[6:7], off
	v_lshl_add_u64 v[6:7], v[244:245], 0, s[26:27]
	s_mov_b32 m0, s59
	s_nop 0
	global_load_lds_dwordx4 v[6:7], off
	v_lshl_add_u64 v[6:7], v[246:247], 0, s[26:27]
	s_mov_b32 m0, s64
	s_nop 0
	global_load_lds_dwordx4 v[6:7], off
	ds_read_b128 v[198:201], v197 offset:49152
	ds_read_b128 v[202:205], v197 offset:50176
	ds_read_b128 v[206:209], v197 offset:51200
	ds_read_b128 v[210:213], v197 offset:52224
	ds_read_b128 v[214:217], v197 offset:53248
	ds_read_b128 v[218:221], v197 offset:54272
	ds_read_b128 v[236:239], v197 offset:55296
	ds_read_b128 v[240:243], v197 offset:56320
	s_waitcnt vmcnt(8)
	s_waitcnt lgkmcnt(0)
	s_barrier
	s_setprio 1
	s_waitcnt lgkmcnt(0)
	v_mfma_f32_16x16x32_bf16 v[64:67], v[154:157], v[198:201], v[64:67]
	v_mfma_f32_16x16x32_bf16 v[60:63], v[162:165], v[198:201], v[60:63]
	v_mfma_f32_16x16x32_bf16 v[48:51], v[154:157], v[206:209], v[48:51]
	v_mfma_f32_16x16x32_bf16 v[44:47], v[162:165], v[206:209], v[44:47]
	v_mfma_f32_16x16x32_bf16 v[32:35], v[154:157], v[214:217], v[32:35]
	v_mfma_f32_16x16x32_bf16 v[28:31], v[162:165], v[214:217], v[28:31]
	v_mfma_f32_16x16x32_bf16 v[16:19], v[154:157], v[236:239], v[16:19]
	v_mfma_f32_16x16x32_bf16 v[12:15], v[162:165], v[236:239], v[12:15]
	v_mfma_f32_16x16x32_bf16 v[64:67], v[158:161], v[202:205], v[64:67]
	v_mfma_f32_16x16x32_bf16 v[60:63], v[166:169], v[202:205], v[60:63]
	v_mfma_f32_16x16x32_bf16 v[48:51], v[158:161], v[210:213], v[48:51]
	v_mfma_f32_16x16x32_bf16 v[44:47], v[166:169], v[210:213], v[44:47]
	v_mfma_f32_16x16x32_bf16 v[32:35], v[158:161], v[218:221], v[32:35]
	v_mfma_f32_16x16x32_bf16 v[28:31], v[166:169], v[218:221], v[28:31]
	v_mfma_f32_16x16x32_bf16 v[16:19], v[158:161], v[240:243], v[16:19]
	v_mfma_f32_16x16x32_bf16 v[12:15], v[166:169], v[240:243], v[12:15]
	s_setprio 0
	s_setprio 1
	v_mfma_f32_16x16x32_bf16 v[56:59], v[170:173], v[198:201], v[56:59]
	v_mfma_f32_16x16x32_bf16 v[52:55], v[184:187], v[198:201], v[52:55]
	v_mfma_f32_16x16x32_bf16 v[40:43], v[170:173], v[206:209], v[40:43]
	v_mfma_f32_16x16x32_bf16 v[36:39], v[184:187], v[206:209], v[36:39]
	v_mfma_f32_16x16x32_bf16 v[24:27], v[170:173], v[214:217], v[24:27]
	v_mfma_f32_16x16x32_bf16 v[20:23], v[184:187], v[214:217], v[20:23]
	v_mfma_f32_16x16x32_bf16 v[6:9], v[170:173], v[236:239], v[8:11]
	v_mfma_f32_16x16x32_bf16 v[2:5], v[184:187], v[236:239], v[2:5]
	v_mfma_f32_16x16x32_bf16 v[56:59], v[174:177], v[202:205], v[56:59]
	v_mfma_f32_16x16x32_bf16 v[52:55], v[188:191], v[202:205], v[52:55]
	v_mfma_f32_16x16x32_bf16 v[40:43], v[174:177], v[210:213], v[40:43]
	v_mfma_f32_16x16x32_bf16 v[36:39], v[188:191], v[210:213], v[36:39]
	v_mfma_f32_16x16x32_bf16 v[24:27], v[174:177], v[218:221], v[24:27]
	v_mfma_f32_16x16x32_bf16 v[20:23], v[188:191], v[218:221], v[20:23]
	v_mfma_f32_16x16x32_bf16 v[8:11], v[174:177], v[240:243], v[6:9]
	v_mfma_f32_16x16x32_bf16 v[4:7], v[188:191], v[240:243], v[2:5]
	s_setprio 0
	s_barrier
	s_and_b32 s2, s73, 6
	s_cmp_lg_u32 s2, 6
	s_cselect_b64 s[2:3], -1, 0
	s_or_b64 s[2:3], vcc, s[2:3]
	s_and_b64 vcc, exec, s[2:3]
	s_cbranch_vccnz .LBB0_989
	s_and_b32 s2, s62, 0xc00
	v_add_u32_e32 v137, s2, v136
	v_add_u32_e32 v154, 0x400, v137
	ds_read2_b32 v[2:3], v137 offset1:16
	ds_read2_b32 v[138:139], v154 offset1:16
	s_waitcnt lgkmcnt(0)
	v_div_scale_f32 v0, s[2:3], v138, v138, v2
	v_rcp_f32_e32 v155, v0
	v_div_scale_f32 v156, vcc, v2, v138, v2
	v_fma_f32 v157, -v0, v155, 1.0
	v_fmac_f32_e32 v155, v157, v155
	v_mul_f32_e32 v157, v156, v155
	v_fma_f32 v158, -v0, v157, v156
	v_fmac_f32_e32 v157, v158, v155
	v_fma_f32 v0, -v0, v157, v156
	v_div_fmas_f32 v0, v0, v155, v157
	v_div_fixup_f32 v0, v0, v138, v2
	v_div_scale_f32 v2, s[2:3], v139, v139, v3
	v_rcp_f32_e32 v138, v2
	v_pk_mul_f32 v[130:131], v[130:131], v[0:1] op_sel_hi:[1,0]
	v_pk_mul_f32 v[128:129], v[128:129], v[0:1] op_sel_hi:[1,0]
	v_pk_mul_f32 v[126:127], v[126:127], v[0:1] op_sel_hi:[1,0]
	v_pk_mul_f32 v[124:125], v[124:125], v[0:1] op_sel_hi:[1,0]
	v_pk_mul_f32 v[122:123], v[122:123], v[0:1] op_sel_hi:[1,0]
	v_pk_mul_f32 v[120:121], v[120:121], v[0:1] op_sel_hi:[1,0]
	v_pk_mul_f32 v[118:119], v[118:119], v[0:1] op_sel_hi:[1,0]
	v_pk_mul_f32 v[116:117], v[116:117], v[0:1] op_sel_hi:[1,0]
	v_fma_f32 v0, -v2, v138, 1.0
	v_fmac_f32_e32 v138, v0, v138
	v_div_scale_f32 v0, vcc, v3, v139, v3
	v_mul_f32_e32 v155, v0, v138
	v_fma_f32 v156, -v2, v155, v0
	v_fmac_f32_e32 v155, v156, v138
	v_fma_f32 v0, -v2, v155, v0
	v_div_fmas_f32 v0, v0, v138, v155
	v_div_fixup_f32 v0, v0, v139, v3
	ds_read2_b32 v[2:3], v137 offset0:32 offset1:48
	ds_read2_b32 v[138:139], v154 offset0:32 offset1:48
	v_pk_mul_f32 v[114:115], v[114:115], v[0:1] op_sel_hi:[1,0]
	v_pk_mul_f32 v[112:113], v[112:113], v[0:1] op_sel_hi:[1,0]
	v_pk_mul_f32 v[110:111], v[110:111], v[0:1] op_sel_hi:[1,0]
	v_pk_mul_f32 v[108:109], v[108:109], v[0:1] op_sel_hi:[1,0]
	s_waitcnt lgkmcnt(0)
	v_div_scale_f32 v155, s[2:3], v138, v138, v2
	v_rcp_f32_e32 v156, v155
	v_pk_mul_f32 v[106:107], v[106:107], v[0:1] op_sel_hi:[1,0]
	v_pk_mul_f32 v[104:105], v[104:105], v[0:1] op_sel_hi:[1,0]
	v_pk_mul_f32 v[102:103], v[102:103], v[0:1] op_sel_hi:[1,0]
	v_pk_mul_f32 v[100:101], v[100:101], v[0:1] op_sel_hi:[1,0]
	v_fma_f32 v0, -v155, v156, 1.0
	v_fmac_f32_e32 v156, v0, v156
	v_div_scale_f32 v0, vcc, v2, v138, v2
	v_mul_f32_e32 v157, v0, v156
	v_fma_f32 v158, -v155, v157, v0
	v_fmac_f32_e32 v157, v158, v156
	v_fma_f32 v0, -v155, v157, v0
	v_div_fmas_f32 v0, v0, v156, v157
	v_div_fixup_f32 v0, v0, v138, v2
	v_div_scale_f32 v2, s[2:3], v139, v139, v3
	v_rcp_f32_e32 v138, v2
	v_pk_mul_f32 v[98:99], v[98:99], v[0:1] op_sel_hi:[1,0]
	v_pk_mul_f32 v[96:97], v[96:97], v[0:1] op_sel_hi:[1,0]
	v_pk_mul_f32 v[94:95], v[94:95], v[0:1] op_sel_hi:[1,0]
	v_pk_mul_f32 v[92:93], v[92:93], v[0:1] op_sel_hi:[1,0]
	v_pk_mul_f32 v[90:91], v[90:91], v[0:1] op_sel_hi:[1,0]
	v_pk_mul_f32 v[88:89], v[88:89], v[0:1] op_sel_hi:[1,0]
	v_pk_mul_f32 v[86:87], v[86:87], v[0:1] op_sel_hi:[1,0]
	v_pk_mul_f32 v[84:85], v[84:85], v[0:1] op_sel_hi:[1,0]
	v_fma_f32 v0, -v2, v138, 1.0
	v_fmac_f32_e32 v138, v0, v138
	v_div_scale_f32 v0, vcc, v3, v139, v3
	v_mul_f32_e32 v155, v0, v138
	v_fma_f32 v156, -v2, v155, v0
	v_fmac_f32_e32 v155, v156, v138
	v_fma_f32 v0, -v2, v155, v0
	v_div_fmas_f32 v0, v0, v138, v155
	v_div_fixup_f32 v0, v0, v139, v3
	ds_read2_b32 v[2:3], v137 offset0:128 offset1:144
	ds_read2_b32 v[138:139], v154 offset0:128 offset1:144
	v_pk_mul_f32 v[82:83], v[82:83], v[0:1] op_sel_hi:[1,0]
	v_pk_mul_f32 v[80:81], v[80:81], v[0:1] op_sel_hi:[1,0]
	v_pk_mul_f32 v[78:79], v[78:79], v[0:1] op_sel_hi:[1,0]
	v_pk_mul_f32 v[76:77], v[76:77], v[0:1] op_sel_hi:[1,0]
	s_waitcnt lgkmcnt(0)
	v_div_scale_f32 v155, s[2:3], v138, v138, v2
	v_rcp_f32_e32 v156, v155
	v_pk_mul_f32 v[74:75], v[74:75], v[0:1] op_sel_hi:[1,0]
	v_pk_mul_f32 v[72:73], v[72:73], v[0:1] op_sel_hi:[1,0]
	v_pk_mul_f32 v[70:71], v[70:71], v[0:1] op_sel_hi:[1,0]
	v_pk_mul_f32 v[68:69], v[68:69], v[0:1] op_sel_hi:[1,0]
	v_fma_f32 v0, -v155, v156, 1.0
	v_fmac_f32_e32 v156, v0, v156
	v_div_scale_f32 v0, vcc, v2, v138, v2
	v_mul_f32_e32 v157, v0, v156
	v_fma_f32 v158, -v155, v157, v0
	v_fmac_f32_e32 v157, v158, v156
	v_fma_f32 v0, -v155, v157, v0
	v_div_fmas_f32 v0, v0, v156, v157
	v_div_fixup_f32 v0, v0, v138, v2
	v_div_scale_f32 v2, s[2:3], v139, v139, v3
	v_rcp_f32_e32 v138, v2
	v_pk_mul_f32 v[66:67], v[66:67], v[0:1] op_sel_hi:[1,0]
	v_pk_mul_f32 v[64:65], v[64:65], v[0:1] op_sel_hi:[1,0]
	v_pk_mul_f32 v[62:63], v[62:63], v[0:1] op_sel_hi:[1,0]
	v_pk_mul_f32 v[60:61], v[60:61], v[0:1] op_sel_hi:[1,0]
	v_pk_mul_f32 v[58:59], v[58:59], v[0:1] op_sel_hi:[1,0]
	v_pk_mul_f32 v[56:57], v[56:57], v[0:1] op_sel_hi:[1,0]
	v_pk_mul_f32 v[54:55], v[54:55], v[0:1] op_sel_hi:[1,0]
	v_pk_mul_f32 v[52:53], v[52:53], v[0:1] op_sel_hi:[1,0]
	v_fma_f32 v0, -v2, v138, 1.0
	v_fmac_f32_e32 v138, v0, v138
	v_div_scale_f32 v0, vcc, v3, v139, v3
	v_mul_f32_e32 v155, v0, v138
	v_fma_f32 v156, -v2, v155, v0
	v_fmac_f32_e32 v155, v156, v138
	v_fma_f32 v0, -v2, v155, v0
	v_div_fmas_f32 v0, v0, v138, v155
	v_div_fixup_f32 v0, v0, v139, v3
	ds_read2_b32 v[2:3], v137 offset0:160 offset1:176
	ds_read2_b32 v[138:139], v154 offset0:160 offset1:176
	v_pk_mul_f32 v[50:51], v[50:51], v[0:1] op_sel_hi:[1,0]
	v_pk_mul_f32 v[48:49], v[48:49], v[0:1] op_sel_hi:[1,0]
	v_pk_mul_f32 v[46:47], v[46:47], v[0:1] op_sel_hi:[1,0]
	v_pk_mul_f32 v[44:45], v[44:45], v[0:1] op_sel_hi:[1,0]
	s_waitcnt lgkmcnt(0)
	v_div_scale_f32 v137, s[2:3], v138, v138, v2
	v_rcp_f32_e32 v154, v137
	v_pk_mul_f32 v[42:43], v[42:43], v[0:1] op_sel_hi:[1,0]
	v_pk_mul_f32 v[40:41], v[40:41], v[0:1] op_sel_hi:[1,0]
	v_pk_mul_f32 v[38:39], v[38:39], v[0:1] op_sel_hi:[1,0]
	v_pk_mul_f32 v[36:37], v[36:37], v[0:1] op_sel_hi:[1,0]
	v_fma_f32 v0, -v137, v154, 1.0
	v_fmac_f32_e32 v154, v0, v154
	v_div_scale_f32 v0, vcc, v2, v138, v2
	v_mul_f32_e32 v155, v0, v154
	v_fma_f32 v156, -v137, v155, v0
	v_fmac_f32_e32 v155, v156, v154
	v_fma_f32 v0, -v137, v155, v0
	v_div_fmas_f32 v0, v0, v154, v155
	v_div_fixup_f32 v0, v0, v138, v2
	v_div_scale_f32 v2, s[2:3], v139, v139, v3
	v_rcp_f32_e32 v137, v2
	v_pk_mul_f32 v[34:35], v[34:35], v[0:1] op_sel_hi:[1,0]
	v_pk_mul_f32 v[32:33], v[32:33], v[0:1] op_sel_hi:[1,0]
	v_pk_mul_f32 v[30:31], v[30:31], v[0:1] op_sel_hi:[1,0]
	v_pk_mul_f32 v[28:29], v[28:29], v[0:1] op_sel_hi:[1,0]
	v_pk_mul_f32 v[26:27], v[26:27], v[0:1] op_sel_hi:[1,0]
	v_pk_mul_f32 v[24:25], v[24:25], v[0:1] op_sel_hi:[1,0]
	v_pk_mul_f32 v[22:23], v[22:23], v[0:1] op_sel_hi:[1,0]
	v_pk_mul_f32 v[20:21], v[20:21], v[0:1] op_sel_hi:[1,0]
	v_fma_f32 v0, -v2, v137, 1.0
	v_fmac_f32_e32 v137, v0, v137
	v_div_scale_f32 v0, vcc, v3, v139, v3
	v_mul_f32_e32 v138, v0, v137
	v_fma_f32 v154, -v2, v138, v0
	v_fmac_f32_e32 v138, v154, v137
	v_fma_f32 v0, -v2, v138, v0
	v_div_fmas_f32 v0, v0, v137, v138
	v_div_fixup_f32 v0, v0, v139, v3
	v_pk_mul_f32 v[18:19], v[18:19], v[0:1] op_sel_hi:[1,0]
	v_pk_mul_f32 v[16:17], v[16:17], v[0:1] op_sel_hi:[1,0]
	v_pk_mul_f32 v[14:15], v[14:15], v[0:1] op_sel_hi:[1,0]
	v_pk_mul_f32 v[12:13], v[12:13], v[0:1] op_sel_hi:[1,0]
	v_pk_mul_f32 v[10:11], v[10:11], v[0:1] op_sel_hi:[1,0]
	v_pk_mul_f32 v[8:9], v[8:9], v[0:1] op_sel_hi:[1,0]
	v_pk_mul_f32 v[6:7], v[6:7], v[0:1] op_sel_hi:[1,0]
	v_pk_mul_f32 v[4:5], v[4:5], v[0:1] op_sel_hi:[1,0]
	s_branch .LBB0_989

; #define PG8_STAGE(bufoff, gbase, voff) do { _Pragma("unroll") for (int _i = 0; _i < 2; ++_i) \
;         __builtin_amdgcn_global_load_lds((const unsigned*)((const char*)(gbase) + (voff)[_i]), (PG8_LAS unsigned*)(lds + (bufoff) + ldsw + _i * 8192), 16, 0, 0); } while (0)
; #define PG8_LDA(dst, b, h) do { _Pragma("unroll") for (int m = 0; m < 4; ++m) _Pragma("unroll") for (int k = 0; k < 2; ++k) dst[m][k] = *(const PG8_LAS bf16x8*)(lds + PG8_SA(b, h) + aoff + m * 2048 + k * 1024); } while (0)
; #define PG8_LDB(dst, b, h) do { _Pragma("unroll") for (int n = 0; n < 2; ++n) _Pragma("unroll") for (int k = 0; k < 2; ++k) dst[n][k] = *(const PG8_LAS bf16x8*)(lds + PG8_SB(b, h) + boff + n * 2048 + k * 1024); } while (0)
; #define PG8_MMA(ai, bj, At, Bt) do { __builtin_amdgcn_s_setprio(1); _Pragma("unroll") for (int m = 0; m < 4; ++m) _Pragma("unroll") for (int n = 0; n < 2; ++n) _Pragma("unroll") for (int k = 0; k < 2; ++k) \
;         acc[ai][bj][m][n] = __builtin_amdgcn_mfma_f32_16x16x32_bf16(Bt[n][k], At[m][k], acc[ai][bj][m][n], 0, 0, 0); __builtin_amdgcn_s_setprio(0); } while (0)
; #define PG8_WAIT_V(n) asm volatile("s_waitcnt vmcnt(" #n ")" ::: "memory")
; #define PG8_WAIT_L(n) asm volatile("s_waitcnt lgkmcnt(" #n ")" ::: "memory")
; template <class Epi, class Sched, bool ALIGN_EPI = true, bool SP2 = true, bool GS = false>
; __device__ __forceinline__ void gemm_phase(PG8_LAS unsigned char* lds, const Gemm g, const Sched& S, const Epi& E, const float* gs_ss = nullptr) {
;     ...
;         for (int t = 0; t < nt; t += 2) {
;             const bool last = (t == nt - 2);
;             const char* a1 = cA + (size_t)(t + 1) * kstep;
;             const char* a2 = last ? nA : cA + (size_t)(t + 2) * kstep; const char* b2 = last ? nB : cB + (size_t)(t + 2) * kstep;
;             const char* a3 = a2 + kstep; const char* b3 = b2 + kstep;
;             if constexpr (SP2) {
;             PG8_LDB(B0, 0, 0); PG8_LDB(B1, 0, 1); PG8_SCHED; PG8_LDA(At, 0, 0); PG8_STAGE(PG8_SA(1, 1), a1 + hstep, voffA);
;             PG8_WAIT_V(8); PG8_WAIT_L(0); PG8_BAR; PG8_MMA(0, 0, At, B0); PG8_MMA(0, 1, At, B1); PG8_BAR; PG8_SCHED;
;             PG8_LDA(At, 0, 1); PG8_STAGE(PG8_SB(0, 0), b2, voffB); PG8_STAGE(PG8_SB(0, 1), b2 + hstep, voffB); PG8_STAGE(PG8_SA(0, 0), a2, voffA);
;             PG8_WAIT_V(8); PG8_WAIT_L(0); PG8_BAR; PG8_MMA(1, 0, At, B0); PG8_MMA(1, 1, At, B1); PG8_BAR; PG8_SCHED;
.LBB0_1036:
	s_add_i32 s75, s75, 2
	s_add_u32 s2, s58, s60
	s_addc_u32 s3, s59, s61
	s_add_u32 s20, s2, 0x100
	s_addc_u32 s21, s3, 0
	s_add_u32 vcc_lo, s73, s60
	s_addc_u32 vcc_hi, s74, s61
	s_cmpk_eq_i32 s60, 0xf00
	s_cselect_b64 s[62:63], -1, 0
	s_and_b64 s[2:3], s[62:63], exec
	s_cselect_b32 s21, s51, s21
	s_cselect_b32 s20, s71, s20
	s_cselect_b32 s3, s49, vcc_hi
	s_cselect_b32 s2, s72, vcc_lo
	v_lshl_add_u64 v[2:3], v[132:133], 0, s[60:61]
	s_add_i32 m0, s13, 0xc000
	s_nop 0
	global_load_lds_dwordx4 v[2:3], off
	v_lshl_add_u64 v[2:3], v[134:135], 0, s[60:61]
	s_add_i32 m0, s13, 0xe000
	s_nop 0
	global_load_lds_dwordx4 v[2:3], off
	s_add_i32 s76, 0, 0x10000
	v_add_u32_e32 v0, s76, v188
	s_add_i32 s77, 0, 0x14000
	ds_read_b128 v[138:141], v0
	ds_read_b128 v[142:145], v0 offset:1024
	ds_read_b128 v[162:165], v0 offset:2048
	ds_read_b128 v[166:169], v0 offset:3072
	v_add_u32_e32 v0, s77, v188
	ds_read_b128 v[170:173], v0
	ds_read_b128 v[184:187], v0 offset:1024
	ds_read_b128 v[192:195], v0 offset:2048
	ds_read_b128 v[196:199], v0 offset:3072
	ds_read_b128 v[200:203], v190
	ds_read_b128 v[204:207], v190 offset:1024
	ds_read_b128 v[208:211], v190 offset:2048
	ds_read_b128 v[212:215], v190 offset:3072
	ds_read_b128 v[216:219], v190 offset:4096
	ds_read_b128 v[236:239], v190 offset:5120
	ds_read_b128 v[240:243], v190 offset:6144
	ds_read_b128 v[244:247], v190 offset:7168
	s_waitcnt vmcnt(8)
	s_waitcnt lgkmcnt(0)
	s_barrier
	s_setprio 1
	s_waitcnt lgkmcnt(0)
	v_mfma_f32_16x16x32_bf16 v[128:131], v[138:141], v[200:203], v[128:131]
	v_mfma_f32_16x16x32_bf16 v[124:127], v[162:165], v[200:203], v[124:127]
	v_mfma_f32_16x16x32_bf16 v[112:115], v[138:141], v[208:211], v[112:115]
	v_mfma_f32_16x16x32_bf16 v[108:111], v[162:165], v[208:211], v[108:111]
	v_mfma_f32_16x16x32_bf16 v[96:99], v[138:141], v[216:219], v[96:99]
	v_mfma_f32_16x16x32_bf16 v[92:95], v[162:165], v[216:219], v[92:95]
	v_mfma_f32_16x16x32_bf16 v[80:83], v[138:141], v[240:243], v[80:83]
	v_mfma_f32_16x16x32_bf16 v[76:79], v[162:165], v[240:243], v[76:79]
	v_mfma_f32_16x16x32_bf16 v[128:131], v[142:145], v[204:207], v[128:131]
	v_mfma_f32_16x16x32_bf16 v[124:127], v[166:169], v[204:207], v[124:127]
	v_mfma_f32_16x16x32_bf16 v[112:115], v[142:145], v[212:215], v[112:115]
	v_mfma_f32_16x16x32_bf16 v[108:111], v[166:169], v[212:215], v[108:111]
	v_mfma_f32_16x16x32_bf16 v[96:99], v[142:145], v[236:239], v[96:99]
	v_mfma_f32_16x16x32_bf16 v[92:95], v[166:169], v[236:239], v[92:95]
	v_mfma_f32_16x16x32_bf16 v[80:83], v[142:145], v[244:247], v[80:83]
	v_mfma_f32_16x16x32_bf16 v[76:79], v[166:169], v[244:247], v[76:79]
	s_setprio 0
	s_setprio 1
	v_mfma_f32_16x16x32_bf16 v[120:123], v[170:173], v[200:203], v[120:123]
	v_mfma_f32_16x16x32_bf16 v[116:119], v[192:195], v[200:203], v[116:119]
	v_mfma_f32_16x16x32_bf16 v[104:107], v[170:173], v[208:211], v[104:107]
	v_mfma_f32_16x16x32_bf16 v[100:103], v[192:195], v[208:211], v[100:103]
	v_mfma_f32_16x16x32_bf16 v[88:91], v[170:173], v[216:219], v[88:91]
	v_mfma_f32_16x16x32_bf16 v[84:87], v[192:195], v[216:219], v[84:87]
	v_mfma_f32_16x16x32_bf16 v[72:75], v[170:173], v[240:243], v[72:75]
	v_mfma_f32_16x16x32_bf16 v[68:71], v[192:195], v[240:243], v[68:71]
	v_mfma_f32_16x16x32_bf16 v[120:123], v[184:187], v[204:207], v[120:123]
	v_mfma_f32_16x16x32_bf16 v[116:119], v[196:199], v[204:207], v[116:119]
	v_mfma_f32_16x16x32_bf16 v[104:107], v[184:187], v[212:215], v[104:107]
	v_mfma_f32_16x16x32_bf16 v[100:103], v[196:199], v[212:215], v[100:103]
	v_mfma_f32_16x16x32_bf16 v[88:91], v[184:187], v[236:239], v[88:91]
	v_mfma_f32_16x16x32_bf16 v[84:87], v[196:199], v[236:239], v[84:87]
	v_mfma_f32_16x16x32_bf16 v[72:75], v[184:187], v[244:247], v[72:75]
	v_mfma_f32_16x16x32_bf16 v[68:71], v[196:199], v[244:247], v[68:71]
	s_setprio 0
	s_barrier
	s_add_i32 s76, s76, s14
	v_lshl_add_u64 v[146:147], s[2:3], 0, v[150:151]
	s_mov_b32 m0, s76
	s_nop 0
	global_load_lds_dwordx4 v[146:147], off
	s_add_i32 m0, s76, 0x2000
	s_add_u32 vcc_lo, s2, 0x80000
	v_lshl_add_u64 v[174:175], s[2:3], 0, v[154:155]
	s_addc_u32 vcc_hi, s3, 0
	s_add_i32 s76, s77, s14
	global_load_lds_dwordx4 v[174:175], off
	v_lshl_add_u64 v[2:3], vcc, 0, v[150:151]
	s_mov_b32 m0, s76
	v_lshl_add_u64 v[180:181], s[20:21], 0, v[148:149]
	global_load_lds_dwordx4 v[2:3], off
	v_lshl_add_u64 v[2:3], vcc, 0, v[154:155]
	s_add_i32 m0, s76, 0x2000
	v_lshl_add_u64 v[220:221], s[20:21], 0, v[152:153]
	global_load_lds_dwordx4 v[2:3], off
	s_mov_b32 m0, s13
	s_nop 0
	global_load_lds_dwordx4 v[180:181], off
	s_mov_b32 m0, s25
	s_nop 0
	global_load_lds_dwordx4 v[220:221], off
	ds_read_b128 v[200:203], v190 offset:16384
	ds_read_b128 v[204:207], v190 offset:17408
	ds_read_b128 v[208:211], v190 offset:18432
	ds_read_b128 v[212:215], v190 offset:19456
	ds_read_b128 v[216:219], v190 offset:20480
	ds_read_b128 v[236:239], v190 offset:21504
	ds_read_b128 v[240:243], v190 offset:22528
	ds_read_b128 v[244:247], v190 offset:23552
	s_waitcnt vmcnt(8)
	s_waitcnt lgkmcnt(0)
	s_barrier
; #define PG8_STAGE(bufoff, gbase, voff) do { _Pragma("unroll") for (int _i = 0; _i < 2; ++_i) \
;         __builtin_amdgcn_global_load_lds((const unsigned*)((const char*)(gbase) + (voff)[_i]), (PG8_LAS unsigned*)(lds + (bufoff) + ldsw + _i * 8192), 16, 0, 0); } while (0)
; #define PG8_LDA(dst, b, h) do { _Pragma("unroll") for (int m = 0; m < 4; ++m) _Pragma("unroll") for (int k = 0; k < 2; ++k) dst[m][k] = *(const PG8_LAS bf16x8*)(lds + PG8_SA(b, h) + aoff + m * 2048 + k * 1024); } while (0)
; #define PG8_LDB(dst, b, h) do { _Pragma("unroll") for (int n = 0; n < 2; ++n) _Pragma("unroll") for (int k = 0; k < 2; ++k) dst[n][k] = *(const PG8_LAS bf16x8*)(lds + PG8_SB(b, h) + boff + n * 2048 + k * 1024); } while (0)
; #define PG8_MMA(ai, bj, At, Bt) do { __builtin_amdgcn_s_setprio(1); _Pragma("unroll") for (int m = 0; m < 4; ++m) _Pragma("unroll") for (int n = 0; n < 2; ++n) _Pragma("unroll") for (int k = 0; k < 2; ++k) \
;         acc[ai][bj][m][n] = __builtin_amdgcn_mfma_f32_16x16x32_bf16(Bt[n][k], At[m][k], acc[ai][bj][m][n], 0, 0, 0); __builtin_amdgcn_s_setprio(0); } while (0)
; #define PG8_WAIT_V(n) asm volatile("s_waitcnt vmcnt(" #n ")" ::: "memory")
; #define PG8_WAIT_L(n) asm volatile("s_waitcnt lgkmcnt(" #n ")" ::: "memory")
; #define PG8_BAR __builtin_amdgcn_s_barrier()
; #define PG8_SCHED __builtin_amdgcn_sched_barrier(0)
; template <class Epi, class Sched, bool ALIGN_EPI = true, bool SP2 = true, bool GS = false>
; __device__ __forceinline__ void gemm_phase(PG8_LAS unsigned char* lds, const Gemm g, const Sched& S, const Epi& E, const float* gs_ss = nullptr) {
;     ...
;             PG8_WAIT_V(8); PG8_WAIT_L(0); PG8_BAR; PG8_MMA(1, 0, At, B0); PG8_MMA(1, 1, At, B1); PG8_BAR; PG8_SCHED;
;             PG8_LDB(B0, 1, 0); PG8_LDB(B1, 1, 1); PG8_SCHED; PG8_LDA(At, 1, 0); PG8_STAGE(PG8_SA(0, 1), a2 + hstep, voffA);
;             PG8_WAIT_V(8); PG8_WAIT_L(0); PG8_BAR; PG8_MMA(0, 0, At, B0); PG8_MMA(0, 1, At, B1); PG8_BAR; PG8_SCHED;
	s_setprio 1
	s_waitcnt lgkmcnt(0)
	v_mfma_f32_16x16x32_bf16 v[64:67], v[138:141], v[200:203], v[64:67]
	v_mfma_f32_16x16x32_bf16 v[60:63], v[162:165], v[200:203], v[60:63]
	v_mfma_f32_16x16x32_bf16 v[48:51], v[138:141], v[208:211], v[48:51]
	v_mfma_f32_16x16x32_bf16 v[44:47], v[162:165], v[208:211], v[44:47]
	v_mfma_f32_16x16x32_bf16 v[32:35], v[138:141], v[216:219], v[32:35]
	v_mfma_f32_16x16x32_bf16 v[28:31], v[162:165], v[216:219], v[28:31]
	v_mfma_f32_16x16x32_bf16 v[16:19], v[138:141], v[240:243], v[16:19]
	v_mfma_f32_16x16x32_bf16 v[12:15], v[162:165], v[240:243], v[12:15]
	v_mfma_f32_16x16x32_bf16 v[64:67], v[142:145], v[204:207], v[64:67]
	v_mfma_f32_16x16x32_bf16 v[60:63], v[166:169], v[204:207], v[60:63]
	v_mfma_f32_16x16x32_bf16 v[48:51], v[142:145], v[212:215], v[48:51]
	v_mfma_f32_16x16x32_bf16 v[44:47], v[166:169], v[212:215], v[44:47]
	v_mfma_f32_16x16x32_bf16 v[32:35], v[142:145], v[236:239], v[32:35]
	v_mfma_f32_16x16x32_bf16 v[28:31], v[166:169], v[236:239], v[28:31]
	v_mfma_f32_16x16x32_bf16 v[16:19], v[142:145], v[244:247], v[16:19]
	v_mfma_f32_16x16x32_bf16 v[12:15], v[166:169], v[244:247], v[12:15]
	s_setprio 0
	s_setprio 1
	v_mfma_f32_16x16x32_bf16 v[56:59], v[170:173], v[200:203], v[56:59]
	v_mfma_f32_16x16x32_bf16 v[52:55], v[192:195], v[200:203], v[52:55]
	v_mfma_f32_16x16x32_bf16 v[40:43], v[170:173], v[208:211], v[40:43]
	v_mfma_f32_16x16x32_bf16 v[36:39], v[192:195], v[208:211], v[36:39]
	v_mfma_f32_16x16x32_bf16 v[24:27], v[170:173], v[216:219], v[24:27]
	v_mfma_f32_16x16x32_bf16 v[20:23], v[192:195], v[216:219], v[20:23]
	v_mfma_f32_16x16x32_bf16 v[8:11], v[170:173], v[240:243], v[8:11]
	v_mfma_f32_16x16x32_bf16 v[2:5], v[192:195], v[240:243], v[4:7]
	v_mfma_f32_16x16x32_bf16 v[56:59], v[184:187], v[204:207], v[56:59]
	v_mfma_f32_16x16x32_bf16 v[52:55], v[196:199], v[204:207], v[52:55]
	v_mfma_f32_16x16x32_bf16 v[40:43], v[184:187], v[212:215], v[40:43]
	v_mfma_f32_16x16x32_bf16 v[36:39], v[196:199], v[212:215], v[36:39]
	v_mfma_f32_16x16x32_bf16 v[24:27], v[184:187], v[236:239], v[24:27]
	v_mfma_f32_16x16x32_bf16 v[20:23], v[196:199], v[236:239], v[20:23]
	v_mfma_f32_16x16x32_bf16 v[8:11], v[184:187], v[244:247], v[8:11]
	v_mfma_f32_16x16x32_bf16 v[2:5], v[196:199], v[244:247], v[2:5]
	s_setprio 0
	s_barrier
	s_add_u32 s20, s20, 0x80000
	s_addc_u32 s21, s21, 0
	s_mov_b32 m0, s30
	v_lshl_add_u64 v[6:7], s[20:21], 0, v[148:149]
	global_load_lds_dwordx4 v[6:7], off
	v_lshl_add_u64 v[6:7], s[20:21], 0, v[152:153]
	s_mov_b32 m0, s36
	s_nop 0
	global_load_lds_dwordx4 v[6:7], off
	s_add_i32 s76, 0, 0x18000
	v_add_u32_e32 v0, s76, v188
	s_add_i32 s77, 0, 0x1c000
	ds_read_b128 v[138:141], v0
	ds_read_b128 v[142:145], v0 offset:1024
	ds_read_b128 v[162:165], v0 offset:2048
	ds_read_b128 v[166:169], v0 offset:3072
	v_add_u32_e32 v0, s77, v188
	ds_read_b128 v[170:173], v0
	ds_read_b128 v[184:187], v0 offset:1024
	ds_read_b128 v[192:195], v0 offset:2048
	ds_read_b128 v[196:199], v0 offset:3072
	ds_read_b128 v[200:203], v190 offset:32768
	ds_read_b128 v[204:207], v190 offset:33792
	ds_read_b128 v[208:211], v190 offset:34816
	ds_read_b128 v[212:215], v190 offset:35840
	ds_read_b128 v[216:219], v190 offset:36864
	ds_read_b128 v[236:239], v190 offset:37888
	ds_read_b128 v[240:243], v190 offset:38912
	ds_read_b128 v[244:247], v190 offset:39936
	s_waitcnt vmcnt(8)
	s_waitcnt lgkmcnt(0)
	s_barrier
	s_setprio 1
	s_waitcnt lgkmcnt(0)
	v_mfma_f32_16x16x32_bf16 v[128:131], v[138:141], v[200:203], v[128:131]
	v_mfma_f32_16x16x32_bf16 v[124:127], v[162:165], v[200:203], v[124:127]
	v_mfma_f32_16x16x32_bf16 v[112:115], v[138:141], v[208:211], v[112:115]
	v_mfma_f32_16x16x32_bf16 v[108:111], v[162:165], v[208:211], v[108:111]
	v_mfma_f32_16x16x32_bf16 v[96:99], v[138:141], v[216:219], v[96:99]
	v_mfma_f32_16x16x32_bf16 v[92:95], v[162:165], v[216:219], v[92:95]
	v_mfma_f32_16x16x32_bf16 v[80:83], v[138:141], v[240:243], v[80:83]
	v_mfma_f32_16x16x32_bf16 v[76:79], v[162:165], v[240:243], v[76:79]
	v_mfma_f32_16x16x32_bf16 v[128:131], v[142:145], v[204:207], v[128:131]
	v_mfma_f32_16x16x32_bf16 v[124:127], v[166:169], v[204:207], v[124:127]
	v_mfma_f32_16x16x32_bf16 v[112:115], v[142:145], v[212:215], v[112:115]
	v_mfma_f32_16x16x32_bf16 v[108:111], v[166:169], v[212:215], v[108:111]
	v_mfma_f32_16x16x32_bf16 v[96:99], v[142:145], v[236:239], v[96:99]
	v_mfma_f32_16x16x32_bf16 v[92:95], v[166:169], v[236:239], v[92:95]
	v_mfma_f32_16x16x32_bf16 v[80:83], v[142:145], v[244:247], v[80:83]
	v_mfma_f32_16x16x32_bf16 v[76:79], v[166:169], v[244:247], v[76:79]
	s_setprio 0
	s_setprio 1
	v_mfma_f32_16x16x32_bf16 v[120:123], v[170:173], v[200:203], v[120:123]
	v_mfma_f32_16x16x32_bf16 v[116:119], v[192:195], v[200:203], v[116:119]
	v_mfma_f32_16x16x32_bf16 v[104:107], v[170:173], v[208:211], v[104:107]
	v_mfma_f32_16x16x32_bf16 v[100:103], v[192:195], v[208:211], v[100:103]
	v_mfma_f32_16x16x32_bf16 v[88:91], v[170:173], v[216:219], v[88:91]
	v_mfma_f32_16x16x32_bf16 v[84:87], v[192:195], v[216:219], v[84:87]
	v_mfma_f32_16x16x32_bf16 v[72:75], v[170:173], v[240:243], v[72:75]
	v_mfma_f32_16x16x32_bf16 v[68:71], v[192:195], v[240:243], v[68:71]
	v_mfma_f32_16x16x32_bf16 v[120:123], v[184:187], v[204:207], v[120:123]
	v_mfma_f32_16x16x32_bf16 v[116:119], v[196:199], v[204:207], v[116:119]
	v_mfma_f32_16x16x32_bf16 v[104:107], v[184:187], v[212:215], v[104:107]
	v_mfma_f32_16x16x32_bf16 v[100:103], v[196:199], v[212:215], v[100:103]
	v_mfma_f32_16x16x32_bf16 v[88:91], v[184:187], v[236:239], v[88:91]
	v_mfma_f32_16x16x32_bf16 v[84:87], v[196:199], v[236:239], v[84:87]
	v_mfma_f32_16x16x32_bf16 v[72:75], v[184:187], v[244:247], v[72:75]
	v_mfma_f32_16x16x32_bf16 v[68:71], v[196:199], v[244:247], v[68:71]
	s_setprio 0
	s_barrier
; #define PG8_STAGE(bufoff, gbase, voff) do { _Pragma("unroll") for (int _i = 0; _i < 2; ++_i) \
;         __builtin_amdgcn_global_load_lds((const unsigned*)((const char*)(gbase) + (voff)[_i]), (PG8_LAS unsigned*)(lds + (bufoff) + ldsw + _i * 8192), 16, 0, 0); } while (0)
; #define PG8_LDA(dst, b, h) do { _Pragma("unroll") for (int m = 0; m < 4; ++m) _Pragma("unroll") for (int k = 0; k < 2; ++k) dst[m][k] = *(const PG8_LAS bf16x8*)(lds + PG8_SA(b, h) + aoff + m * 2048 + k * 1024); } while (0)
; template <class Epi, class Sched, bool ALIGN_EPI = true, bool SP2 = true, bool GS = false>
; __device__ __forceinline__ void gemm_phase(PG8_LAS unsigned char* lds, const Gemm g, const Sched& S, const Epi& E, const float* gs_ss = nullptr) {
;     ...
;             PG8_LDA(At, 1, 1); PG8_STAGE(PG8_SB(1, 0), b3, voffB); PG8_STAGE(PG8_SB(1, 1), b3 + hstep, voffB); PG8_STAGE(PG8_SA(1, 0), a3, voffA);
;             PG8_WAIT_V(8); PG8_WAIT_L(0); PG8_BAR; PG8_MMA(1, 0, At, B0); PG8_MMA(1, 1, At, B1); PG8_BAR; PG8_SCHED;
;             } else {
;             PG8_LDB(B0, 0, 0); PG8_SCHED; PG8_LDA(At, 0, 0); PG8_STAGE(PG8_SA(1, 1), a1 + hstep, voffA);
;             PG8_WAIT_L(8); PG8_BAR; PG8_WAIT_L(0); PG8_MMA(0, 0, At, B0); PG8_BAR; PG8_SCHED;
;             PG8_LDB(B1, 0, 1); PG8_STAGE(PG8_SB(0, 0), b2, voffB);
;             PG8_BAR; PG8_WAIT_L(0); PG8_MMA(0, 1, At, B1); PG8_BAR;
;             PG8_LDA(At, 0, 1); PG8_STAGE(PG8_SA(0, 0), a2, voffA);
;             PG8_BAR; PG8_WAIT_L(0); PG8_MMA(1, 0, At, B0); PG8_BAR; PG8_SCHED;
;             PG8_STAGE(PG8_SB(0, 1), b2 + hstep, voffB);
;             PG8_WAIT_V(6); PG8_BAR; PG8_MMA(1, 1, At, B1); PG8_BAR;
;             PG8_LDB(B0, 1, 0); PG8_SCHED; PG8_LDA(At, 1, 0); PG8_STAGE(PG8_SA(0, 1), a2 + hstep, voffA);
;             PG8_WAIT_L(8); PG8_BAR; PG8_WAIT_L(0); PG8_MMA(0, 0, At, B0); PG8_BAR; PG8_SCHED;
;             PG8_LDB(B1, 1, 1); PG8_STAGE(PG8_SB(1, 0), b3, voffB);
;             PG8_BAR; PG8_WAIT_L(0); PG8_MMA(0, 1, At, B1); PG8_BAR;
;             PG8_LDA(At, 1, 1); PG8_STAGE(PG8_SA(1, 0), a3, voffA);
;             PG8_BAR; PG8_WAIT_L(0); PG8_MMA(1, 0, At, B0); PG8_BAR; PG8_SCHED;
;             PG8_STAGE(PG8_SB(1, 1), b3 + hstep, voffB);
;             PG8_WAIT_V(6); PG8_BAR; PG8_MMA(1, 1, At, B1); PG8_BAR;
;                     }
;             if constexpr (GS) { if ((t & 7) == 6 && !last) { PG8_GS_SCALE(t >> 3, gpar); } }
	s_add_i32 s20, s76, s14
	v_lshl_add_u64 v[6:7], v[146:147], 0, s[26:27]
	s_mov_b32 m0, s20
	s_nop 0
	global_load_lds_dwordx4 v[6:7], off
	s_add_i32 m0, s20, 0x2000
	s_add_u32 s2, s2, 0x80080
	v_lshl_add_u64 v[6:7], v[174:175], 0, s[26:27]
	s_addc_u32 s3, s3, 0
	s_add_i32 s20, s77, s14
	global_load_lds_dwordx4 v[6:7], off
	v_lshl_add_u64 v[6:7], s[2:3], 0, v[150:151]
	s_mov_b32 m0, s20
	s_nop 0
	global_load_lds_dwordx4 v[6:7], off
	v_lshl_add_u64 v[6:7], s[2:3], 0, v[154:155]
	s_add_i32 m0, s20, 0x2000
	s_nop 0
	global_load_lds_dwordx4 v[6:7], off
	v_lshl_add_u64 v[6:7], v[180:181], 0, s[26:27]
	s_mov_b32 m0, s57
	s_nop 0
	global_load_lds_dwordx4 v[6:7], off
	v_lshl_add_u64 v[6:7], v[220:221], 0, s[26:27]
	s_mov_b32 m0, s64
	s_nop 0
	global_load_lds_dwordx4 v[6:7], off
	ds_read_b128 v[200:203], v190 offset:49152
	ds_read_b128 v[204:207], v190 offset:50176
	ds_read_b128 v[208:211], v190 offset:51200
	ds_read_b128 v[212:215], v190 offset:52224
	ds_read_b128 v[216:219], v190 offset:53248
	ds_read_b128 v[236:239], v190 offset:54272
	ds_read_b128 v[240:243], v190 offset:55296
	ds_read_b128 v[244:247], v190 offset:56320
	s_waitcnt vmcnt(8)
	s_waitcnt lgkmcnt(0)
	s_barrier
	s_setprio 1
	s_waitcnt lgkmcnt(0)
	v_mfma_f32_16x16x32_bf16 v[64:67], v[138:141], v[200:203], v[64:67]
	v_mfma_f32_16x16x32_bf16 v[60:63], v[162:165], v[200:203], v[60:63]
	v_mfma_f32_16x16x32_bf16 v[48:51], v[138:141], v[208:211], v[48:51]
	v_mfma_f32_16x16x32_bf16 v[44:47], v[162:165], v[208:211], v[44:47]
	v_mfma_f32_16x16x32_bf16 v[32:35], v[138:141], v[216:219], v[32:35]
	v_mfma_f32_16x16x32_bf16 v[28:31], v[162:165], v[216:219], v[28:31]
	v_mfma_f32_16x16x32_bf16 v[16:19], v[138:141], v[240:243], v[16:19]
	v_mfma_f32_16x16x32_bf16 v[12:15], v[162:165], v[240:243], v[12:15]
	v_mfma_f32_16x16x32_bf16 v[64:67], v[142:145], v[204:207], v[64:67]
	v_mfma_f32_16x16x32_bf16 v[60:63], v[166:169], v[204:207], v[60:63]
	v_mfma_f32_16x16x32_bf16 v[48:51], v[142:145], v[212:215], v[48:51]
	v_mfma_f32_16x16x32_bf16 v[44:47], v[166:169], v[212:215], v[44:47]
	v_mfma_f32_16x16x32_bf16 v[32:35], v[142:145], v[236:239], v[32:35]
	v_mfma_f32_16x16x32_bf16 v[28:31], v[166:169], v[236:239], v[28:31]
	v_mfma_f32_16x16x32_bf16 v[16:19], v[142:145], v[244:247], v[16:19]
	v_mfma_f32_16x16x32_bf16 v[12:15], v[166:169], v[244:247], v[12:15]
	s_setprio 0
	s_setprio 1
	v_mfma_f32_16x16x32_bf16 v[56:59], v[170:173], v[200:203], v[56:59]
	v_mfma_f32_16x16x32_bf16 v[52:55], v[192:195], v[200:203], v[52:55]
	v_mfma_f32_16x16x32_bf16 v[40:43], v[170:173], v[208:211], v[40:43]
	v_mfma_f32_16x16x32_bf16 v[36:39], v[192:195], v[208:211], v[36:39]
	v_mfma_f32_16x16x32_bf16 v[24:27], v[170:173], v[216:219], v[24:27]
	v_mfma_f32_16x16x32_bf16 v[20:23], v[192:195], v[216:219], v[20:23]
	v_mfma_f32_16x16x32_bf16 v[6:9], v[170:173], v[240:243], v[8:11]
	v_mfma_f32_16x16x32_bf16 v[2:5], v[192:195], v[240:243], v[2:5]
	v_mfma_f32_16x16x32_bf16 v[56:59], v[184:187], v[204:207], v[56:59]
	v_mfma_f32_16x16x32_bf16 v[52:55], v[196:199], v[204:207], v[52:55]
	v_mfma_f32_16x16x32_bf16 v[40:43], v[184:187], v[212:215], v[40:43]
	v_mfma_f32_16x16x32_bf16 v[36:39], v[196:199], v[212:215], v[36:39]
	v_mfma_f32_16x16x32_bf16 v[24:27], v[184:187], v[236:239], v[24:27]
	v_mfma_f32_16x16x32_bf16 v[20:23], v[196:199], v[236:239], v[20:23]
	v_mfma_f32_16x16x32_bf16 v[8:11], v[184:187], v[244:247], v[6:9]
	v_mfma_f32_16x16x32_bf16 v[4:7], v[196:199], v[244:247], v[2:5]
	s_setprio 0
	s_barrier
	s_and_b32 s2, s75, 6
	s_cmp_lg_u32 s2, 6
	s_cselect_b64 s[2:3], -1, 0
	s_or_b64 s[2:3], s[62:63], s[2:3]
	s_and_b64 vcc, exec, s[2:3]
	s_cbranch_vccnz .LBB0_1035
	s_and_b32 s2, s60, 0xc00
	v_add_u32_e32 v137, s2, v136
	v_add_u32_e32 v140, 0x400, v137
	ds_read2_b32 v[2:3], v137 offset1:16
	ds_read2_b32 v[138:139], v140 offset1:16
	s_waitcnt lgkmcnt(0)
	v_div_scale_f32 v0, s[2:3], v138, v138, v2
	v_rcp_f32_e32 v141, v0
	v_div_scale_f32 v142, vcc, v2, v138, v2
	v_fma_f32 v143, -v0, v141, 1.0
	v_fmac_f32_e32 v141, v143, v141
	v_mul_f32_e32 v143, v142, v141
	v_fma_f32 v144, -v0, v143, v142
	v_fmac_f32_e32 v143, v144, v141
	v_fma_f32 v0, -v0, v143, v142
	v_div_fmas_f32 v0, v0, v141, v143
	v_div_fixup_f32 v0, v0, v138, v2
	v_div_scale_f32 v2, s[2:3], v139, v139, v3
	v_rcp_f32_e32 v138, v2
	v_pk_mul_f32 v[130:131], v[130:131], v[0:1] op_sel_hi:[1,0]
	v_pk_mul_f32 v[128:129], v[128:129], v[0:1] op_sel_hi:[1,0]
	v_pk_mul_f32 v[126:127], v[126:127], v[0:1] op_sel_hi:[1,0]
	v_pk_mul_f32 v[124:125], v[124:125], v[0:1] op_sel_hi:[1,0]
	v_pk_mul_f32 v[122:123], v[122:123], v[0:1] op_sel_hi:[1,0]
	v_pk_mul_f32 v[120:121], v[120:121], v[0:1] op_sel_hi:[1,0]
	v_pk_mul_f32 v[118:119], v[118:119], v[0:1] op_sel_hi:[1,0]
	v_pk_mul_f32 v[116:117], v[116:117], v[0:1] op_sel_hi:[1,0]
	v_fma_f32 v0, -v2, v138, 1.0
	v_fmac_f32_e32 v138, v0, v138
	v_div_scale_f32 v0, vcc, v3, v139, v3
	v_mul_f32_e32 v141, v0, v138
	v_fma_f32 v142, -v2, v141, v0
	v_fmac_f32_e32 v141, v142, v138
	v_fma_f32 v0, -v2, v141, v0
	v_div_fmas_f32 v0, v0, v138, v141
	v_div_fixup_f32 v0, v0, v139, v3
	ds_read2_b32 v[2:3], v137 offset0:32 offset1:48
	ds_read2_b32 v[138:139], v140 offset0:32 offset1:48
	v_pk_mul_f32 v[114:115], v[114:115], v[0:1] op_sel_hi:[1,0]
	v_pk_mul_f32 v[112:113], v[112:113], v[0:1] op_sel_hi:[1,0]
	v_pk_mul_f32 v[110:111], v[110:111], v[0:1] op_sel_hi:[1,0]
	v_pk_mul_f32 v[108:109], v[108:109], v[0:1] op_sel_hi:[1,0]
	s_waitcnt lgkmcnt(0)
	v_div_scale_f32 v141, s[2:3], v138, v138, v2
	v_rcp_f32_e32 v142, v141
	v_pk_mul_f32 v[106:107], v[106:107], v[0:1] op_sel_hi:[1,0]
	v_pk_mul_f32 v[104:105], v[104:105], v[0:1] op_sel_hi:[1,0]
	v_pk_mul_f32 v[102:103], v[102:103], v[0:1] op_sel_hi:[1,0]
	v_pk_mul_f32 v[100:101], v[100:101], v[0:1] op_sel_hi:[1,0]
	v_fma_f32 v0, -v141, v142, 1.0
	v_fmac_f32_e32 v142, v0, v142
	v_div_scale_f32 v0, vcc, v2, v138, v2
	v_mul_f32_e32 v143, v0, v142
	v_fma_f32 v144, -v141, v143, v0
	v_fmac_f32_e32 v143, v144, v142
	v_fma_f32 v0, -v141, v143, v0
	v_div_fmas_f32 v0, v0, v142, v143
	v_div_fixup_f32 v0, v0, v138, v2
	v_div_scale_f32 v2, s[2:3], v139, v139, v3
	v_rcp_f32_e32 v138, v2
	v_pk_mul_f32 v[98:99], v[98:99], v[0:1] op_sel_hi:[1,0]
	v_pk_mul_f32 v[96:97], v[96:97], v[0:1] op_sel_hi:[1,0]
	v_pk_mul_f32 v[94:95], v[94:95], v[0:1] op_sel_hi:[1,0]
	v_pk_mul_f32 v[92:93], v[92:93], v[0:1] op_sel_hi:[1,0]
	v_pk_mul_f32 v[90:91], v[90:91], v[0:1] op_sel_hi:[1,0]
	v_pk_mul_f32 v[88:89], v[88:89], v[0:1] op_sel_hi:[1,0]
	v_pk_mul_f32 v[86:87], v[86:87], v[0:1] op_sel_hi:[1,0]
	v_pk_mul_f32 v[84:85], v[84:85], v[0:1] op_sel_hi:[1,0]
	v_fma_f32 v0, -v2, v138, 1.0
	v_fmac_f32_e32 v138, v0, v138
	v_div_scale_f32 v0, vcc, v3, v139, v3
	v_mul_f32_e32 v141, v0, v138
	v_fma_f32 v142, -v2, v141, v0
	v_fmac_f32_e32 v141, v142, v138
	v_fma_f32 v0, -v2, v141, v0
	v_div_fmas_f32 v0, v0, v138, v141
	v_div_fixup_f32 v0, v0, v139, v3
	ds_read2_b32 v[2:3], v137 offset0:128 offset1:144
	ds_read2_b32 v[138:139], v140 offset0:128 offset1:144
	v_pk_mul_f32 v[82:83], v[82:83], v[0:1] op_sel_hi:[1,0]
	v_pk_mul_f32 v[80:81], v[80:81], v[0:1] op_sel_hi:[1,0]
	v_pk_mul_f32 v[78:79], v[78:79], v[0:1] op_sel_hi:[1,0]
	v_pk_mul_f32 v[76:77], v[76:77], v[0:1] op_sel_hi:[1,0]
	s_waitcnt lgkmcnt(0)
	v_div_scale_f32 v141, s[2:3], v138, v138, v2
	v_rcp_f32_e32 v142, v141
	v_pk_mul_f32 v[74:75], v[74:75], v[0:1] op_sel_hi:[1,0]
	v_pk_mul_f32 v[72:73], v[72:73], v[0:1] op_sel_hi:[1,0]
	v_pk_mul_f32 v[70:71], v[70:71], v[0:1] op_sel_hi:[1,0]
	v_pk_mul_f32 v[68:69], v[68:69], v[0:1] op_sel_hi:[1,0]
	v_fma_f32 v0, -v141, v142, 1.0
	v_fmac_f32_e32 v142, v0, v142
	v_div_scale_f32 v0, vcc, v2, v138, v2
	v_mul_f32_e32 v143, v0, v142
	v_fma_f32 v144, -v141, v143, v0
	v_fmac_f32_e32 v143, v144, v142
	v_fma_f32 v0, -v141, v143, v0
	v_div_fmas_f32 v0, v0, v142, v143
	v_div_fixup_f32 v0, v0, v138, v2
	v_div_scale_f32 v2, s[2:3], v139, v139, v3
	v_rcp_f32_e32 v138, v2
	v_pk_mul_f32 v[66:67], v[66:67], v[0:1] op_sel_hi:[1,0]
	v_pk_mul_f32 v[64:65], v[64:65], v[0:1] op_sel_hi:[1,0]
	v_pk_mul_f32 v[62:63], v[62:63], v[0:1] op_sel_hi:[1,0]
	v_pk_mul_f32 v[60:61], v[60:61], v[0:1] op_sel_hi:[1,0]
	v_pk_mul_f32 v[58:59], v[58:59], v[0:1] op_sel_hi:[1,0]
	v_pk_mul_f32 v[56:57], v[56:57], v[0:1] op_sel_hi:[1,0]
	v_pk_mul_f32 v[54:55], v[54:55], v[0:1] op_sel_hi:[1,0]
	v_pk_mul_f32 v[52:53], v[52:53], v[0:1] op_sel_hi:[1,0]
	v_fma_f32 v0, -v2, v138, 1.0
	v_fmac_f32_e32 v138, v0, v138
	v_div_scale_f32 v0, vcc, v3, v139, v3
	v_mul_f32_e32 v141, v0, v138
	v_fma_f32 v142, -v2, v141, v0
	v_fmac_f32_e32 v141, v142, v138
	v_fma_f32 v0, -v2, v141, v0
	v_div_fmas_f32 v0, v0, v138, v141
	v_div_fixup_f32 v0, v0, v139, v3
	ds_read2_b32 v[2:3], v137 offset0:160 offset1:176
	ds_read2_b32 v[138:139], v140 offset0:160 offset1:176
	v_pk_mul_f32 v[50:51], v[50:51], v[0:1] op_sel_hi:[1,0]
	v_pk_mul_f32 v[48:49], v[48:49], v[0:1] op_sel_hi:[1,0]
	v_pk_mul_f32 v[46:47], v[46:47], v[0:1] op_sel_hi:[1,0]
	v_pk_mul_f32 v[44:45], v[44:45], v[0:1] op_sel_hi:[1,0]
	s_waitcnt lgkmcnt(0)
	v_div_scale_f32 v137, s[2:3], v138, v138, v2
	v_rcp_f32_e32 v140, v137
	v_pk_mul_f32 v[42:43], v[42:43], v[0:1] op_sel_hi:[1,0]
	v_pk_mul_f32 v[40:41], v[40:41], v[0:1] op_sel_hi:[1,0]
	v_pk_mul_f32 v[38:39], v[38:39], v[0:1] op_sel_hi:[1,0]
	v_pk_mul_f32 v[36:37], v[36:37], v[0:1] op_sel_hi:[1,0]
	v_fma_f32 v0, -v137, v140, 1.0
	v_fmac_f32_e32 v140, v0, v140
	v_div_scale_f32 v0, vcc, v2, v138, v2
	v_mul_f32_e32 v141, v0, v140
	v_fma_f32 v142, -v137, v141, v0
	v_fmac_f32_e32 v141, v142, v140
	v_fma_f32 v0, -v137, v141, v0
	v_div_fmas_f32 v0, v0, v140, v141
	v_div_fixup_f32 v0, v0, v138, v2
	v_div_scale_f32 v2, s[2:3], v139, v139, v3
	v_rcp_f32_e32 v137, v2
	v_pk_mul_f32 v[34:35], v[34:35], v[0:1] op_sel_hi:[1,0]
	v_pk_mul_f32 v[32:33], v[32:33], v[0:1] op_sel_hi:[1,0]
	v_pk_mul_f32 v[30:31], v[30:31], v[0:1] op_sel_hi:[1,0]
	v_pk_mul_f32 v[28:29], v[28:29], v[0:1] op_sel_hi:[1,0]
	v_pk_mul_f32 v[26:27], v[26:27], v[0:1] op_sel_hi:[1,0]
	v_pk_mul_f32 v[24:25], v[24:25], v[0:1] op_sel_hi:[1,0]
	v_pk_mul_f32 v[22:23], v[22:23], v[0:1] op_sel_hi:[1,0]
	v_pk_mul_f32 v[20:21], v[20:21], v[0:1] op_sel_hi:[1,0]
	v_fma_f32 v0, -v2, v137, 1.0
	v_fmac_f32_e32 v137, v0, v137
	v_div_scale_f32 v0, vcc, v3, v139, v3
	v_mul_f32_e32 v138, v0, v137
	v_fma_f32 v140, -v2, v138, v0
	v_fmac_f32_e32 v138, v140, v137
	v_fma_f32 v0, -v2, v138, v0
	v_div_fmas_f32 v0, v0, v137, v138
	v_div_fixup_f32 v0, v0, v139, v3
	v_pk_mul_f32 v[18:19], v[18:19], v[0:1] op_sel_hi:[1,0]
	v_pk_mul_f32 v[16:17], v[16:17], v[0:1] op_sel_hi:[1,0]
	v_pk_mul_f32 v[14:15], v[14:15], v[0:1] op_sel_hi:[1,0]
	v_pk_mul_f32 v[12:13], v[12:13], v[0:1] op_sel_hi:[1,0]
	v_pk_mul_f32 v[10:11], v[10:11], v[0:1] op_sel_hi:[1,0]
	v_pk_mul_f32 v[8:9], v[8:9], v[0:1] op_sel_hi:[1,0]
	v_pk_mul_f32 v[6:7], v[6:7], v[0:1] op_sel_hi:[1,0]
	v_pk_mul_f32 v[4:5], v[4:5], v[0:1] op_sel_hi:[1,0]
	s_branch .LBB0_1035

;     __device__ bool next(int i, Unit& u) const { const int L = i * G + c; if (L >= 192) return false; u.pm = L / 6; u.pn = L % 6; return true; }
;     __device__ __forceinline__ size_t a_extra(const Unit& u) const { return (size_t)(u.pn >> 1) * ((size_t)T * 512 * 2); }
;     __device__ bool next(int i, Unit& u) const { const int L = i * G + c; if (L >= 256) return false; u.pm = L >> 3; u.pn = L & 7; return true; }
;     __device__ __forceinline__ size_t a_extra(const Unit& u) const { return (size_t)(u.pn >> 1) * 512 * 2; }
;     __device__ __forceinline__ size_t b_extra(const Unit& u) const { return (size_t)(u.pn >> 1) * 512 * 2 - (size_t)(u.pn & ~1) * ((size_t)256 * D * 2); }
; #define PG8_STAGE(bufoff, gbase, voff) do { _Pragma("unroll") for (int _i = 0; _i < 2; ++_i) \
;         __builtin_amdgcn_global_load_lds((const unsigned*)((const char*)(gbase) + (voff)[_i]), (PG8_LAS unsigned*)(lds + (bufoff) + ldsw + _i * 8192), 16, 0, 0); } while (0)
; template <class Epi, class Sched, bool ALIGN_EPI = true, bool SP2 = true, bool GS = false>
; __device__ __forceinline__ void gemm_phase(PG8_LAS unsigned char* lds, const Gemm g, const Sched& S, const Epi& E, const float* gs_ss = nullptr) {
;     ...
;         const bool has_next = S.next(ui + 1, nxt);
;         const char* nA = has_next ? (const char*)g.A + S.a_extra(nxt) + (size_t)nxt.pm * tstep : cA; const char* nB = has_next ? (const char*)g.Bt + S.b_extra(nxt) + (size_t)nxt.pn * tstep : cB;
;         for (int t = 0; t < nt; t += 2) {
;             const bool last = (t == nt - 2);
;             const char* a1 = cA + (size_t)(t + 1) * kstep;
;             const char* a2 = last ? nA : cA + (size_t)(t + 2) * kstep; const char* b2 = last ? nB : cB + (size_t)(t + 2) * kstep;
;             const char* a3 = a2 + kstep; const char* b3 = b2 + kstep;
;             if constexpr (SP2) {
;             PG8_LDB(B0, 0, 0); PG8_LDB(B1, 0, 1); PG8_SCHED; PG8_LDA(At, 0, 0); PG8_STAGE(PG8_SA(1, 1), a1 + hstep, voffA);
;             PG8_WAIT_V(8); PG8_WAIT_L(0); PG8_BAR; PG8_MMA(0, 0, At, B0); PG8_MMA(0, 1, At, B1); PG8_BAR; PG8_SCHED;
;             PG8_LDA(At, 0, 1); PG8_STAGE(PG8_SB(0, 0), b2, voffB); PG8_STAGE(PG8_SB(0, 1), b2 + hstep, voffB); PG8_STAGE(PG8_SA(0, 0), a2, voffA);
;             PG8_WAIT_V(8); PG8_WAIT_L(0); PG8_BAR; PG8_MMA(1, 0, At, B0); PG8_MMA(1, 1, At, B1); PG8_BAR; PG8_SCHED;
.LBB0_1119:
	s_add_u32 s2, s44, 0xfff80080
	s_addc_u32 s3, s45, -1
	s_cmp_eq_u32 s58, 4
	s_cselect_b32 s21, s52, s3
	s_cselect_b32 s20, s53, s2
	s_cselect_b32 s3, s54, s57
	s_cselect_b32 s2, s55, s56
	v_lshl_add_u64 v[142:143], s[44:45], 0, v[138:139]
	s_add_i32 m0, s9, 0xc000
	s_nop 0
	global_load_lds_dwordx4 v[142:143], off
	v_lshl_add_u64 v[142:143], s[44:45], 0, v[140:141]
	s_add_i32 m0, s9, 0xe000
	s_nop 0
	global_load_lds_dwordx4 v[142:143], off
	s_add_i32 s59, 0, 0x10000
	v_add_u32_e32 v0, s59, v145
	s_add_i32 s62, 0, 0x14000
	ds_read_b128 v[148:151], v0
	ds_read_b128 v[152:155], v0 offset:1024
	ds_read_b128 v[156:159], v0 offset:2048
	ds_read_b128 v[160:163], v0 offset:3072
	v_add_u32_e32 v0, s62, v145
	ds_read_b128 v[164:167], v0
	ds_read_b128 v[168:171], v0 offset:1024
	ds_read_b128 v[172:175], v0 offset:2048
	ds_read_b128 v[180:183], v0 offset:3072
	ds_read_b128 v[184:187], v147
	ds_read_b128 v[188:191], v147 offset:1024
	ds_read_b128 v[192:195], v147 offset:2048
	ds_read_b128 v[196:199], v147 offset:3072
	ds_read_b128 v[200:203], v147 offset:4096
	ds_read_b128 v[204:207], v147 offset:5120
	ds_read_b128 v[208:211], v147 offset:6144
	ds_read_b128 v[212:215], v147 offset:7168
	s_waitcnt vmcnt(8)
	s_waitcnt lgkmcnt(0)
	s_barrier
	s_setprio 1
	s_waitcnt lgkmcnt(0)
	v_mfma_f32_16x16x32_bf16 v[126:129], v[148:151], v[184:187], v[126:129]
	v_mfma_f32_16x16x32_bf16 v[122:125], v[156:159], v[184:187], v[122:125]
	v_mfma_f32_16x16x32_bf16 v[118:121], v[148:151], v[192:195], v[118:121]
	v_mfma_f32_16x16x32_bf16 v[110:113], v[156:159], v[192:195], v[110:113]
	v_mfma_f32_16x16x32_bf16 v[102:105], v[148:151], v[200:203], v[102:105]
	v_mfma_f32_16x16x32_bf16 v[94:97], v[156:159], v[200:203], v[94:97]
	v_mfma_f32_16x16x32_bf16 v[86:89], v[148:151], v[208:211], v[86:89]
	v_mfma_f32_16x16x32_bf16 v[78:81], v[156:159], v[208:211], v[78:81]
	v_mfma_f32_16x16x32_bf16 v[126:129], v[152:155], v[188:191], v[126:129]
	v_mfma_f32_16x16x32_bf16 v[122:125], v[160:163], v[188:191], v[122:125]
	v_mfma_f32_16x16x32_bf16 v[118:121], v[152:155], v[196:199], v[118:121]
	v_mfma_f32_16x16x32_bf16 v[110:113], v[160:163], v[196:199], v[110:113]
	v_mfma_f32_16x16x32_bf16 v[102:105], v[152:155], v[204:207], v[102:105]
	v_mfma_f32_16x16x32_bf16 v[94:97], v[160:163], v[204:207], v[94:97]
	v_mfma_f32_16x16x32_bf16 v[86:89], v[152:155], v[212:215], v[86:89]
	v_mfma_f32_16x16x32_bf16 v[78:81], v[160:163], v[212:215], v[78:81]
	s_setprio 0
	s_setprio 1
	v_mfma_f32_16x16x32_bf16 v[114:117], v[164:167], v[184:187], v[114:117]
	v_mfma_f32_16x16x32_bf16 v[106:109], v[172:175], v[184:187], v[106:109]
	v_mfma_f32_16x16x32_bf16 v[98:101], v[164:167], v[192:195], v[98:101]
	v_mfma_f32_16x16x32_bf16 v[90:93], v[172:175], v[192:195], v[90:93]
	v_mfma_f32_16x16x32_bf16 v[82:85], v[164:167], v[200:203], v[82:85]
	v_mfma_f32_16x16x32_bf16 v[74:77], v[172:175], v[200:203], v[74:77]
	v_mfma_f32_16x16x32_bf16 v[70:73], v[164:167], v[208:211], v[70:73]
	v_mfma_f32_16x16x32_bf16 v[66:69], v[172:175], v[208:211], v[66:69]
	v_mfma_f32_16x16x32_bf16 v[114:117], v[168:171], v[188:191], v[114:117]
	v_mfma_f32_16x16x32_bf16 v[106:109], v[180:183], v[188:191], v[106:109]
	v_mfma_f32_16x16x32_bf16 v[98:101], v[168:171], v[196:199], v[98:101]
	v_mfma_f32_16x16x32_bf16 v[90:93], v[180:183], v[196:199], v[90:93]
	v_mfma_f32_16x16x32_bf16 v[82:85], v[168:171], v[204:207], v[82:85]
	v_mfma_f32_16x16x32_bf16 v[74:77], v[180:183], v[204:207], v[74:77]
	v_mfma_f32_16x16x32_bf16 v[70:73], v[168:171], v[212:215], v[70:73]
	v_mfma_f32_16x16x32_bf16 v[66:69], v[180:183], v[212:215], v[66:69]
	s_setprio 0
	s_barrier
	s_add_i32 s59, s59, s23
	v_lshl_add_u64 v[142:143], s[2:3], 0, v[134:135]
	s_mov_b32 m0, s59
	s_nop 0
	global_load_lds_dwordx4 v[142:143], off
	s_add_i32 m0, s59, 0x2000
	s_add_u32 s60, s2, 0x80000
	v_lshl_add_u64 v[176:177], s[2:3], 0, v[130:131]
	s_addc_u32 s61, s3, 0
	s_add_i32 s59, s62, s23
	global_load_lds_dwordx4 v[176:177], off
	v_lshl_add_u64 v[216:217], s[60:61], 0, v[134:135]
	s_mov_b32 m0, s59
	v_lshl_add_u64 v[218:219], s[20:21], 0, v[132:133]
	global_load_lds_dwordx4 v[216:217], off
	v_lshl_add_u64 v[216:217], s[60:61], 0, v[130:131]
	s_add_i32 m0, s59, 0x2000
	s_nop 0
	global_load_lds_dwordx4 v[216:217], off
	v_lshl_add_u64 v[216:217], s[20:21], 0, v[136:137]
	s_mov_b32 m0, s9
	s_nop 0
	global_load_lds_dwordx4 v[216:217], off
	s_mov_b32 m0, s25
	s_nop 0
	global_load_lds_dwordx4 v[218:219], off
	ds_read_b128 v[184:187], v147 offset:16384
	ds_read_b128 v[188:191], v147 offset:17408
	ds_read_b128 v[192:195], v147 offset:18432
	ds_read_b128 v[196:199], v147 offset:19456
	ds_read_b128 v[200:203], v147 offset:20480
	ds_read_b128 v[204:207], v147 offset:21504
	ds_read_b128 v[208:211], v147 offset:22528
	ds_read_b128 v[212:215], v147 offset:23552
	s_waitcnt vmcnt(8)
	s_waitcnt lgkmcnt(0)
	s_barrier
; #define PG8_STAGE(bufoff, gbase, voff) do { _Pragma("unroll") for (int _i = 0; _i < 2; ++_i) \
;         __builtin_amdgcn_global_load_lds((const unsigned*)((const char*)(gbase) + (voff)[_i]), (PG8_LAS unsigned*)(lds + (bufoff) + ldsw + _i * 8192), 16, 0, 0); } while (0)
; #define PG8_LDA(dst, b, h) do { _Pragma("unroll") for (int m = 0; m < 4; ++m) _Pragma("unroll") for (int k = 0; k < 2; ++k) dst[m][k] = *(const PG8_LAS bf16x8*)(lds + PG8_SA(b, h) + aoff + m * 2048 + k * 1024); } while (0)
; #define PG8_LDB(dst, b, h) do { _Pragma("unroll") for (int n = 0; n < 2; ++n) _Pragma("unroll") for (int k = 0; k < 2; ++k) dst[n][k] = *(const PG8_LAS bf16x8*)(lds + PG8_SB(b, h) + boff + n * 2048 + k * 1024); } while (0)
; #define PG8_MMA(ai, bj, At, Bt) do { __builtin_amdgcn_s_setprio(1); _Pragma("unroll") for (int m = 0; m < 4; ++m) _Pragma("unroll") for (int n = 0; n < 2; ++n) _Pragma("unroll") for (int k = 0; k < 2; ++k) \
;         acc[ai][bj][m][n] = __builtin_amdgcn_mfma_f32_16x16x32_bf16(Bt[n][k], At[m][k], acc[ai][bj][m][n], 0, 0, 0); __builtin_amdgcn_s_setprio(0); } while (0)
; #define PG8_WAIT_V(n) asm volatile("s_waitcnt vmcnt(" #n ")" ::: "memory")
; #define PG8_WAIT_L(n) asm volatile("s_waitcnt lgkmcnt(" #n ")" ::: "memory")
; #define PG8_BAR __builtin_amdgcn_s_barrier()
; #define PG8_SCHED __builtin_amdgcn_sched_barrier(0)
; template <class Epi, class Sched, bool ALIGN_EPI = true, bool SP2 = true, bool GS = false>
; __device__ __forceinline__ void gemm_phase(PG8_LAS unsigned char* lds, const Gemm g, const Sched& S, const Epi& E, const float* gs_ss = nullptr) {
;     ...
;             PG8_WAIT_V(8); PG8_WAIT_L(0); PG8_BAR; PG8_MMA(1, 0, At, B0); PG8_MMA(1, 1, At, B1); PG8_BAR; PG8_SCHED;
;             PG8_LDB(B0, 1, 0); PG8_LDB(B1, 1, 1); PG8_SCHED; PG8_LDA(At, 1, 0); PG8_STAGE(PG8_SA(0, 1), a2 + hstep, voffA);
;             PG8_WAIT_V(8); PG8_WAIT_L(0); PG8_BAR; PG8_MMA(0, 0, At, B0); PG8_MMA(0, 1, At, B1); PG8_BAR; PG8_SCHED;
	s_setprio 1
	s_waitcnt lgkmcnt(0)
	v_mfma_f32_16x16x32_bf16 v[62:65], v[148:151], v[184:187], v[62:65]
	v_mfma_f32_16x16x32_bf16 v[58:61], v[156:159], v[184:187], v[58:61]
	v_mfma_f32_16x16x32_bf16 v[54:57], v[148:151], v[192:195], v[54:57]
	v_mfma_f32_16x16x32_bf16 v[46:49], v[156:159], v[192:195], v[46:49]
	v_mfma_f32_16x16x32_bf16 v[38:41], v[148:151], v[200:203], v[38:41]
	v_mfma_f32_16x16x32_bf16 v[30:33], v[156:159], v[200:203], v[30:33]
	v_mfma_f32_16x16x32_bf16 v[22:25], v[148:151], v[208:211], v[22:25]
	v_mfma_f32_16x16x32_bf16 v[14:17], v[156:159], v[208:211], v[14:17]
	v_mfma_f32_16x16x32_bf16 v[62:65], v[152:155], v[188:191], v[62:65]
	v_mfma_f32_16x16x32_bf16 v[58:61], v[160:163], v[188:191], v[58:61]
	v_mfma_f32_16x16x32_bf16 v[54:57], v[152:155], v[196:199], v[54:57]
	v_mfma_f32_16x16x32_bf16 v[46:49], v[160:163], v[196:199], v[46:49]
	v_mfma_f32_16x16x32_bf16 v[38:41], v[152:155], v[204:207], v[38:41]
	v_mfma_f32_16x16x32_bf16 v[30:33], v[160:163], v[204:207], v[30:33]
	v_mfma_f32_16x16x32_bf16 v[22:25], v[152:155], v[212:215], v[22:25]
	v_mfma_f32_16x16x32_bf16 v[14:17], v[160:163], v[212:215], v[14:17]
	s_setprio 0
	s_setprio 1
	v_mfma_f32_16x16x32_bf16 v[50:53], v[164:167], v[184:187], v[50:53]
	v_mfma_f32_16x16x32_bf16 v[42:45], v[172:175], v[184:187], v[42:45]
	v_mfma_f32_16x16x32_bf16 v[34:37], v[164:167], v[192:195], v[34:37]
	v_mfma_f32_16x16x32_bf16 v[26:29], v[172:175], v[192:195], v[26:29]
	v_mfma_f32_16x16x32_bf16 v[18:21], v[164:167], v[200:203], v[18:21]
	v_mfma_f32_16x16x32_bf16 v[10:13], v[172:175], v[200:203], v[10:13]
	v_mfma_f32_16x16x32_bf16 v[6:9], v[164:167], v[208:211], v[6:9]
	v_mfma_f32_16x16x32_bf16 v[2:5], v[172:175], v[208:211], v[2:5]
	v_mfma_f32_16x16x32_bf16 v[50:53], v[168:171], v[188:191], v[50:53]
	v_mfma_f32_16x16x32_bf16 v[42:45], v[180:183], v[188:191], v[42:45]
	v_mfma_f32_16x16x32_bf16 v[34:37], v[168:171], v[196:199], v[34:37]
	v_mfma_f32_16x16x32_bf16 v[26:29], v[180:183], v[196:199], v[26:29]
	v_mfma_f32_16x16x32_bf16 v[18:21], v[168:171], v[204:207], v[18:21]
	v_mfma_f32_16x16x32_bf16 v[10:13], v[180:183], v[204:207], v[10:13]
	v_mfma_f32_16x16x32_bf16 v[6:9], v[168:171], v[212:215], v[6:9]
	v_mfma_f32_16x16x32_bf16 v[2:5], v[180:183], v[212:215], v[2:5]
	s_setprio 0
	s_barrier
	s_add_u32 s20, s20, 0x80000
	s_addc_u32 s21, s21, 0
	s_mov_b32 m0, s30
	v_lshl_add_u64 v[220:221], s[20:21], 0, v[136:137]
	global_load_lds_dwordx4 v[220:221], off
	v_lshl_add_u64 v[220:221], s[20:21], 0, v[132:133]
	s_mov_b32 m0, s36
	s_nop 0
	global_load_lds_dwordx4 v[220:221], off
	s_add_i32 s59, 0, 0x18000
	v_add_u32_e32 v0, s59, v145
	s_add_i32 s60, 0, 0x1c000
	ds_read_b128 v[148:151], v0
	ds_read_b128 v[152:155], v0 offset:1024
	ds_read_b128 v[156:159], v0 offset:2048
	ds_read_b128 v[160:163], v0 offset:3072
	v_add_u32_e32 v0, s60, v145
	ds_read_b128 v[164:167], v0
	ds_read_b128 v[168:171], v0 offset:1024
	ds_read_b128 v[172:175], v0 offset:2048
	ds_read_b128 v[180:183], v0 offset:3072
	ds_read_b128 v[184:187], v147 offset:32768
	ds_read_b128 v[188:191], v147 offset:33792
	ds_read_b128 v[192:195], v147 offset:34816
	ds_read_b128 v[196:199], v147 offset:35840
	ds_read_b128 v[200:203], v147 offset:36864
	ds_read_b128 v[204:207], v147 offset:37888
	ds_read_b128 v[208:211], v147 offset:38912
	ds_read_b128 v[212:215], v147 offset:39936
	s_waitcnt vmcnt(8)
	s_waitcnt lgkmcnt(0)
	s_barrier
	s_setprio 1
	s_waitcnt lgkmcnt(0)
	v_mfma_f32_16x16x32_bf16 v[126:129], v[148:151], v[184:187], v[126:129]
	v_mfma_f32_16x16x32_bf16 v[122:125], v[156:159], v[184:187], v[122:125]
	v_mfma_f32_16x16x32_bf16 v[118:121], v[148:151], v[192:195], v[118:121]
	v_mfma_f32_16x16x32_bf16 v[110:113], v[156:159], v[192:195], v[110:113]
	v_mfma_f32_16x16x32_bf16 v[102:105], v[148:151], v[200:203], v[102:105]
	v_mfma_f32_16x16x32_bf16 v[94:97], v[156:159], v[200:203], v[94:97]
	v_mfma_f32_16x16x32_bf16 v[86:89], v[148:151], v[208:211], v[86:89]
	v_mfma_f32_16x16x32_bf16 v[78:81], v[156:159], v[208:211], v[78:81]
	v_mfma_f32_16x16x32_bf16 v[126:129], v[152:155], v[188:191], v[126:129]
	v_mfma_f32_16x16x32_bf16 v[122:125], v[160:163], v[188:191], v[122:125]
	v_mfma_f32_16x16x32_bf16 v[118:121], v[152:155], v[196:199], v[118:121]
	v_mfma_f32_16x16x32_bf16 v[110:113], v[160:163], v[196:199], v[110:113]
	v_mfma_f32_16x16x32_bf16 v[102:105], v[152:155], v[204:207], v[102:105]
	v_mfma_f32_16x16x32_bf16 v[94:97], v[160:163], v[204:207], v[94:97]
	v_mfma_f32_16x16x32_bf16 v[86:89], v[152:155], v[212:215], v[86:89]
	v_mfma_f32_16x16x32_bf16 v[78:81], v[160:163], v[212:215], v[78:81]
	s_setprio 0
	s_setprio 1
	v_mfma_f32_16x16x32_bf16 v[114:117], v[164:167], v[184:187], v[114:117]
	v_mfma_f32_16x16x32_bf16 v[106:109], v[172:175], v[184:187], v[106:109]
	v_mfma_f32_16x16x32_bf16 v[98:101], v[164:167], v[192:195], v[98:101]
	v_mfma_f32_16x16x32_bf16 v[90:93], v[172:175], v[192:195], v[90:93]
	v_mfma_f32_16x16x32_bf16 v[82:85], v[164:167], v[200:203], v[82:85]
	v_mfma_f32_16x16x32_bf16 v[74:77], v[172:175], v[200:203], v[74:77]
	v_mfma_f32_16x16x32_bf16 v[70:73], v[164:167], v[208:211], v[70:73]
	v_mfma_f32_16x16x32_bf16 v[66:69], v[172:175], v[208:211], v[66:69]
	v_mfma_f32_16x16x32_bf16 v[114:117], v[168:171], v[188:191], v[114:117]
	v_mfma_f32_16x16x32_bf16 v[106:109], v[180:183], v[188:191], v[106:109]
	v_mfma_f32_16x16x32_bf16 v[98:101], v[168:171], v[196:199], v[98:101]
	v_mfma_f32_16x16x32_bf16 v[90:93], v[180:183], v[196:199], v[90:93]
	v_mfma_f32_16x16x32_bf16 v[82:85], v[168:171], v[204:207], v[82:85]
	v_mfma_f32_16x16x32_bf16 v[74:77], v[180:183], v[204:207], v[74:77]
	v_mfma_f32_16x16x32_bf16 v[70:73], v[168:171], v[212:215], v[70:73]
	v_mfma_f32_16x16x32_bf16 v[66:69], v[180:183], v[212:215], v[66:69]
	s_setprio 0
	s_barrier
; #define PG8_STAGE(bufoff, gbase, voff) do { _Pragma("unroll") for (int _i = 0; _i < 2; ++_i) \
;         __builtin_amdgcn_global_load_lds((const unsigned*)((const char*)(gbase) + (voff)[_i]), (PG8_LAS unsigned*)(lds + (bufoff) + ldsw + _i * 8192), 16, 0, 0); } while (0)
; #define PG8_LDA(dst, b, h) do { _Pragma("unroll") for (int m = 0; m < 4; ++m) _Pragma("unroll") for (int k = 0; k < 2; ++k) dst[m][k] = *(const PG8_LAS bf16x8*)(lds + PG8_SA(b, h) + aoff + m * 2048 + k * 1024); } while (0)
; #define PG8_MMA(ai, bj, At, Bt) do { __builtin_amdgcn_s_setprio(1); _Pragma("unroll") for (int m = 0; m < 4; ++m) _Pragma("unroll") for (int n = 0; n < 2; ++n) _Pragma("unroll") for (int k = 0; k < 2; ++k) \
;         acc[ai][bj][m][n] = __builtin_amdgcn_mfma_f32_16x16x32_bf16(Bt[n][k], At[m][k], acc[ai][bj][m][n], 0, 0, 0); __builtin_amdgcn_s_setprio(0); } while (0)
; #define PG8_WAIT_V(n) asm volatile("s_waitcnt vmcnt(" #n ")" ::: "memory")
; #define PG8_WAIT_L(n) asm volatile("s_waitcnt lgkmcnt(" #n ")" ::: "memory")
; #define PG8_BAR __builtin_amdgcn_s_barrier()
; #define PG8_SCHED __builtin_amdgcn_sched_barrier(0)
; template <class Epi, class Sched, bool ALIGN_EPI = true, bool SP2 = true, bool GS = false>
; __device__ __forceinline__ void gemm_phase(PG8_LAS unsigned char* lds, const Gemm g, const Sched& S, const Epi& E, const float* gs_ss = nullptr) {
;     ...
;             PG8_LDA(At, 1, 1); PG8_STAGE(PG8_SB(1, 0), b3, voffB); PG8_STAGE(PG8_SB(1, 1), b3 + hstep, voffB); PG8_STAGE(PG8_SA(1, 0), a3, voffA);
;             PG8_WAIT_V(8); PG8_WAIT_L(0); PG8_BAR; PG8_MMA(1, 0, At, B0); PG8_MMA(1, 1, At, B1); PG8_BAR; PG8_SCHED;
	s_add_i32 s20, s59, s23
	v_lshl_add_u64 v[142:143], v[142:143], 0, s[26:27]
	s_mov_b32 m0, s20
	s_nop 0
	global_load_lds_dwordx4 v[142:143], off
	s_add_i32 m0, s20, 0x2000
	s_add_u32 s2, s2, 0x80080
	v_lshl_add_u64 v[142:143], v[176:177], 0, s[26:27]
	s_addc_u32 s3, s3, 0
	s_add_i32 s20, s60, s23
	global_load_lds_dwordx4 v[142:143], off
	v_lshl_add_u64 v[142:143], s[2:3], 0, v[134:135]
	s_mov_b32 m0, s20
	s_nop 0
	global_load_lds_dwordx4 v[142:143], off
	v_lshl_add_u64 v[142:143], s[2:3], 0, v[130:131]
	s_add_i32 m0, s20, 0x2000
	s_nop 0
	global_load_lds_dwordx4 v[142:143], off
	v_lshl_add_u64 v[142:143], v[216:217], 0, s[26:27]
	s_mov_b32 m0, s47
	s_nop 0
	global_load_lds_dwordx4 v[142:143], off
	v_lshl_add_u64 v[142:143], v[218:219], 0, s[26:27]
	s_mov_b32 m0, s48
	s_nop 0
	global_load_lds_dwordx4 v[142:143], off
	ds_read_b128 v[184:187], v147 offset:49152
	ds_read_b128 v[188:191], v147 offset:50176
	ds_read_b128 v[192:195], v147 offset:51200
	ds_read_b128 v[196:199], v147 offset:52224
	ds_read_b128 v[200:203], v147 offset:53248
	ds_read_b128 v[204:207], v147 offset:54272
	ds_read_b128 v[208:211], v147 offset:55296
	ds_read_b128 v[212:215], v147 offset:56320
	s_waitcnt vmcnt(8)
	s_waitcnt lgkmcnt(0)
	s_barrier
	s_setprio 1
	s_waitcnt lgkmcnt(0)
	v_mfma_f32_16x16x32_bf16 v[62:65], v[148:151], v[184:187], v[62:65]
	v_mfma_f32_16x16x32_bf16 v[58:61], v[156:159], v[184:187], v[58:61]
	v_mfma_f32_16x16x32_bf16 v[54:57], v[148:151], v[192:195], v[54:57]
	v_mfma_f32_16x16x32_bf16 v[46:49], v[156:159], v[192:195], v[46:49]
	v_mfma_f32_16x16x32_bf16 v[38:41], v[148:151], v[200:203], v[38:41]
	v_mfma_f32_16x16x32_bf16 v[30:33], v[156:159], v[200:203], v[30:33]
	v_mfma_f32_16x16x32_bf16 v[22:25], v[148:151], v[208:211], v[22:25]
	v_mfma_f32_16x16x32_bf16 v[14:17], v[156:159], v[208:211], v[14:17]
	v_mfma_f32_16x16x32_bf16 v[62:65], v[152:155], v[188:191], v[62:65]
	v_mfma_f32_16x16x32_bf16 v[58:61], v[160:163], v[188:191], v[58:61]
	v_mfma_f32_16x16x32_bf16 v[54:57], v[152:155], v[196:199], v[54:57]
	v_mfma_f32_16x16x32_bf16 v[46:49], v[160:163], v[196:199], v[46:49]
	v_mfma_f32_16x16x32_bf16 v[38:41], v[152:155], v[204:207], v[38:41]
	v_mfma_f32_16x16x32_bf16 v[30:33], v[160:163], v[204:207], v[30:33]
	v_mfma_f32_16x16x32_bf16 v[22:25], v[152:155], v[212:215], v[22:25]
	v_mfma_f32_16x16x32_bf16 v[14:17], v[160:163], v[212:215], v[14:17]
	s_setprio 0
	s_setprio 1
	v_mfma_f32_16x16x32_bf16 v[50:53], v[164:167], v[184:187], v[50:53]
	v_mfma_f32_16x16x32_bf16 v[42:45], v[172:175], v[184:187], v[42:45]
	v_mfma_f32_16x16x32_bf16 v[34:37], v[164:167], v[192:195], v[34:37]
	v_mfma_f32_16x16x32_bf16 v[26:29], v[172:175], v[192:195], v[26:29]
	v_mfma_f32_16x16x32_bf16 v[18:21], v[164:167], v[200:203], v[18:21]
	v_mfma_f32_16x16x32_bf16 v[10:13], v[172:175], v[200:203], v[10:13]
	v_mfma_f32_16x16x32_bf16 v[6:9], v[164:167], v[208:211], v[6:9]
	v_mfma_f32_16x16x32_bf16 v[2:5], v[172:175], v[208:211], v[2:5]
	v_mfma_f32_16x16x32_bf16 v[50:53], v[168:171], v[188:191], v[50:53]
	v_mfma_f32_16x16x32_bf16 v[42:45], v[180:183], v[188:191], v[42:45]
	v_mfma_f32_16x16x32_bf16 v[34:37], v[168:171], v[196:199], v[34:37]
	v_mfma_f32_16x16x32_bf16 v[26:29], v[180:183], v[196:199], v[26:29]
	v_mfma_f32_16x16x32_bf16 v[18:21], v[168:171], v[204:207], v[18:21]
	v_mfma_f32_16x16x32_bf16 v[10:13], v[180:183], v[204:207], v[10:13]
	v_mfma_f32_16x16x32_bf16 v[6:9], v[168:171], v[212:215], v[6:9]
	v_mfma_f32_16x16x32_bf16 v[2:5], v[180:183], v[212:215], v[2:5]
	s_setprio 0
	s_barrier
	s_add_i32 s58, s58, 2
	s_add_u32 s44, s44, 0x100
	s_addc_u32 s45, s45, 0
	s_add_u32 s56, s56, 0x100
	s_addc_u32 s57, s57, 0
	s_cmp_gt_u32 s58, 5
	s_cbranch_scc0 .LBB0_1119
	s_and_b64 vcc, exec, s[38:39]
	s_cbranch_vccz .LBB0_1122
	s_barrier

;     __device__ bool next(int i, Unit& u) const { const int L = i * G + c; if (L >= 192) return false; u.pm = L / 6; u.pn = L % 6; return true; }
;     __device__ __forceinline__ size_t a_extra(const Unit& u) const { return (size_t)(u.pn >> 1) * ((size_t)T * 512 * 2); }
;     __device__ bool next(int i, Unit& u) const { const int L = i * G + c; if (L >= 256) return false; u.pm = L >> 3; u.pn = L & 7; return true; }
;     __device__ __forceinline__ size_t a_extra(const Unit& u) const { return (size_t)(u.pn >> 1) * 512 * 2; }
;     __device__ __forceinline__ size_t b_extra(const Unit& u) const { return (size_t)(u.pn >> 1) * 512 * 2 - (size_t)(u.pn & ~1) * ((size_t)256 * D * 2); }
; #define PG8_STAGE(bufoff, gbase, voff) do { _Pragma("unroll") for (int _i = 0; _i < 2; ++_i) \
;         __builtin_amdgcn_global_load_lds((const unsigned*)((const char*)(gbase) + (voff)[_i]), (PG8_LAS unsigned*)(lds + (bufoff) + ldsw + _i * 8192), 16, 0, 0); } while (0)
; template <class Epi, class Sched, bool ALIGN_EPI = true, bool SP2 = true, bool GS = false>
; __device__ __forceinline__ void gemm_phase(PG8_LAS unsigned char* lds, const Gemm g, const Sched& S, const Epi& E, const float* gs_ss = nullptr) {
;     ...
;         const bool has_next = S.next(ui + 1, nxt);
;         const char* nA = has_next ? (const char*)g.A + S.a_extra(nxt) + (size_t)nxt.pm * tstep : cA; const char* nB = has_next ? (const char*)g.Bt + S.b_extra(nxt) + (size_t)nxt.pn * tstep : cB;
;         for (int t = 0; t < nt; t += 2) {
;             const bool last = (t == nt - 2);
;             const char* a1 = cA + (size_t)(t + 1) * kstep;
;             const char* a2 = last ? nA : cA + (size_t)(t + 2) * kstep; const char* b2 = last ? nB : cB + (size_t)(t + 2) * kstep;
;             const char* a3 = a2 + kstep; const char* b3 = b2 + kstep;
;             if constexpr (SP2) {
;             PG8_LDB(B0, 0, 0); PG8_LDB(B1, 0, 1); PG8_SCHED; PG8_LDA(At, 0, 0); PG8_STAGE(PG8_SA(1, 1), a1 + hstep, voffA);
;             PG8_WAIT_V(8); PG8_WAIT_L(0); PG8_BAR; PG8_MMA(0, 0, At, B0); PG8_MMA(0, 1, At, B1); PG8_BAR; PG8_SCHED;
;             PG8_LDA(At, 0, 1); PG8_STAGE(PG8_SB(0, 0), b2, voffB); PG8_STAGE(PG8_SB(0, 1), b2 + hstep, voffB); PG8_STAGE(PG8_SA(0, 0), a2, voffA);
;             PG8_WAIT_V(8); PG8_WAIT_L(0); PG8_BAR; PG8_MMA(1, 0, At, B0); PG8_MMA(1, 1, At, B1); PG8_BAR; PG8_SCHED;
.LBB0_1252:
	s_add_u32 s2, s56, 0xfffe0080
	s_addc_u32 s3, s57, -1
	s_cmp_eq_u32 s64, 4
	s_cselect_b32 s21, s18, s3
	s_cselect_b32 s20, s51, s2
	s_cselect_b32 s3, s49, s59
	s_cselect_b32 s2, s63, s58
	v_lshl_add_u64 v[176:177], s[56:57], 0, v[152:153]
	s_add_i32 m0, s9, 0xc000
	s_nop 0
	global_load_lds_dwordx4 v[176:177], off
	v_lshl_add_u64 v[176:177], s[56:57], 0, v[154:155]
	s_add_i32 m0, s9, 0xe000
	s_nop 0
	global_load_lds_dwordx4 v[176:177], off
	s_add_i32 s65, 0, 0x10000
	s_add_i32 s67, 0, 0x14000
	v_add_u32_e32 v142, s65, v183
	v_add_u32_e32 v168, s67, v183
	ds_read_b128 v[122:125], v142
	ds_read_b128 v[130:133], v142 offset:1024
	ds_read_b128 v[138:141], v142 offset:2048
	ds_read_b128 v[142:145], v142 offset:3072
	ds_read_b128 v[156:159], v168
	ds_read_b128 v[160:163], v168 offset:1024
	ds_read_b128 v[164:167], v168 offset:2048
	ds_read_b128 v[168:171], v168 offset:3072
	ds_read_b128 v[172:175], v197
	ds_read_b128 v[184:187], v197 offset:1024
	ds_read_b128 v[188:191], v197 offset:2048
	ds_read_b128 v[192:195], v197 offset:3072
	ds_read_b128 v[198:201], v197 offset:4096
	ds_read_b128 v[202:205], v197 offset:5120
	ds_read_b128 v[206:209], v197 offset:6144
	ds_read_b128 v[210:213], v197 offset:7168
	s_waitcnt vmcnt(8)
	s_waitcnt lgkmcnt(0)
	s_barrier
	s_setprio 1
	s_waitcnt lgkmcnt(0)
	v_mfma_f32_16x16x32_bf16 v[134:137], v[122:125], v[172:175], v[134:137]
	v_mfma_f32_16x16x32_bf16 v[126:129], v[138:141], v[172:175], v[126:129]
	v_mfma_f32_16x16x32_bf16 v[110:113], v[122:125], v[188:191], v[110:113]
	v_mfma_f32_16x16x32_bf16 v[106:109], v[138:141], v[188:191], v[106:109]
	v_mfma_f32_16x16x32_bf16 v[94:97], v[122:125], v[198:201], v[94:97]
	v_mfma_f32_16x16x32_bf16 v[90:93], v[138:141], v[198:201], v[90:93]
	v_mfma_f32_16x16x32_bf16 v[78:81], v[122:125], v[206:209], v[78:81]
	v_mfma_f32_16x16x32_bf16 v[74:77], v[138:141], v[206:209], v[74:77]
	v_mfma_f32_16x16x32_bf16 v[134:137], v[130:133], v[184:187], v[134:137]
	v_mfma_f32_16x16x32_bf16 v[126:129], v[142:145], v[184:187], v[126:129]
	v_mfma_f32_16x16x32_bf16 v[110:113], v[130:133], v[192:195], v[110:113]
	v_mfma_f32_16x16x32_bf16 v[106:109], v[142:145], v[192:195], v[106:109]
	v_mfma_f32_16x16x32_bf16 v[94:97], v[130:133], v[202:205], v[94:97]
	v_mfma_f32_16x16x32_bf16 v[90:93], v[142:145], v[202:205], v[90:93]
	v_mfma_f32_16x16x32_bf16 v[78:81], v[130:133], v[210:213], v[78:81]
	v_mfma_f32_16x16x32_bf16 v[74:77], v[142:145], v[210:213], v[74:77]
	s_setprio 0
	s_setprio 1
	v_mfma_f32_16x16x32_bf16 v[118:121], v[156:159], v[172:175], v[118:121]
	v_mfma_f32_16x16x32_bf16 v[114:117], v[164:167], v[172:175], v[114:117]
	v_mfma_f32_16x16x32_bf16 v[102:105], v[156:159], v[188:191], v[102:105]
	v_mfma_f32_16x16x32_bf16 v[98:101], v[164:167], v[188:191], v[98:101]
	v_mfma_f32_16x16x32_bf16 v[86:89], v[156:159], v[198:201], v[86:89]
	v_mfma_f32_16x16x32_bf16 v[82:85], v[164:167], v[198:201], v[82:85]
	v_mfma_f32_16x16x32_bf16 v[70:73], v[156:159], v[206:209], v[70:73]
	v_mfma_f32_16x16x32_bf16 v[66:69], v[164:167], v[206:209], v[66:69]
	v_mfma_f32_16x16x32_bf16 v[118:121], v[160:163], v[184:187], v[118:121]
	v_mfma_f32_16x16x32_bf16 v[114:117], v[168:171], v[184:187], v[114:117]
	v_mfma_f32_16x16x32_bf16 v[102:105], v[160:163], v[192:195], v[102:105]
	v_mfma_f32_16x16x32_bf16 v[98:101], v[168:171], v[192:195], v[98:101]
	v_mfma_f32_16x16x32_bf16 v[86:89], v[160:163], v[202:205], v[86:89]
	v_mfma_f32_16x16x32_bf16 v[82:85], v[168:171], v[202:205], v[82:85]
	v_mfma_f32_16x16x32_bf16 v[70:73], v[160:163], v[210:213], v[70:73]
	v_mfma_f32_16x16x32_bf16 v[66:69], v[168:171], v[210:213], v[66:69]
	s_setprio 0
	s_barrier
	s_add_i32 s65, s65, s24
	v_lshl_add_u64 v[176:177], s[2:3], 0, v[0:1]
	s_mov_b32 m0, s65
	s_nop 0
	global_load_lds_dwordx4 v[176:177], off
	s_add_i32 m0, s65, 0x2000
	s_add_u32 s70, s2, 0x20000
	v_lshl_add_u64 v[180:181], s[2:3], 0, v[150:151]
	s_addc_u32 s71, s3, 0
	s_add_i32 s65, s67, s24
	global_load_lds_dwordx4 v[180:181], off
	v_lshl_add_u64 v[214:215], s[70:71], 0, v[0:1]
	s_mov_b32 m0, s65
	v_lshl_add_u64 v[216:217], s[20:21], 0, v[148:149]
	global_load_lds_dwordx4 v[214:215], off
	v_lshl_add_u64 v[214:215], s[70:71], 0, v[150:151]
	s_add_i32 m0, s65, 0x2000
	s_nop 0
	global_load_lds_dwordx4 v[214:215], off
	v_lshl_add_u64 v[214:215], s[20:21], 0, v[146:147]
	s_mov_b32 m0, s9
	s_nop 0
	global_load_lds_dwordx4 v[214:215], off
	s_mov_b32 m0, s13
	s_nop 0
	global_load_lds_dwordx4 v[216:217], off
	ds_read_b128 v[172:175], v197 offset:16384
	ds_read_b128 v[184:187], v197 offset:17408
	ds_read_b128 v[188:191], v197 offset:18432
	ds_read_b128 v[192:195], v197 offset:19456
	ds_read_b128 v[198:201], v197 offset:20480
	ds_read_b128 v[202:205], v197 offset:21504
	ds_read_b128 v[206:209], v197 offset:22528
	ds_read_b128 v[210:213], v197 offset:23552
	s_waitcnt vmcnt(8)
	s_waitcnt lgkmcnt(0)
	s_barrier
; #define PG8_STAGE(bufoff, gbase, voff) do { _Pragma("unroll") for (int _i = 0; _i < 2; ++_i) \
;         __builtin_amdgcn_global_load_lds((const unsigned*)((const char*)(gbase) + (voff)[_i]), (PG8_LAS unsigned*)(lds + (bufoff) + ldsw + _i * 8192), 16, 0, 0); } while (0)
; #define PG8_LDA(dst, b, h) do { _Pragma("unroll") for (int m = 0; m < 4; ++m) _Pragma("unroll") for (int k = 0; k < 2; ++k) dst[m][k] = *(const PG8_LAS bf16x8*)(lds + PG8_SA(b, h) + aoff + m * 2048 + k * 1024); } while (0)
; #define PG8_LDB(dst, b, h) do { _Pragma("unroll") for (int n = 0; n < 2; ++n) _Pragma("unroll") for (int k = 0; k < 2; ++k) dst[n][k] = *(const PG8_LAS bf16x8*)(lds + PG8_SB(b, h) + boff + n * 2048 + k * 1024); } while (0)
; #define PG8_MMA(ai, bj, At, Bt) do { __builtin_amdgcn_s_setprio(1); _Pragma("unroll") for (int m = 0; m < 4; ++m) _Pragma("unroll") for (int n = 0; n < 2; ++n) _Pragma("unroll") for (int k = 0; k < 2; ++k) \
;         acc[ai][bj][m][n] = __builtin_amdgcn_mfma_f32_16x16x32_bf16(Bt[n][k], At[m][k], acc[ai][bj][m][n], 0, 0, 0); __builtin_amdgcn_s_setprio(0); } while (0)
; #define PG8_WAIT_V(n) asm volatile("s_waitcnt vmcnt(" #n ")" ::: "memory")
; #define PG8_WAIT_L(n) asm volatile("s_waitcnt lgkmcnt(" #n ")" ::: "memory")
; #define PG8_BAR __builtin_amdgcn_s_barrier()
; #define PG8_SCHED __builtin_amdgcn_sched_barrier(0)
; template <class Epi, class Sched, bool ALIGN_EPI = true, bool SP2 = true, bool GS = false>
; __device__ __forceinline__ void gemm_phase(PG8_LAS unsigned char* lds, const Gemm g, const Sched& S, const Epi& E, const float* gs_ss = nullptr) {
;     ...
;             PG8_WAIT_V(8); PG8_WAIT_L(0); PG8_BAR; PG8_MMA(1, 0, At, B0); PG8_MMA(1, 1, At, B1); PG8_BAR; PG8_SCHED;
;             PG8_LDB(B0, 1, 0); PG8_LDB(B1, 1, 1); PG8_SCHED; PG8_LDA(At, 1, 0); PG8_STAGE(PG8_SA(0, 1), a2 + hstep, voffA);
;             PG8_WAIT_V(8); PG8_WAIT_L(0); PG8_BAR; PG8_MMA(0, 0, At, B0); PG8_MMA(0, 1, At, B1); PG8_BAR; PG8_SCHED;
	s_setprio 1
	s_waitcnt lgkmcnt(0)
	v_mfma_f32_16x16x32_bf16 v[62:65], v[122:125], v[172:175], v[62:65]
	v_mfma_f32_16x16x32_bf16 v[58:61], v[138:141], v[172:175], v[58:61]
	v_mfma_f32_16x16x32_bf16 v[46:49], v[122:125], v[188:191], v[46:49]
	v_mfma_f32_16x16x32_bf16 v[42:45], v[138:141], v[188:191], v[42:45]
	v_mfma_f32_16x16x32_bf16 v[30:33], v[122:125], v[198:201], v[30:33]
	v_mfma_f32_16x16x32_bf16 v[26:29], v[138:141], v[198:201], v[26:29]
	v_mfma_f32_16x16x32_bf16 v[14:17], v[122:125], v[206:209], v[14:17]
	v_mfma_f32_16x16x32_bf16 v[10:13], v[138:141], v[206:209], v[10:13]
	v_mfma_f32_16x16x32_bf16 v[62:65], v[130:133], v[184:187], v[62:65]
	v_mfma_f32_16x16x32_bf16 v[58:61], v[142:145], v[184:187], v[58:61]
	v_mfma_f32_16x16x32_bf16 v[46:49], v[130:133], v[192:195], v[46:49]
	v_mfma_f32_16x16x32_bf16 v[42:45], v[142:145], v[192:195], v[42:45]
	v_mfma_f32_16x16x32_bf16 v[30:33], v[130:133], v[202:205], v[30:33]
	v_mfma_f32_16x16x32_bf16 v[26:29], v[142:145], v[202:205], v[26:29]
	v_mfma_f32_16x16x32_bf16 v[14:17], v[130:133], v[210:213], v[14:17]
	v_mfma_f32_16x16x32_bf16 v[10:13], v[142:145], v[210:213], v[10:13]
	s_setprio 0
	s_setprio 1
	v_mfma_f32_16x16x32_bf16 v[54:57], v[156:159], v[172:175], v[54:57]
	v_mfma_f32_16x16x32_bf16 v[50:53], v[164:167], v[172:175], v[50:53]
	v_mfma_f32_16x16x32_bf16 v[38:41], v[156:159], v[188:191], v[38:41]
	v_mfma_f32_16x16x32_bf16 v[34:37], v[164:167], v[188:191], v[34:37]
	v_mfma_f32_16x16x32_bf16 v[22:25], v[156:159], v[198:201], v[22:25]
	v_mfma_f32_16x16x32_bf16 v[18:21], v[164:167], v[198:201], v[18:21]
	v_mfma_f32_16x16x32_bf16 v[6:9], v[156:159], v[206:209], v[6:9]
	v_mfma_f32_16x16x32_bf16 v[2:5], v[164:167], v[206:209], v[2:5]
	v_mfma_f32_16x16x32_bf16 v[54:57], v[160:163], v[184:187], v[54:57]
	v_mfma_f32_16x16x32_bf16 v[50:53], v[168:171], v[184:187], v[50:53]
	v_mfma_f32_16x16x32_bf16 v[38:41], v[160:163], v[192:195], v[38:41]
	v_mfma_f32_16x16x32_bf16 v[34:37], v[168:171], v[192:195], v[34:37]
	v_mfma_f32_16x16x32_bf16 v[22:25], v[160:163], v[202:205], v[22:25]
	v_mfma_f32_16x16x32_bf16 v[18:21], v[168:171], v[202:205], v[18:21]
	v_mfma_f32_16x16x32_bf16 v[6:9], v[160:163], v[210:213], v[6:9]
	v_mfma_f32_16x16x32_bf16 v[2:5], v[168:171], v[210:213], v[2:5]
	s_setprio 0
	s_barrier
	s_add_u32 s20, s20, 0x20000
	s_addc_u32 s21, s21, 0
	s_mov_b32 m0, s25
	v_lshl_add_u64 v[218:219], s[20:21], 0, v[146:147]
	global_load_lds_dwordx4 v[218:219], off
	v_lshl_add_u64 v[218:219], s[20:21], 0, v[148:149]
	s_mov_b32 m0, s30
	s_nop 0
	global_load_lds_dwordx4 v[218:219], off
	s_add_i32 s65, 0, 0x18000
	s_add_i32 s67, 0, 0x1c000
	v_add_u32_e32 v142, s65, v183
	v_add_u32_e32 v168, s67, v183
	ds_read_b128 v[122:125], v142
	ds_read_b128 v[130:133], v142 offset:1024
	ds_read_b128 v[138:141], v142 offset:2048
	ds_read_b128 v[142:145], v142 offset:3072
	ds_read_b128 v[156:159], v168
	ds_read_b128 v[160:163], v168 offset:1024
	ds_read_b128 v[164:167], v168 offset:2048
	ds_read_b128 v[168:171], v168 offset:3072
	ds_read_b128 v[172:175], v197 offset:32768
	ds_read_b128 v[184:187], v197 offset:33792
	ds_read_b128 v[188:191], v197 offset:34816
	ds_read_b128 v[192:195], v197 offset:35840
	ds_read_b128 v[198:201], v197 offset:36864
	ds_read_b128 v[202:205], v197 offset:37888
	ds_read_b128 v[206:209], v197 offset:38912
	ds_read_b128 v[210:213], v197 offset:39936
	s_waitcnt vmcnt(8)
	s_waitcnt lgkmcnt(0)
	s_barrier
	s_setprio 1
	s_waitcnt lgkmcnt(0)
	v_mfma_f32_16x16x32_bf16 v[134:137], v[122:125], v[172:175], v[134:137]
	v_mfma_f32_16x16x32_bf16 v[126:129], v[138:141], v[172:175], v[126:129]
	v_mfma_f32_16x16x32_bf16 v[110:113], v[122:125], v[188:191], v[110:113]
	v_mfma_f32_16x16x32_bf16 v[106:109], v[138:141], v[188:191], v[106:109]
	v_mfma_f32_16x16x32_bf16 v[94:97], v[122:125], v[198:201], v[94:97]
	v_mfma_f32_16x16x32_bf16 v[90:93], v[138:141], v[198:201], v[90:93]
	v_mfma_f32_16x16x32_bf16 v[78:81], v[122:125], v[206:209], v[78:81]
	v_mfma_f32_16x16x32_bf16 v[74:77], v[138:141], v[206:209], v[74:77]
	v_mfma_f32_16x16x32_bf16 v[134:137], v[130:133], v[184:187], v[134:137]
	v_mfma_f32_16x16x32_bf16 v[126:129], v[142:145], v[184:187], v[126:129]
	v_mfma_f32_16x16x32_bf16 v[110:113], v[130:133], v[192:195], v[110:113]
	v_mfma_f32_16x16x32_bf16 v[106:109], v[142:145], v[192:195], v[106:109]
	v_mfma_f32_16x16x32_bf16 v[94:97], v[130:133], v[202:205], v[94:97]
	v_mfma_f32_16x16x32_bf16 v[90:93], v[142:145], v[202:205], v[90:93]
	v_mfma_f32_16x16x32_bf16 v[78:81], v[130:133], v[210:213], v[78:81]
	v_mfma_f32_16x16x32_bf16 v[74:77], v[142:145], v[210:213], v[74:77]
	s_setprio 0
	s_setprio 1
	v_mfma_f32_16x16x32_bf16 v[118:121], v[156:159], v[172:175], v[118:121]
	v_mfma_f32_16x16x32_bf16 v[114:117], v[164:167], v[172:175], v[114:117]
	v_mfma_f32_16x16x32_bf16 v[102:105], v[156:159], v[188:191], v[102:105]
	v_mfma_f32_16x16x32_bf16 v[98:101], v[164:167], v[188:191], v[98:101]
	v_mfma_f32_16x16x32_bf16 v[86:89], v[156:159], v[198:201], v[86:89]
	v_mfma_f32_16x16x32_bf16 v[82:85], v[164:167], v[198:201], v[82:85]
	v_mfma_f32_16x16x32_bf16 v[70:73], v[156:159], v[206:209], v[70:73]
	v_mfma_f32_16x16x32_bf16 v[66:69], v[164:167], v[206:209], v[66:69]
	v_mfma_f32_16x16x32_bf16 v[118:121], v[160:163], v[184:187], v[118:121]
	v_mfma_f32_16x16x32_bf16 v[114:117], v[168:171], v[184:187], v[114:117]
	v_mfma_f32_16x16x32_bf16 v[102:105], v[160:163], v[192:195], v[102:105]
	v_mfma_f32_16x16x32_bf16 v[98:101], v[168:171], v[192:195], v[98:101]
	v_mfma_f32_16x16x32_bf16 v[86:89], v[160:163], v[202:205], v[86:89]
	v_mfma_f32_16x16x32_bf16 v[82:85], v[168:171], v[202:205], v[82:85]
	v_mfma_f32_16x16x32_bf16 v[70:73], v[160:163], v[210:213], v[70:73]
	v_mfma_f32_16x16x32_bf16 v[66:69], v[168:171], v[210:213], v[66:69]
	s_setprio 0
	s_barrier
; #define PG8_STAGE(bufoff, gbase, voff) do { _Pragma("unroll") for (int _i = 0; _i < 2; ++_i) \
;         __builtin_amdgcn_global_load_lds((const unsigned*)((const char*)(gbase) + (voff)[_i]), (PG8_LAS unsigned*)(lds + (bufoff) + ldsw + _i * 8192), 16, 0, 0); } while (0)
; #define PG8_LDA(dst, b, h) do { _Pragma("unroll") for (int m = 0; m < 4; ++m) _Pragma("unroll") for (int k = 0; k < 2; ++k) dst[m][k] = *(const PG8_LAS bf16x8*)(lds + PG8_SA(b, h) + aoff + m * 2048 + k * 1024); } while (0)
; #define PG8_MMA(ai, bj, At, Bt) do { __builtin_amdgcn_s_setprio(1); _Pragma("unroll") for (int m = 0; m < 4; ++m) _Pragma("unroll") for (int n = 0; n < 2; ++n) _Pragma("unroll") for (int k = 0; k < 2; ++k) \
;         acc[ai][bj][m][n] = __builtin_amdgcn_mfma_f32_16x16x32_bf16(Bt[n][k], At[m][k], acc[ai][bj][m][n], 0, 0, 0); __builtin_amdgcn_s_setprio(0); } while (0)
; #define PG8_WAIT_V(n) asm volatile("s_waitcnt vmcnt(" #n ")" ::: "memory")
; #define PG8_WAIT_L(n) asm volatile("s_waitcnt lgkmcnt(" #n ")" ::: "memory")
; #define PG8_BAR __builtin_amdgcn_s_barrier()
; #define PG8_SCHED __builtin_amdgcn_sched_barrier(0)
; template <class Epi, class Sched, bool ALIGN_EPI = true, bool SP2 = true, bool GS = false>
; __device__ __forceinline__ void gemm_phase(PG8_LAS unsigned char* lds, const Gemm g, const Sched& S, const Epi& E, const float* gs_ss = nullptr) {
;     ...
;             PG8_LDA(At, 1, 1); PG8_STAGE(PG8_SB(1, 0), b3, voffB); PG8_STAGE(PG8_SB(1, 1), b3 + hstep, voffB); PG8_STAGE(PG8_SA(1, 0), a3, voffA);
;             PG8_WAIT_V(8); PG8_WAIT_L(0); PG8_BAR; PG8_MMA(1, 0, At, B0); PG8_MMA(1, 1, At, B1); PG8_BAR; PG8_SCHED;
	s_add_i32 s20, s65, s24
	v_lshl_add_u64 v[176:177], v[176:177], 0, s[26:27]
	s_mov_b32 m0, s20
	s_nop 0
	global_load_lds_dwordx4 v[176:177], off
	s_add_i32 m0, s20, 0x2000
	s_add_u32 s2, s2, 0x20080
	v_lshl_add_u64 v[176:177], v[180:181], 0, s[26:27]
	s_addc_u32 s3, s3, 0
	s_add_i32 s20, s67, s24
	global_load_lds_dwordx4 v[176:177], off
	v_lshl_add_u64 v[176:177], s[2:3], 0, v[0:1]
	s_mov_b32 m0, s20
	s_nop 0
	global_load_lds_dwordx4 v[176:177], off
	v_lshl_add_u64 v[176:177], s[2:3], 0, v[150:151]
	s_add_i32 m0, s20, 0x2000
	s_nop 0
	global_load_lds_dwordx4 v[176:177], off
	v_lshl_add_u64 v[176:177], v[214:215], 0, s[26:27]
	s_mov_b32 m0, s37
	s_nop 0
	global_load_lds_dwordx4 v[176:177], off
	v_lshl_add_u64 v[176:177], v[216:217], 0, s[26:27]
	s_mov_b32 m0, s60
	s_nop 0
	global_load_lds_dwordx4 v[176:177], off
	ds_read_b128 v[172:175], v197 offset:49152
	ds_read_b128 v[184:187], v197 offset:50176
	ds_read_b128 v[188:191], v197 offset:51200
	ds_read_b128 v[192:195], v197 offset:52224
	ds_read_b128 v[198:201], v197 offset:53248
	ds_read_b128 v[202:205], v197 offset:54272
	ds_read_b128 v[206:209], v197 offset:55296
	ds_read_b128 v[210:213], v197 offset:56320
	s_waitcnt vmcnt(8)
	s_waitcnt lgkmcnt(0)
	s_barrier
	s_setprio 1
	s_waitcnt lgkmcnt(0)
	v_mfma_f32_16x16x32_bf16 v[62:65], v[122:125], v[172:175], v[62:65]
	v_mfma_f32_16x16x32_bf16 v[58:61], v[138:141], v[172:175], v[58:61]
	v_mfma_f32_16x16x32_bf16 v[46:49], v[122:125], v[188:191], v[46:49]
	v_mfma_f32_16x16x32_bf16 v[42:45], v[138:141], v[188:191], v[42:45]
	v_mfma_f32_16x16x32_bf16 v[30:33], v[122:125], v[198:201], v[30:33]
	v_mfma_f32_16x16x32_bf16 v[26:29], v[138:141], v[198:201], v[26:29]
	v_mfma_f32_16x16x32_bf16 v[14:17], v[122:125], v[206:209], v[14:17]
	v_mfma_f32_16x16x32_bf16 v[10:13], v[138:141], v[206:209], v[10:13]
	v_mfma_f32_16x16x32_bf16 v[62:65], v[130:133], v[184:187], v[62:65]
	v_mfma_f32_16x16x32_bf16 v[58:61], v[142:145], v[184:187], v[58:61]
	v_mfma_f32_16x16x32_bf16 v[46:49], v[130:133], v[192:195], v[46:49]
	v_mfma_f32_16x16x32_bf16 v[42:45], v[142:145], v[192:195], v[42:45]
	v_mfma_f32_16x16x32_bf16 v[30:33], v[130:133], v[202:205], v[30:33]
	v_mfma_f32_16x16x32_bf16 v[26:29], v[142:145], v[202:205], v[26:29]
	v_mfma_f32_16x16x32_bf16 v[14:17], v[130:133], v[210:213], v[14:17]
	v_mfma_f32_16x16x32_bf16 v[10:13], v[142:145], v[210:213], v[10:13]
	s_setprio 0
	s_setprio 1
	v_mfma_f32_16x16x32_bf16 v[54:57], v[156:159], v[172:175], v[54:57]
	v_mfma_f32_16x16x32_bf16 v[50:53], v[164:167], v[172:175], v[50:53]
	v_mfma_f32_16x16x32_bf16 v[38:41], v[156:159], v[188:191], v[38:41]
	v_mfma_f32_16x16x32_bf16 v[34:37], v[164:167], v[188:191], v[34:37]
	v_mfma_f32_16x16x32_bf16 v[22:25], v[156:159], v[198:201], v[22:25]
	v_mfma_f32_16x16x32_bf16 v[18:21], v[164:167], v[198:201], v[18:21]
	v_mfma_f32_16x16x32_bf16 v[6:9], v[156:159], v[206:209], v[6:9]
	v_mfma_f32_16x16x32_bf16 v[2:5], v[164:167], v[206:209], v[2:5]
	v_mfma_f32_16x16x32_bf16 v[54:57], v[160:163], v[184:187], v[54:57]
	v_mfma_f32_16x16x32_bf16 v[50:53], v[168:171], v[184:187], v[50:53]
	v_mfma_f32_16x16x32_bf16 v[38:41], v[160:163], v[192:195], v[38:41]
	v_mfma_f32_16x16x32_bf16 v[34:37], v[168:171], v[192:195], v[34:37]
	v_mfma_f32_16x16x32_bf16 v[22:25], v[160:163], v[202:205], v[22:25]
	v_mfma_f32_16x16x32_bf16 v[18:21], v[168:171], v[202:205], v[18:21]
	v_mfma_f32_16x16x32_bf16 v[6:9], v[160:163], v[210:213], v[6:9]
	v_mfma_f32_16x16x32_bf16 v[2:5], v[168:171], v[210:213], v[2:5]
	s_setprio 0
	s_barrier
	s_add_i32 s64, s64, 2
	s_add_u32 s56, s56, 0x100
	s_addc_u32 s57, s57, 0
	s_add_u32 s58, s58, 0x100
	s_addc_u32 s59, s59, 0
	s_cmp_gt_u32 s64, 5
	s_cbranch_scc0 .LBB0_1252
	s_and_b64 vcc, exec, s[46:47]
	s_cbranch_vccz .LBB0_1255
	s_barrier

;     __device__ bool next(int i, Unit& u) const { const int L = i * G + c; if (L >= 192) return false; u.pm = L / 6; u.pn = L % 6; return true; }
;     __device__ __forceinline__ size_t a_extra(const Unit& u) const { return (size_t)(u.pn >> 1) * ((size_t)T * 512 * 2); }
;     __device__ bool next(int i, Unit& u) const { const int L = i * G + c; if (L >= 256) return false; u.pm = L >> 3; u.pn = L & 7; return true; }
;     __device__ __forceinline__ size_t a_extra(const Unit& u) const { return (size_t)(u.pn >> 1) * 512 * 2; }
;     __device__ __forceinline__ size_t b_extra(const Unit& u) const { return (size_t)(u.pn >> 1) * 512 * 2 - (size_t)(u.pn & ~1) * ((size_t)256 * D * 2); }
; #define PG8_STAGE(bufoff, gbase, voff) do { _Pragma("unroll") for (int _i = 0; _i < 2; ++_i) \
;         __builtin_amdgcn_global_load_lds((const unsigned*)((const char*)(gbase) + (voff)[_i]), (PG8_LAS unsigned*)(lds + (bufoff) + ldsw + _i * 8192), 16, 0, 0); } while (0)
; template <class Epi, class Sched, bool ALIGN_EPI = true, bool SP2 = true, bool GS = false>
; __device__ __forceinline__ void gemm_phase(PG8_LAS unsigned char* lds, const Gemm g, const Sched& S, const Epi& E, const float* gs_ss = nullptr) {
;     ...
;         const bool has_next = S.next(ui + 1, nxt);
;         const char* nA = has_next ? (const char*)g.A + S.a_extra(nxt) + (size_t)nxt.pm * tstep : cA; const char* nB = has_next ? (const char*)g.Bt + S.b_extra(nxt) + (size_t)nxt.pn * tstep : cB;
;         for (int t = 0; t < nt; t += 2) {
;             const bool last = (t == nt - 2);
;             const char* a1 = cA + (size_t)(t + 1) * kstep;
;             const char* a2 = last ? nA : cA + (size_t)(t + 2) * kstep; const char* b2 = last ? nB : cB + (size_t)(t + 2) * kstep;
;             const char* a3 = a2 + kstep; const char* b3 = b2 + kstep;
;             if constexpr (SP2) {
;             PG8_LDB(B0, 0, 0); PG8_LDB(B1, 0, 1); PG8_SCHED; PG8_LDA(At, 0, 0); PG8_STAGE(PG8_SA(1, 1), a1 + hstep, voffA);
;             PG8_WAIT_V(8); PG8_WAIT_L(0); PG8_BAR; PG8_MMA(0, 0, At, B0); PG8_MMA(0, 1, At, B1); PG8_BAR; PG8_SCHED;
;             PG8_LDA(At, 0, 1); PG8_STAGE(PG8_SB(0, 0), b2, voffB); PG8_STAGE(PG8_SB(0, 1), b2 + hstep, voffB); PG8_STAGE(PG8_SA(0, 0), a2, voffA);
;             PG8_WAIT_V(8); PG8_WAIT_L(0); PG8_BAR; PG8_MMA(1, 0, At, B0); PG8_MMA(1, 1, At, B1); PG8_BAR; PG8_SCHED;
.LBB0_1344:
	s_add_u32 s2, s50, 0xfff80080
	s_addc_u32 s3, s51, -1
	s_add_i32 s60, 0, 0x10000
	s_cmp_eq_u32 s59, 28
	s_cselect_b32 s21, s43, s3
	s_cselect_b32 s20, s57, s2
	v_add_u32_e32 v140, s60, v143
	s_cselect_b32 s3, s41, s53
	s_cselect_b32 s2, s58, s52
	s_add_i32 s62, 0, 0x14000
	ds_read_b128 v[146:149], v140
	ds_read_b128 v[150:153], v140 offset:1024
	ds_read_b128 v[154:157], v140 offset:2048
	ds_read_b128 v[158:161], v140 offset:3072
	v_add_u32_e32 v140, s62, v143
	ds_read_b128 v[162:165], v140
	ds_read_b128 v[166:169], v140 offset:1024
	ds_read_b128 v[170:173], v140 offset:2048
	ds_read_b128 v[174:177], v140 offset:3072
	v_lshl_add_u64 v[140:141], s[50:51], 0, v[136:137]
	s_add_i32 m0, s30, 0xc000
	ds_read_b128 v[180:183], v145
	ds_read_b128 v[184:187], v145 offset:1024
	ds_read_b128 v[188:191], v145 offset:2048
	ds_read_b128 v[192:195], v145 offset:3072
	ds_read_b128 v[196:199], v145 offset:4096
	ds_read_b128 v[200:203], v145 offset:5120
	ds_read_b128 v[204:207], v145 offset:6144
	ds_read_b128 v[208:211], v145 offset:7168
	global_load_lds_dwordx4 v[140:141], off
	v_lshl_add_u64 v[140:141], s[50:51], 0, v[138:139]
	s_add_i32 m0, s30, 0xe000
	s_nop 0
	global_load_lds_dwordx4 v[140:141], off
	s_waitcnt vmcnt(8)
	s_waitcnt lgkmcnt(0)
	s_barrier
	s_setprio 1
	s_waitcnt lgkmcnt(0)
	v_mfma_f32_16x16x32_bf16 v[126:129], v[146:149], v[180:183], v[126:129]
	v_mfma_f32_16x16x32_bf16 v[122:125], v[154:157], v[180:183], v[122:125]
	v_mfma_f32_16x16x32_bf16 v[110:113], v[146:149], v[188:191], v[110:113]
	v_mfma_f32_16x16x32_bf16 v[106:109], v[154:157], v[188:191], v[106:109]
	v_mfma_f32_16x16x32_bf16 v[94:97], v[146:149], v[196:199], v[94:97]
	v_mfma_f32_16x16x32_bf16 v[90:93], v[154:157], v[196:199], v[90:93]
	v_mfma_f32_16x16x32_bf16 v[78:81], v[146:149], v[204:207], v[78:81]
	v_mfma_f32_16x16x32_bf16 v[74:77], v[154:157], v[204:207], v[74:77]
	v_mfma_f32_16x16x32_bf16 v[126:129], v[150:153], v[184:187], v[126:129]
	v_mfma_f32_16x16x32_bf16 v[122:125], v[158:161], v[184:187], v[122:125]
	v_mfma_f32_16x16x32_bf16 v[110:113], v[150:153], v[192:195], v[110:113]
	v_mfma_f32_16x16x32_bf16 v[106:109], v[158:161], v[192:195], v[106:109]
	v_mfma_f32_16x16x32_bf16 v[94:97], v[150:153], v[200:203], v[94:97]
	v_mfma_f32_16x16x32_bf16 v[90:93], v[158:161], v[200:203], v[90:93]
	v_mfma_f32_16x16x32_bf16 v[78:81], v[150:153], v[208:211], v[78:81]
	v_mfma_f32_16x16x32_bf16 v[74:77], v[158:161], v[208:211], v[74:77]
	s_setprio 0
	s_setprio 1
	v_mfma_f32_16x16x32_bf16 v[118:121], v[162:165], v[180:183], v[118:121]
	v_mfma_f32_16x16x32_bf16 v[114:117], v[170:173], v[180:183], v[114:117]
	v_mfma_f32_16x16x32_bf16 v[102:105], v[162:165], v[188:191], v[102:105]
	v_mfma_f32_16x16x32_bf16 v[98:101], v[170:173], v[188:191], v[98:101]
	v_mfma_f32_16x16x32_bf16 v[86:89], v[162:165], v[196:199], v[86:89]
	v_mfma_f32_16x16x32_bf16 v[82:85], v[170:173], v[196:199], v[82:85]
	v_mfma_f32_16x16x32_bf16 v[70:73], v[162:165], v[204:207], v[70:73]
	v_mfma_f32_16x16x32_bf16 v[66:69], v[170:173], v[204:207], v[66:69]
	v_mfma_f32_16x16x32_bf16 v[118:121], v[166:169], v[184:187], v[118:121]
	v_mfma_f32_16x16x32_bf16 v[114:117], v[174:177], v[184:187], v[114:117]
	v_mfma_f32_16x16x32_bf16 v[102:105], v[166:169], v[192:195], v[102:105]
	v_mfma_f32_16x16x32_bf16 v[98:101], v[174:177], v[192:195], v[98:101]
	v_mfma_f32_16x16x32_bf16 v[86:89], v[166:169], v[200:203], v[86:89]
	v_mfma_f32_16x16x32_bf16 v[82:85], v[174:177], v[200:203], v[82:85]
	v_mfma_f32_16x16x32_bf16 v[70:73], v[166:169], v[208:211], v[70:73]
	v_mfma_f32_16x16x32_bf16 v[66:69], v[174:177], v[208:211], v[66:69]
	s_setprio 0
	s_barrier
	s_add_i32 s60, s60, s25
	v_lshl_add_u64 v[140:141], s[2:3], 0, v[0:1]
	s_mov_b32 m0, s60
	s_nop 0
	global_load_lds_dwordx4 v[140:141], off
	s_add_i32 m0, s60, 0x2000
	s_add_u32 s60, s2, 0x80000
	v_lshl_add_u64 v[212:213], s[2:3], 0, v[134:135]
	s_addc_u32 s61, s3, 0
	s_add_i32 s62, s62, s25
	global_load_lds_dwordx4 v[212:213], off
	v_lshl_add_u64 v[214:215], s[60:61], 0, v[0:1]
	s_mov_b32 m0, s62
	v_lshl_add_u64 v[216:217], s[20:21], 0, v[132:133]
	global_load_lds_dwordx4 v[214:215], off
	v_lshl_add_u64 v[214:215], s[60:61], 0, v[134:135]
	s_add_i32 m0, s62, 0x2000
	s_nop 0
	global_load_lds_dwordx4 v[214:215], off
	v_lshl_add_u64 v[214:215], s[20:21], 0, v[130:131]
	s_mov_b32 m0, s30
	s_nop 0
	global_load_lds_dwordx4 v[214:215], off
	s_mov_b32 m0, s36
	s_nop 0
	global_load_lds_dwordx4 v[216:217], off
	ds_read_b128 v[180:183], v145 offset:16384
	ds_read_b128 v[184:187], v145 offset:17408
	ds_read_b128 v[188:191], v145 offset:18432
	ds_read_b128 v[192:195], v145 offset:19456
	ds_read_b128 v[196:199], v145 offset:20480
	ds_read_b128 v[200:203], v145 offset:21504
	ds_read_b128 v[204:207], v145 offset:22528
	ds_read_b128 v[208:211], v145 offset:23552
	s_waitcnt vmcnt(8)
	s_waitcnt lgkmcnt(0)
	s_barrier
; #define PG8_STAGE(bufoff, gbase, voff) do { _Pragma("unroll") for (int _i = 0; _i < 2; ++_i) \
;         __builtin_amdgcn_global_load_lds((const unsigned*)((const char*)(gbase) + (voff)[_i]), (PG8_LAS unsigned*)(lds + (bufoff) + ldsw + _i * 8192), 16, 0, 0); } while (0)
; #define PG8_LDA(dst, b, h) do { _Pragma("unroll") for (int m = 0; m < 4; ++m) _Pragma("unroll") for (int k = 0; k < 2; ++k) dst[m][k] = *(const PG8_LAS bf16x8*)(lds + PG8_SA(b, h) + aoff + m * 2048 + k * 1024); } while (0)
; #define PG8_LDB(dst, b, h) do { _Pragma("unroll") for (int n = 0; n < 2; ++n) _Pragma("unroll") for (int k = 0; k < 2; ++k) dst[n][k] = *(const PG8_LAS bf16x8*)(lds + PG8_SB(b, h) + boff + n * 2048 + k * 1024); } while (0)
; #define PG8_MMA(ai, bj, At, Bt) do { __builtin_amdgcn_s_setprio(1); _Pragma("unroll") for (int m = 0; m < 4; ++m) _Pragma("unroll") for (int n = 0; n < 2; ++n) _Pragma("unroll") for (int k = 0; k < 2; ++k) \
;         acc[ai][bj][m][n] = __builtin_amdgcn_mfma_f32_16x16x32_bf16(Bt[n][k], At[m][k], acc[ai][bj][m][n], 0, 0, 0); __builtin_amdgcn_s_setprio(0); } while (0)
; #define PG8_WAIT_V(n) asm volatile("s_waitcnt vmcnt(" #n ")" ::: "memory")
; #define PG8_WAIT_L(n) asm volatile("s_waitcnt lgkmcnt(" #n ")" ::: "memory")
; #define PG8_BAR __builtin_amdgcn_s_barrier()
; #define PG8_SCHED __builtin_amdgcn_sched_barrier(0)
; template <class Epi, class Sched, bool ALIGN_EPI = true, bool SP2 = true, bool GS = false>
; __device__ __forceinline__ void gemm_phase(PG8_LAS unsigned char* lds, const Gemm g, const Sched& S, const Epi& E, const float* gs_ss = nullptr) {
;     ...
;             PG8_WAIT_V(8); PG8_WAIT_L(0); PG8_BAR; PG8_MMA(1, 0, At, B0); PG8_MMA(1, 1, At, B1); PG8_BAR; PG8_SCHED;
;             PG8_LDB(B0, 1, 0); PG8_LDB(B1, 1, 1); PG8_SCHED; PG8_LDA(At, 1, 0); PG8_STAGE(PG8_SA(0, 1), a2 + hstep, voffA);
;             PG8_WAIT_V(8); PG8_WAIT_L(0); PG8_BAR; PG8_MMA(0, 0, At, B0); PG8_MMA(0, 1, At, B1); PG8_BAR; PG8_SCHED;
	s_setprio 1
	s_waitcnt lgkmcnt(0)
	v_mfma_f32_16x16x32_bf16 v[62:65], v[146:149], v[180:183], v[62:65]
	v_mfma_f32_16x16x32_bf16 v[58:61], v[154:157], v[180:183], v[58:61]
	v_mfma_f32_16x16x32_bf16 v[46:49], v[146:149], v[188:191], v[46:49]
	v_mfma_f32_16x16x32_bf16 v[42:45], v[154:157], v[188:191], v[42:45]
	v_mfma_f32_16x16x32_bf16 v[30:33], v[146:149], v[196:199], v[30:33]
	v_mfma_f32_16x16x32_bf16 v[26:29], v[154:157], v[196:199], v[26:29]
	v_mfma_f32_16x16x32_bf16 v[14:17], v[146:149], v[204:207], v[14:17]
	v_mfma_f32_16x16x32_bf16 v[10:13], v[154:157], v[204:207], v[10:13]
	v_mfma_f32_16x16x32_bf16 v[62:65], v[150:153], v[184:187], v[62:65]
	v_mfma_f32_16x16x32_bf16 v[58:61], v[158:161], v[184:187], v[58:61]
	v_mfma_f32_16x16x32_bf16 v[46:49], v[150:153], v[192:195], v[46:49]
	v_mfma_f32_16x16x32_bf16 v[42:45], v[158:161], v[192:195], v[42:45]
	v_mfma_f32_16x16x32_bf16 v[30:33], v[150:153], v[200:203], v[30:33]
	v_mfma_f32_16x16x32_bf16 v[26:29], v[158:161], v[200:203], v[26:29]
	v_mfma_f32_16x16x32_bf16 v[14:17], v[150:153], v[208:211], v[14:17]
	v_mfma_f32_16x16x32_bf16 v[10:13], v[158:161], v[208:211], v[10:13]
	s_setprio 0
	s_setprio 1
	v_mfma_f32_16x16x32_bf16 v[54:57], v[162:165], v[180:183], v[54:57]
	v_mfma_f32_16x16x32_bf16 v[50:53], v[170:173], v[180:183], v[50:53]
	v_mfma_f32_16x16x32_bf16 v[38:41], v[162:165], v[188:191], v[38:41]
	v_mfma_f32_16x16x32_bf16 v[34:37], v[170:173], v[188:191], v[34:37]
	v_mfma_f32_16x16x32_bf16 v[22:25], v[162:165], v[196:199], v[22:25]
	v_mfma_f32_16x16x32_bf16 v[18:21], v[170:173], v[196:199], v[18:21]
	v_mfma_f32_16x16x32_bf16 v[6:9], v[162:165], v[204:207], v[6:9]
	v_mfma_f32_16x16x32_bf16 v[2:5], v[170:173], v[204:207], v[2:5]
	v_mfma_f32_16x16x32_bf16 v[54:57], v[166:169], v[184:187], v[54:57]
	v_mfma_f32_16x16x32_bf16 v[50:53], v[174:177], v[184:187], v[50:53]
	v_mfma_f32_16x16x32_bf16 v[38:41], v[166:169], v[192:195], v[38:41]
	v_mfma_f32_16x16x32_bf16 v[34:37], v[174:177], v[192:195], v[34:37]
	v_mfma_f32_16x16x32_bf16 v[22:25], v[166:169], v[200:203], v[22:25]
	v_mfma_f32_16x16x32_bf16 v[18:21], v[174:177], v[200:203], v[18:21]
	v_mfma_f32_16x16x32_bf16 v[6:9], v[166:169], v[208:211], v[6:9]
	v_mfma_f32_16x16x32_bf16 v[2:5], v[174:177], v[208:211], v[2:5]
	s_setprio 0
	s_barrier
	s_add_u32 s20, s20, 0x80000
	s_addc_u32 s21, s21, 0
	s_mov_b32 m0, s37
	v_lshl_add_u64 v[218:219], s[20:21], 0, v[130:131]
	global_load_lds_dwordx4 v[218:219], off
	v_lshl_add_u64 v[218:219], s[20:21], 0, v[132:133]
	s_mov_b32 m0, s49
	s_nop 0
	global_load_lds_dwordx4 v[218:219], off
	s_add_i32 s60, 0, 0x18000
	s_add_i32 s61, 0, 0x1c000
	v_add_u32_e32 v158, s60, v143
	v_add_u32_e32 v174, s61, v143
	ds_read_b128 v[146:149], v158
	ds_read_b128 v[150:153], v158 offset:1024
	ds_read_b128 v[154:157], v158 offset:2048
	ds_read_b128 v[158:161], v158 offset:3072
	ds_read_b128 v[162:165], v174
	ds_read_b128 v[166:169], v174 offset:1024
	ds_read_b128 v[170:173], v174 offset:2048
	ds_read_b128 v[174:177], v174 offset:3072
	ds_read_b128 v[180:183], v145 offset:32768
	ds_read_b128 v[184:187], v145 offset:33792
	ds_read_b128 v[188:191], v145 offset:34816
	ds_read_b128 v[192:195], v145 offset:35840
	ds_read_b128 v[196:199], v145 offset:36864
	ds_read_b128 v[200:203], v145 offset:37888
	ds_read_b128 v[204:207], v145 offset:38912
	ds_read_b128 v[208:211], v145 offset:39936
	s_waitcnt vmcnt(8)
	s_waitcnt lgkmcnt(0)
	s_barrier
	s_setprio 1
	s_waitcnt lgkmcnt(0)
	v_mfma_f32_16x16x32_bf16 v[126:129], v[146:149], v[180:183], v[126:129]
	v_mfma_f32_16x16x32_bf16 v[122:125], v[154:157], v[180:183], v[122:125]
	v_mfma_f32_16x16x32_bf16 v[110:113], v[146:149], v[188:191], v[110:113]
	v_mfma_f32_16x16x32_bf16 v[106:109], v[154:157], v[188:191], v[106:109]
	v_mfma_f32_16x16x32_bf16 v[94:97], v[146:149], v[196:199], v[94:97]
	v_mfma_f32_16x16x32_bf16 v[90:93], v[154:157], v[196:199], v[90:93]
	v_mfma_f32_16x16x32_bf16 v[78:81], v[146:149], v[204:207], v[78:81]
	v_mfma_f32_16x16x32_bf16 v[74:77], v[154:157], v[204:207], v[74:77]
	v_mfma_f32_16x16x32_bf16 v[126:129], v[150:153], v[184:187], v[126:129]
	v_mfma_f32_16x16x32_bf16 v[122:125], v[158:161], v[184:187], v[122:125]
	v_mfma_f32_16x16x32_bf16 v[110:113], v[150:153], v[192:195], v[110:113]
	v_mfma_f32_16x16x32_bf16 v[106:109], v[158:161], v[192:195], v[106:109]
	v_mfma_f32_16x16x32_bf16 v[94:97], v[150:153], v[200:203], v[94:97]
	v_mfma_f32_16x16x32_bf16 v[90:93], v[158:161], v[200:203], v[90:93]
	v_mfma_f32_16x16x32_bf16 v[78:81], v[150:153], v[208:211], v[78:81]
	v_mfma_f32_16x16x32_bf16 v[74:77], v[158:161], v[208:211], v[74:77]
	s_setprio 0
	s_setprio 1
	v_mfma_f32_16x16x32_bf16 v[118:121], v[162:165], v[180:183], v[118:121]
	v_mfma_f32_16x16x32_bf16 v[114:117], v[170:173], v[180:183], v[114:117]
	v_mfma_f32_16x16x32_bf16 v[102:105], v[162:165], v[188:191], v[102:105]
	v_mfma_f32_16x16x32_bf16 v[98:101], v[170:173], v[188:191], v[98:101]
	v_mfma_f32_16x16x32_bf16 v[86:89], v[162:165], v[196:199], v[86:89]
	v_mfma_f32_16x16x32_bf16 v[82:85], v[170:173], v[196:199], v[82:85]
	v_mfma_f32_16x16x32_bf16 v[70:73], v[162:165], v[204:207], v[70:73]
	v_mfma_f32_16x16x32_bf16 v[66:69], v[170:173], v[204:207], v[66:69]
	v_mfma_f32_16x16x32_bf16 v[118:121], v[166:169], v[184:187], v[118:121]
	v_mfma_f32_16x16x32_bf16 v[114:117], v[174:177], v[184:187], v[114:117]
	v_mfma_f32_16x16x32_bf16 v[102:105], v[166:169], v[192:195], v[102:105]
	v_mfma_f32_16x16x32_bf16 v[98:101], v[174:177], v[192:195], v[98:101]
	v_mfma_f32_16x16x32_bf16 v[86:89], v[166:169], v[200:203], v[86:89]
	v_mfma_f32_16x16x32_bf16 v[82:85], v[174:177], v[200:203], v[82:85]
	v_mfma_f32_16x16x32_bf16 v[70:73], v[166:169], v[208:211], v[70:73]
	v_mfma_f32_16x16x32_bf16 v[66:69], v[174:177], v[208:211], v[66:69]
	s_setprio 0
	s_barrier
; #define PG8_STAGE(bufoff, gbase, voff) do { _Pragma("unroll") for (int _i = 0; _i < 2; ++_i) \
;         __builtin_amdgcn_global_load_lds((const unsigned*)((const char*)(gbase) + (voff)[_i]), (PG8_LAS unsigned*)(lds + (bufoff) + ldsw + _i * 8192), 16, 0, 0); } while (0)
; #define PG8_LDA(dst, b, h) do { _Pragma("unroll") for (int m = 0; m < 4; ++m) _Pragma("unroll") for (int k = 0; k < 2; ++k) dst[m][k] = *(const PG8_LAS bf16x8*)(lds + PG8_SA(b, h) + aoff + m * 2048 + k * 1024); } while (0)
; #define PG8_MMA(ai, bj, At, Bt) do { __builtin_amdgcn_s_setprio(1); _Pragma("unroll") for (int m = 0; m < 4; ++m) _Pragma("unroll") for (int n = 0; n < 2; ++n) _Pragma("unroll") for (int k = 0; k < 2; ++k) \
;         acc[ai][bj][m][n] = __builtin_amdgcn_mfma_f32_16x16x32_bf16(Bt[n][k], At[m][k], acc[ai][bj][m][n], 0, 0, 0); __builtin_amdgcn_s_setprio(0); } while (0)
; #define PG8_WAIT_V(n) asm volatile("s_waitcnt vmcnt(" #n ")" ::: "memory")
; #define PG8_WAIT_L(n) asm volatile("s_waitcnt lgkmcnt(" #n ")" ::: "memory")
; #define PG8_BAR __builtin_amdgcn_s_barrier()
; #define PG8_SCHED __builtin_amdgcn_sched_barrier(0)
; template <class Epi, class Sched, bool ALIGN_EPI = true, bool SP2 = true, bool GS = false>
; __device__ __forceinline__ void gemm_phase(PG8_LAS unsigned char* lds, const Gemm g, const Sched& S, const Epi& E, const float* gs_ss = nullptr) {
;     ...
;             PG8_LDA(At, 1, 1); PG8_STAGE(PG8_SB(1, 0), b3, voffB); PG8_STAGE(PG8_SB(1, 1), b3 + hstep, voffB); PG8_STAGE(PG8_SA(1, 0), a3, voffA);
;             PG8_WAIT_V(8); PG8_WAIT_L(0); PG8_BAR; PG8_MMA(1, 0, At, B0); PG8_MMA(1, 1, At, B1); PG8_BAR; PG8_SCHED;
	s_add_i32 s20, s60, s25
	v_lshl_add_u64 v[140:141], v[140:141], 0, s[26:27]
	s_mov_b32 m0, s20
	s_nop 0
	global_load_lds_dwordx4 v[140:141], off
	s_add_i32 m0, s20, 0x2000
	s_add_u32 s2, s2, 0x80080
	v_lshl_add_u64 v[140:141], v[212:213], 0, s[26:27]
	s_addc_u32 s3, s3, 0
	s_add_i32 s20, s61, s25
	global_load_lds_dwordx4 v[140:141], off
	v_lshl_add_u64 v[140:141], s[2:3], 0, v[0:1]
	s_mov_b32 m0, s20
	s_nop 0
	global_load_lds_dwordx4 v[140:141], off
	v_lshl_add_u64 v[140:141], s[2:3], 0, v[134:135]
	s_add_i32 m0, s20, 0x2000
	s_nop 0
	global_load_lds_dwordx4 v[140:141], off
	v_lshl_add_u64 v[140:141], v[214:215], 0, s[26:27]
	s_mov_b32 m0, s18
	s_nop 0
	global_load_lds_dwordx4 v[140:141], off
	v_lshl_add_u64 v[140:141], v[216:217], 0, s[26:27]
	s_mov_b32 m0, s54
	s_nop 0
	global_load_lds_dwordx4 v[140:141], off
	ds_read_b128 v[180:183], v145 offset:49152
	ds_read_b128 v[184:187], v145 offset:50176
	ds_read_b128 v[188:191], v145 offset:51200
	ds_read_b128 v[192:195], v145 offset:52224
	ds_read_b128 v[196:199], v145 offset:53248
	ds_read_b128 v[200:203], v145 offset:54272
	ds_read_b128 v[204:207], v145 offset:55296
	ds_read_b128 v[208:211], v145 offset:56320
	s_waitcnt vmcnt(8)
	s_waitcnt lgkmcnt(0)
	s_barrier
	s_setprio 1
	s_waitcnt lgkmcnt(0)
	v_mfma_f32_16x16x32_bf16 v[62:65], v[146:149], v[180:183], v[62:65]
	v_mfma_f32_16x16x32_bf16 v[58:61], v[154:157], v[180:183], v[58:61]
	v_mfma_f32_16x16x32_bf16 v[46:49], v[146:149], v[188:191], v[46:49]
	v_mfma_f32_16x16x32_bf16 v[42:45], v[154:157], v[188:191], v[42:45]
	v_mfma_f32_16x16x32_bf16 v[30:33], v[146:149], v[196:199], v[30:33]
	v_mfma_f32_16x16x32_bf16 v[26:29], v[154:157], v[196:199], v[26:29]
	v_mfma_f32_16x16x32_bf16 v[14:17], v[146:149], v[204:207], v[14:17]
	v_mfma_f32_16x16x32_bf16 v[10:13], v[154:157], v[204:207], v[10:13]
	v_mfma_f32_16x16x32_bf16 v[62:65], v[150:153], v[184:187], v[62:65]
	v_mfma_f32_16x16x32_bf16 v[58:61], v[158:161], v[184:187], v[58:61]
	v_mfma_f32_16x16x32_bf16 v[46:49], v[150:153], v[192:195], v[46:49]
	v_mfma_f32_16x16x32_bf16 v[42:45], v[158:161], v[192:195], v[42:45]
	v_mfma_f32_16x16x32_bf16 v[30:33], v[150:153], v[200:203], v[30:33]
	v_mfma_f32_16x16x32_bf16 v[26:29], v[158:161], v[200:203], v[26:29]
	v_mfma_f32_16x16x32_bf16 v[14:17], v[150:153], v[208:211], v[14:17]
	v_mfma_f32_16x16x32_bf16 v[10:13], v[158:161], v[208:211], v[10:13]
	s_setprio 0
	s_setprio 1
	v_mfma_f32_16x16x32_bf16 v[54:57], v[162:165], v[180:183], v[54:57]
	v_mfma_f32_16x16x32_bf16 v[50:53], v[170:173], v[180:183], v[50:53]
	v_mfma_f32_16x16x32_bf16 v[38:41], v[162:165], v[188:191], v[38:41]
	v_mfma_f32_16x16x32_bf16 v[34:37], v[170:173], v[188:191], v[34:37]
	v_mfma_f32_16x16x32_bf16 v[22:25], v[162:165], v[196:199], v[22:25]
	v_mfma_f32_16x16x32_bf16 v[18:21], v[170:173], v[196:199], v[18:21]
	v_mfma_f32_16x16x32_bf16 v[6:9], v[162:165], v[204:207], v[6:9]
	v_mfma_f32_16x16x32_bf16 v[2:5], v[170:173], v[204:207], v[2:5]
	v_mfma_f32_16x16x32_bf16 v[54:57], v[166:169], v[184:187], v[54:57]
	v_mfma_f32_16x16x32_bf16 v[50:53], v[174:177], v[184:187], v[50:53]
	v_mfma_f32_16x16x32_bf16 v[38:41], v[166:169], v[192:195], v[38:41]
	v_mfma_f32_16x16x32_bf16 v[34:37], v[174:177], v[192:195], v[34:37]
	v_mfma_f32_16x16x32_bf16 v[22:25], v[166:169], v[200:203], v[22:25]
	v_mfma_f32_16x16x32_bf16 v[18:21], v[174:177], v[200:203], v[18:21]
	v_mfma_f32_16x16x32_bf16 v[6:9], v[166:169], v[208:211], v[6:9]
	v_mfma_f32_16x16x32_bf16 v[2:5], v[174:177], v[208:211], v[2:5]
	s_setprio 0
	s_barrier
	s_add_i32 s59, s59, 2
	s_add_u32 s50, s50, 0x100
	s_addc_u32 s51, s51, 0
	s_add_u32 s52, s52, 0x100
	s_addc_u32 s53, s53, 0
	s_cmp_gt_u32 s59, 29
	s_cbranch_scc0 .LBB0_1344
	s_and_b64 vcc, exec, s[34:35]
	s_cbranch_vccz .LBB0_1347
	s_barrier

;     __device__ bool next(int i, Unit& u) const { const int L = i * G + c; if (L >= 192) return false; u.pm = L / 6; u.pn = L % 6; return true; }
;     __device__ __forceinline__ size_t a_extra(const Unit& u) const { return (size_t)(u.pn >> 1) * ((size_t)T * 512 * 2); }
;     __device__ bool next(int i, Unit& u) const { const int L = i * G + c; if (L >= 256) return false; u.pm = L >> 3; u.pn = L & 7; return true; }
;     __device__ __forceinline__ size_t a_extra(const Unit& u) const { return (size_t)(u.pn >> 1) * 512 * 2; }
;     __device__ __forceinline__ size_t b_extra(const Unit& u) const { return (size_t)(u.pn >> 1) * 512 * 2 - (size_t)(u.pn & ~1) * ((size_t)256 * D * 2); }
; #define PG8_STAGE(bufoff, gbase, voff) do { _Pragma("unroll") for (int _i = 0; _i < 2; ++_i) \
;         __builtin_amdgcn_global_load_lds((const unsigned*)((const char*)(gbase) + (voff)[_i]), (PG8_LAS unsigned*)(lds + (bufoff) + ldsw + _i * 8192), 16, 0, 0); } while (0)
; template <class Epi, class Sched, bool ALIGN_EPI = true, bool SP2 = true, bool GS = false>
; __device__ __forceinline__ void gemm_phase(PG8_LAS unsigned char* lds, const Gemm g, const Sched& S, const Epi& E, const float* gs_ss = nullptr) {
;     ...
;         const bool has_next = S.next(ui + 1, nxt);
;         const char* nA = has_next ? (const char*)g.A + S.a_extra(nxt) + (size_t)nxt.pm * tstep : cA; const char* nB = has_next ? (const char*)g.Bt + S.b_extra(nxt) + (size_t)nxt.pn * tstep : cB;
;         for (int t = 0; t < nt; t += 2) {
;             const bool last = (t == nt - 2);
;             const char* a1 = cA + (size_t)(t + 1) * kstep;
;             const char* a2 = last ? nA : cA + (size_t)(t + 2) * kstep; const char* b2 = last ? nB : cB + (size_t)(t + 2) * kstep;
;             const char* a3 = a2 + kstep; const char* b3 = b2 + kstep;
;             if constexpr (SP2) {
;             PG8_LDB(B0, 0, 0); PG8_LDB(B1, 0, 1); PG8_SCHED; PG8_LDA(At, 0, 0); PG8_STAGE(PG8_SA(1, 1), a1 + hstep, voffA);
;             PG8_WAIT_V(8); PG8_WAIT_L(0); PG8_BAR; PG8_MMA(0, 0, At, B0); PG8_MMA(0, 1, At, B1); PG8_BAR; PG8_SCHED;
;             PG8_LDA(At, 0, 1); PG8_STAGE(PG8_SB(0, 0), b2, voffB); PG8_STAGE(PG8_SB(0, 1), b2 + hstep, voffB); PG8_STAGE(PG8_SA(0, 0), a2, voffA);
;             PG8_WAIT_V(8); PG8_WAIT_L(0); PG8_BAR; PG8_MMA(1, 0, At, B0); PG8_MMA(1, 1, At, B1); PG8_BAR; PG8_SCHED;
.LBB0_1422:
	s_add_u32 s2, s56, 0xffe00080
	s_addc_u32 s3, s57, -1
	s_cmpk_eq_i32 s64, 0x7c
	s_cselect_b32 s21, s18, s3
	s_cselect_b32 s20, s51, s2
	s_cselect_b32 s3, s49, s59
	s_cselect_b32 s2, s63, s58
	v_lshl_add_u64 v[180:181], s[56:57], 0, v[154:155]
	s_add_i32 m0, s9, 0xc000
	s_nop 0
	global_load_lds_dwordx4 v[180:181], off
	v_lshl_add_u64 v[180:181], s[56:57], 0, v[156:157]
	s_add_i32 m0, s9, 0xe000
	s_nop 0
	global_load_lds_dwordx4 v[180:181], off
	s_add_i32 s65, 0, 0x10000
	s_add_i32 s67, 0, 0x14000
	v_add_u32_e32 v142, s65, v236
	v_add_u32_e32 v170, s67, v236
	ds_read_b128 v[130:133], v142
	ds_read_b128 v[134:137], v142 offset:1024
	ds_read_b128 v[138:141], v142 offset:2048
	ds_read_b128 v[142:145], v142 offset:3072
	ds_read_b128 v[158:161], v170
	ds_read_b128 v[162:165], v170 offset:1024
	ds_read_b128 v[166:169], v170 offset:2048
	ds_read_b128 v[170:173], v170 offset:3072
	ds_read_b128 v[174:177], v238
	ds_read_b128 v[184:187], v238 offset:1024
	ds_read_b128 v[188:191], v238 offset:2048
	ds_read_b128 v[192:195], v238 offset:3072
	ds_read_b128 v[196:199], v238 offset:4096
	ds_read_b128 v[200:203], v238 offset:5120
	ds_read_b128 v[204:207], v238 offset:6144
	ds_read_b128 v[208:211], v238 offset:7168
	s_waitcnt vmcnt(8)
	s_waitcnt lgkmcnt(0)
	s_barrier
	s_setprio 1
	s_waitcnt lgkmcnt(0)
	v_mfma_f32_16x16x32_bf16 v[126:129], v[130:133], v[174:177], v[126:129]
	v_mfma_f32_16x16x32_bf16 v[122:125], v[138:141], v[174:177], v[122:125]
	v_mfma_f32_16x16x32_bf16 v[110:113], v[130:133], v[188:191], v[110:113]
	v_mfma_f32_16x16x32_bf16 v[106:109], v[138:141], v[188:191], v[106:109]
	v_mfma_f32_16x16x32_bf16 v[94:97], v[130:133], v[196:199], v[94:97]
	v_mfma_f32_16x16x32_bf16 v[90:93], v[138:141], v[196:199], v[90:93]
	v_mfma_f32_16x16x32_bf16 v[78:81], v[130:133], v[204:207], v[78:81]
	v_mfma_f32_16x16x32_bf16 v[74:77], v[138:141], v[204:207], v[74:77]
	v_mfma_f32_16x16x32_bf16 v[126:129], v[134:137], v[184:187], v[126:129]
	v_mfma_f32_16x16x32_bf16 v[122:125], v[142:145], v[184:187], v[122:125]
	v_mfma_f32_16x16x32_bf16 v[110:113], v[134:137], v[192:195], v[110:113]
	v_mfma_f32_16x16x32_bf16 v[106:109], v[142:145], v[192:195], v[106:109]
	v_mfma_f32_16x16x32_bf16 v[94:97], v[134:137], v[200:203], v[94:97]
	v_mfma_f32_16x16x32_bf16 v[90:93], v[142:145], v[200:203], v[90:93]
	v_mfma_f32_16x16x32_bf16 v[78:81], v[134:137], v[208:211], v[78:81]
	v_mfma_f32_16x16x32_bf16 v[74:77], v[142:145], v[208:211], v[74:77]
	s_setprio 0
	s_setprio 1
	v_mfma_f32_16x16x32_bf16 v[118:121], v[158:161], v[174:177], v[118:121]
	v_mfma_f32_16x16x32_bf16 v[114:117], v[166:169], v[174:177], v[114:117]
	v_mfma_f32_16x16x32_bf16 v[102:105], v[158:161], v[188:191], v[102:105]
	v_mfma_f32_16x16x32_bf16 v[98:101], v[166:169], v[188:191], v[98:101]
	v_mfma_f32_16x16x32_bf16 v[86:89], v[158:161], v[196:199], v[86:89]
	v_mfma_f32_16x16x32_bf16 v[82:85], v[166:169], v[196:199], v[82:85]
	v_mfma_f32_16x16x32_bf16 v[70:73], v[158:161], v[204:207], v[70:73]
	v_mfma_f32_16x16x32_bf16 v[66:69], v[166:169], v[204:207], v[66:69]
	v_mfma_f32_16x16x32_bf16 v[118:121], v[162:165], v[184:187], v[118:121]
	v_mfma_f32_16x16x32_bf16 v[114:117], v[170:173], v[184:187], v[114:117]
	v_mfma_f32_16x16x32_bf16 v[102:105], v[162:165], v[192:195], v[102:105]
	v_mfma_f32_16x16x32_bf16 v[98:101], v[170:173], v[192:195], v[98:101]
	v_mfma_f32_16x16x32_bf16 v[86:89], v[162:165], v[200:203], v[86:89]
	v_mfma_f32_16x16x32_bf16 v[82:85], v[170:173], v[200:203], v[82:85]
	v_mfma_f32_16x16x32_bf16 v[70:73], v[162:165], v[208:211], v[70:73]
	v_mfma_f32_16x16x32_bf16 v[66:69], v[170:173], v[208:211], v[66:69]
	s_setprio 0
	s_barrier
	s_add_i32 s65, s65, s24
	v_lshl_add_u64 v[180:181], s[2:3], 0, v[0:1]
	s_mov_b32 m0, s65
	s_nop 0
	global_load_lds_dwordx4 v[180:181], off
	s_add_i32 m0, s65, 0x2000
	s_add_u32 s70, s2, 0x200000
	v_lshl_add_u64 v[212:213], s[2:3], 0, v[150:151]
	s_addc_u32 s71, s3, 0
	s_add_i32 s65, s67, s24
	global_load_lds_dwordx4 v[212:213], off
	v_lshl_add_u64 v[214:215], s[70:71], 0, v[0:1]
	s_mov_b32 m0, s65
	v_lshl_add_u64 v[216:217], s[20:21], 0, v[148:149]
	global_load_lds_dwordx4 v[214:215], off
	v_lshl_add_u64 v[214:215], s[70:71], 0, v[150:151]
	s_add_i32 m0, s65, 0x2000
	s_nop 0
	global_load_lds_dwordx4 v[214:215], off
	v_lshl_add_u64 v[214:215], s[20:21], 0, v[146:147]
	s_mov_b32 m0, s9
	s_nop 0
	global_load_lds_dwordx4 v[214:215], off
	s_mov_b32 m0, s13
	s_nop 0
	global_load_lds_dwordx4 v[216:217], off
	ds_read_b128 v[174:177], v238 offset:16384
	ds_read_b128 v[184:187], v238 offset:17408
	ds_read_b128 v[188:191], v238 offset:18432
	ds_read_b128 v[192:195], v238 offset:19456
	ds_read_b128 v[196:199], v238 offset:20480
	ds_read_b128 v[200:203], v238 offset:21504
	ds_read_b128 v[204:207], v238 offset:22528
	ds_read_b128 v[208:211], v238 offset:23552
	s_waitcnt vmcnt(8)
	s_waitcnt lgkmcnt(0)
	s_barrier
; #define PG8_STAGE(bufoff, gbase, voff) do { _Pragma("unroll") for (int _i = 0; _i < 2; ++_i) \
;         __builtin_amdgcn_global_load_lds((const unsigned*)((const char*)(gbase) + (voff)[_i]), (PG8_LAS unsigned*)(lds + (bufoff) + ldsw + _i * 8192), 16, 0, 0); } while (0)
; #define PG8_LDA(dst, b, h) do { _Pragma("unroll") for (int m = 0; m < 4; ++m) _Pragma("unroll") for (int k = 0; k < 2; ++k) dst[m][k] = *(const PG8_LAS bf16x8*)(lds + PG8_SA(b, h) + aoff + m * 2048 + k * 1024); } while (0)
; #define PG8_LDB(dst, b, h) do { _Pragma("unroll") for (int n = 0; n < 2; ++n) _Pragma("unroll") for (int k = 0; k < 2; ++k) dst[n][k] = *(const PG8_LAS bf16x8*)(lds + PG8_SB(b, h) + boff + n * 2048 + k * 1024); } while (0)
; #define PG8_MMA(ai, bj, At, Bt) do { __builtin_amdgcn_s_setprio(1); _Pragma("unroll") for (int m = 0; m < 4; ++m) _Pragma("unroll") for (int n = 0; n < 2; ++n) _Pragma("unroll") for (int k = 0; k < 2; ++k) \
;         acc[ai][bj][m][n] = __builtin_amdgcn_mfma_f32_16x16x32_bf16(Bt[n][k], At[m][k], acc[ai][bj][m][n], 0, 0, 0); __builtin_amdgcn_s_setprio(0); } while (0)
; #define PG8_WAIT_V(n) asm volatile("s_waitcnt vmcnt(" #n ")" ::: "memory")
; #define PG8_WAIT_L(n) asm volatile("s_waitcnt lgkmcnt(" #n ")" ::: "memory")
; #define PG8_BAR __builtin_amdgcn_s_barrier()
; #define PG8_SCHED __builtin_amdgcn_sched_barrier(0)
; template <class Epi, class Sched, bool ALIGN_EPI = true, bool SP2 = true, bool GS = false>
; __device__ __forceinline__ void gemm_phase(PG8_LAS unsigned char* lds, const Gemm g, const Sched& S, const Epi& E, const float* gs_ss = nullptr) {
;     ...
;             PG8_WAIT_V(8); PG8_WAIT_L(0); PG8_BAR; PG8_MMA(1, 0, At, B0); PG8_MMA(1, 1, At, B1); PG8_BAR; PG8_SCHED;
;             PG8_LDB(B0, 1, 0); PG8_LDB(B1, 1, 1); PG8_SCHED; PG8_LDA(At, 1, 0); PG8_STAGE(PG8_SA(0, 1), a2 + hstep, voffA);
;             PG8_WAIT_V(8); PG8_WAIT_L(0); PG8_BAR; PG8_MMA(0, 0, At, B0); PG8_MMA(0, 1, At, B1); PG8_BAR; PG8_SCHED;
	s_setprio 1
	s_waitcnt lgkmcnt(0)
	v_mfma_f32_16x16x32_bf16 v[62:65], v[130:133], v[174:177], v[62:65]
	v_mfma_f32_16x16x32_bf16 v[58:61], v[138:141], v[174:177], v[58:61]
	v_mfma_f32_16x16x32_bf16 v[46:49], v[130:133], v[188:191], v[46:49]
	v_mfma_f32_16x16x32_bf16 v[42:45], v[138:141], v[188:191], v[42:45]
	v_mfma_f32_16x16x32_bf16 v[30:33], v[130:133], v[196:199], v[30:33]
	v_mfma_f32_16x16x32_bf16 v[26:29], v[138:141], v[196:199], v[26:29]
	v_mfma_f32_16x16x32_bf16 v[14:17], v[130:133], v[204:207], v[14:17]
	v_mfma_f32_16x16x32_bf16 v[10:13], v[138:141], v[204:207], v[10:13]
	v_mfma_f32_16x16x32_bf16 v[62:65], v[134:137], v[184:187], v[62:65]
	v_mfma_f32_16x16x32_bf16 v[58:61], v[142:145], v[184:187], v[58:61]
	v_mfma_f32_16x16x32_bf16 v[46:49], v[134:137], v[192:195], v[46:49]
	v_mfma_f32_16x16x32_bf16 v[42:45], v[142:145], v[192:195], v[42:45]
	v_mfma_f32_16x16x32_bf16 v[30:33], v[134:137], v[200:203], v[30:33]
	v_mfma_f32_16x16x32_bf16 v[26:29], v[142:145], v[200:203], v[26:29]
	v_mfma_f32_16x16x32_bf16 v[14:17], v[134:137], v[208:211], v[14:17]
	v_mfma_f32_16x16x32_bf16 v[10:13], v[142:145], v[208:211], v[10:13]
	s_setprio 0
	s_setprio 1
	v_mfma_f32_16x16x32_bf16 v[54:57], v[158:161], v[174:177], v[54:57]
	v_mfma_f32_16x16x32_bf16 v[50:53], v[166:169], v[174:177], v[50:53]
	v_mfma_f32_16x16x32_bf16 v[38:41], v[158:161], v[188:191], v[38:41]
	v_mfma_f32_16x16x32_bf16 v[34:37], v[166:169], v[188:191], v[34:37]
	v_mfma_f32_16x16x32_bf16 v[22:25], v[158:161], v[196:199], v[22:25]
	v_mfma_f32_16x16x32_bf16 v[18:21], v[166:169], v[196:199], v[18:21]
	v_mfma_f32_16x16x32_bf16 v[6:9], v[158:161], v[204:207], v[6:9]
	v_mfma_f32_16x16x32_bf16 v[2:5], v[166:169], v[204:207], v[2:5]
	v_mfma_f32_16x16x32_bf16 v[54:57], v[162:165], v[184:187], v[54:57]
	v_mfma_f32_16x16x32_bf16 v[50:53], v[170:173], v[184:187], v[50:53]
	v_mfma_f32_16x16x32_bf16 v[38:41], v[162:165], v[192:195], v[38:41]
	v_mfma_f32_16x16x32_bf16 v[34:37], v[170:173], v[192:195], v[34:37]
	v_mfma_f32_16x16x32_bf16 v[22:25], v[162:165], v[200:203], v[22:25]
	v_mfma_f32_16x16x32_bf16 v[18:21], v[170:173], v[200:203], v[18:21]
	v_mfma_f32_16x16x32_bf16 v[6:9], v[162:165], v[208:211], v[6:9]
	v_mfma_f32_16x16x32_bf16 v[2:5], v[170:173], v[208:211], v[2:5]
	s_setprio 0
	s_barrier
	s_add_u32 s20, s20, 0x200000
	s_addc_u32 s21, s21, 0
	s_mov_b32 m0, s25
	v_lshl_add_u64 v[218:219], s[20:21], 0, v[146:147]
	global_load_lds_dwordx4 v[218:219], off
	v_lshl_add_u64 v[218:219], s[20:21], 0, v[148:149]
	s_mov_b32 m0, s30
	s_nop 0
	global_load_lds_dwordx4 v[218:219], off
	s_add_i32 s65, 0, 0x18000
	s_add_i32 s67, 0, 0x1c000
	v_add_u32_e32 v142, s65, v236
	v_add_u32_e32 v170, s67, v236
	ds_read_b128 v[130:133], v142
	ds_read_b128 v[134:137], v142 offset:1024
	ds_read_b128 v[138:141], v142 offset:2048
	ds_read_b128 v[142:145], v142 offset:3072
	ds_read_b128 v[158:161], v170
	ds_read_b128 v[162:165], v170 offset:1024
	ds_read_b128 v[166:169], v170 offset:2048
	ds_read_b128 v[170:173], v170 offset:3072
	ds_read_b128 v[174:177], v238 offset:32768
	ds_read_b128 v[184:187], v238 offset:33792
	ds_read_b128 v[188:191], v238 offset:34816
	ds_read_b128 v[192:195], v238 offset:35840
	ds_read_b128 v[196:199], v238 offset:36864
	ds_read_b128 v[200:203], v238 offset:37888
	ds_read_b128 v[204:207], v238 offset:38912
	ds_read_b128 v[208:211], v238 offset:39936
	s_waitcnt vmcnt(8)
	s_waitcnt lgkmcnt(0)
	s_barrier
	s_setprio 1
	s_waitcnt lgkmcnt(0)
	v_mfma_f32_16x16x32_bf16 v[126:129], v[130:133], v[174:177], v[126:129]
	v_mfma_f32_16x16x32_bf16 v[122:125], v[138:141], v[174:177], v[122:125]
	v_mfma_f32_16x16x32_bf16 v[110:113], v[130:133], v[188:191], v[110:113]
	v_mfma_f32_16x16x32_bf16 v[106:109], v[138:141], v[188:191], v[106:109]
	v_mfma_f32_16x16x32_bf16 v[94:97], v[130:133], v[196:199], v[94:97]
	v_mfma_f32_16x16x32_bf16 v[90:93], v[138:141], v[196:199], v[90:93]
	v_mfma_f32_16x16x32_bf16 v[78:81], v[130:133], v[204:207], v[78:81]
	v_mfma_f32_16x16x32_bf16 v[74:77], v[138:141], v[204:207], v[74:77]
	v_mfma_f32_16x16x32_bf16 v[126:129], v[134:137], v[184:187], v[126:129]
	v_mfma_f32_16x16x32_bf16 v[122:125], v[142:145], v[184:187], v[122:125]
	v_mfma_f32_16x16x32_bf16 v[110:113], v[134:137], v[192:195], v[110:113]
	v_mfma_f32_16x16x32_bf16 v[106:109], v[142:145], v[192:195], v[106:109]
	v_mfma_f32_16x16x32_bf16 v[94:97], v[134:137], v[200:203], v[94:97]
	v_mfma_f32_16x16x32_bf16 v[90:93], v[142:145], v[200:203], v[90:93]
	v_mfma_f32_16x16x32_bf16 v[78:81], v[134:137], v[208:211], v[78:81]
	v_mfma_f32_16x16x32_bf16 v[74:77], v[142:145], v[208:211], v[74:77]
	s_setprio 0
	s_setprio 1
	v_mfma_f32_16x16x32_bf16 v[118:121], v[158:161], v[174:177], v[118:121]
	v_mfma_f32_16x16x32_bf16 v[114:117], v[166:169], v[174:177], v[114:117]
	v_mfma_f32_16x16x32_bf16 v[102:105], v[158:161], v[188:191], v[102:105]
	v_mfma_f32_16x16x32_bf16 v[98:101], v[166:169], v[188:191], v[98:101]
	v_mfma_f32_16x16x32_bf16 v[86:89], v[158:161], v[196:199], v[86:89]
	v_mfma_f32_16x16x32_bf16 v[82:85], v[166:169], v[196:199], v[82:85]
	v_mfma_f32_16x16x32_bf16 v[70:73], v[158:161], v[204:207], v[70:73]
	v_mfma_f32_16x16x32_bf16 v[66:69], v[166:169], v[204:207], v[66:69]
	v_mfma_f32_16x16x32_bf16 v[118:121], v[162:165], v[184:187], v[118:121]
	v_mfma_f32_16x16x32_bf16 v[114:117], v[170:173], v[184:187], v[114:117]
	v_mfma_f32_16x16x32_bf16 v[102:105], v[162:165], v[192:195], v[102:105]
	v_mfma_f32_16x16x32_bf16 v[98:101], v[170:173], v[192:195], v[98:101]
	v_mfma_f32_16x16x32_bf16 v[86:89], v[162:165], v[200:203], v[86:89]
	v_mfma_f32_16x16x32_bf16 v[82:85], v[170:173], v[200:203], v[82:85]
	v_mfma_f32_16x16x32_bf16 v[70:73], v[162:165], v[208:211], v[70:73]
	v_mfma_f32_16x16x32_bf16 v[66:69], v[170:173], v[208:211], v[66:69]
	s_setprio 0
	s_barrier
; #define PG8_STAGE(bufoff, gbase, voff) do { _Pragma("unroll") for (int _i = 0; _i < 2; ++_i) \
;         __builtin_amdgcn_global_load_lds((const unsigned*)((const char*)(gbase) + (voff)[_i]), (PG8_LAS unsigned*)(lds + (bufoff) + ldsw + _i * 8192), 16, 0, 0); } while (0)
; #define PG8_LDA(dst, b, h) do { _Pragma("unroll") for (int m = 0; m < 4; ++m) _Pragma("unroll") for (int k = 0; k < 2; ++k) dst[m][k] = *(const PG8_LAS bf16x8*)(lds + PG8_SA(b, h) + aoff + m * 2048 + k * 1024); } while (0)
; #define PG8_MMA(ai, bj, At, Bt) do { __builtin_amdgcn_s_setprio(1); _Pragma("unroll") for (int m = 0; m < 4; ++m) _Pragma("unroll") for (int n = 0; n < 2; ++n) _Pragma("unroll") for (int k = 0; k < 2; ++k) \
;         acc[ai][bj][m][n] = __builtin_amdgcn_mfma_f32_16x16x32_bf16(Bt[n][k], At[m][k], acc[ai][bj][m][n], 0, 0, 0); __builtin_amdgcn_s_setprio(0); } while (0)
; #define PG8_WAIT_V(n) asm volatile("s_waitcnt vmcnt(" #n ")" ::: "memory")
; #define PG8_WAIT_L(n) asm volatile("s_waitcnt lgkmcnt(" #n ")" ::: "memory")
; #define PG8_BAR __builtin_amdgcn_s_barrier()
; #define PG8_SCHED __builtin_amdgcn_sched_barrier(0)
; template <class Epi, class Sched, bool ALIGN_EPI = true, bool SP2 = true, bool GS = false>
; __device__ __forceinline__ void gemm_phase(PG8_LAS unsigned char* lds, const Gemm g, const Sched& S, const Epi& E, const float* gs_ss = nullptr) {
;     ...
;             PG8_LDA(At, 1, 1); PG8_STAGE(PG8_SB(1, 0), b3, voffB); PG8_STAGE(PG8_SB(1, 1), b3 + hstep, voffB); PG8_STAGE(PG8_SA(1, 0), a3, voffA);
;             PG8_WAIT_V(8); PG8_WAIT_L(0); PG8_BAR; PG8_MMA(1, 0, At, B0); PG8_MMA(1, 1, At, B1); PG8_BAR; PG8_SCHED;
	s_add_i32 s20, s65, s24
	v_lshl_add_u64 v[180:181], v[180:181], 0, s[26:27]
	s_mov_b32 m0, s20
	s_nop 0
	global_load_lds_dwordx4 v[180:181], off
	s_add_i32 m0, s20, 0x2000
	s_add_u32 s2, s2, 0x200080
	v_lshl_add_u64 v[180:181], v[212:213], 0, s[26:27]
	s_addc_u32 s3, s3, 0
	s_add_i32 s20, s67, s24
	global_load_lds_dwordx4 v[180:181], off
	v_lshl_add_u64 v[180:181], s[2:3], 0, v[0:1]
	s_mov_b32 m0, s20
	s_nop 0
	global_load_lds_dwordx4 v[180:181], off
	v_lshl_add_u64 v[180:181], s[2:3], 0, v[150:151]
	s_add_i32 m0, s20, 0x2000
	s_nop 0
	global_load_lds_dwordx4 v[180:181], off
	v_lshl_add_u64 v[180:181], v[214:215], 0, s[26:27]
	s_mov_b32 m0, s37
	s_nop 0
	global_load_lds_dwordx4 v[180:181], off
	v_lshl_add_u64 v[180:181], v[216:217], 0, s[26:27]
	s_mov_b32 m0, s60
	s_nop 0
	global_load_lds_dwordx4 v[180:181], off
	ds_read_b128 v[174:177], v238 offset:49152
	ds_read_b128 v[184:187], v238 offset:50176
	ds_read_b128 v[188:191], v238 offset:51200
	ds_read_b128 v[192:195], v238 offset:52224
	ds_read_b128 v[196:199], v238 offset:53248
	ds_read_b128 v[200:203], v238 offset:54272
	ds_read_b128 v[204:207], v238 offset:55296
	ds_read_b128 v[208:211], v238 offset:56320
	s_waitcnt vmcnt(8)
	s_waitcnt lgkmcnt(0)
	s_barrier
	s_setprio 1
	s_waitcnt lgkmcnt(0)
	v_mfma_f32_16x16x32_bf16 v[62:65], v[130:133], v[174:177], v[62:65]
	v_mfma_f32_16x16x32_bf16 v[58:61], v[138:141], v[174:177], v[58:61]
	v_mfma_f32_16x16x32_bf16 v[46:49], v[130:133], v[188:191], v[46:49]
	v_mfma_f32_16x16x32_bf16 v[42:45], v[138:141], v[188:191], v[42:45]
	v_mfma_f32_16x16x32_bf16 v[30:33], v[130:133], v[196:199], v[30:33]
	v_mfma_f32_16x16x32_bf16 v[26:29], v[138:141], v[196:199], v[26:29]
	v_mfma_f32_16x16x32_bf16 v[14:17], v[130:133], v[204:207], v[14:17]
	v_mfma_f32_16x16x32_bf16 v[10:13], v[138:141], v[204:207], v[10:13]
	v_mfma_f32_16x16x32_bf16 v[62:65], v[134:137], v[184:187], v[62:65]
	v_mfma_f32_16x16x32_bf16 v[58:61], v[142:145], v[184:187], v[58:61]
	v_mfma_f32_16x16x32_bf16 v[46:49], v[134:137], v[192:195], v[46:49]
	v_mfma_f32_16x16x32_bf16 v[42:45], v[142:145], v[192:195], v[42:45]
	v_mfma_f32_16x16x32_bf16 v[30:33], v[134:137], v[200:203], v[30:33]
	v_mfma_f32_16x16x32_bf16 v[26:29], v[142:145], v[200:203], v[26:29]
	v_mfma_f32_16x16x32_bf16 v[14:17], v[134:137], v[208:211], v[14:17]
	v_mfma_f32_16x16x32_bf16 v[10:13], v[142:145], v[208:211], v[10:13]
	s_setprio 0
	s_setprio 1
	v_mfma_f32_16x16x32_bf16 v[54:57], v[158:161], v[174:177], v[54:57]
	v_mfma_f32_16x16x32_bf16 v[50:53], v[166:169], v[174:177], v[50:53]
	v_mfma_f32_16x16x32_bf16 v[38:41], v[158:161], v[188:191], v[38:41]
	v_mfma_f32_16x16x32_bf16 v[34:37], v[166:169], v[188:191], v[34:37]
	v_mfma_f32_16x16x32_bf16 v[22:25], v[158:161], v[196:199], v[22:25]
	v_mfma_f32_16x16x32_bf16 v[18:21], v[166:169], v[196:199], v[18:21]
	v_mfma_f32_16x16x32_bf16 v[6:9], v[158:161], v[204:207], v[6:9]
	v_mfma_f32_16x16x32_bf16 v[2:5], v[166:169], v[204:207], v[2:5]
	v_mfma_f32_16x16x32_bf16 v[54:57], v[162:165], v[184:187], v[54:57]
	v_mfma_f32_16x16x32_bf16 v[50:53], v[170:173], v[184:187], v[50:53]
	v_mfma_f32_16x16x32_bf16 v[38:41], v[162:165], v[192:195], v[38:41]
	v_mfma_f32_16x16x32_bf16 v[34:37], v[170:173], v[192:195], v[34:37]
	v_mfma_f32_16x16x32_bf16 v[22:25], v[162:165], v[200:203], v[22:25]
	v_mfma_f32_16x16x32_bf16 v[18:21], v[170:173], v[200:203], v[18:21]
	v_mfma_f32_16x16x32_bf16 v[6:9], v[162:165], v[208:211], v[6:9]
	v_mfma_f32_16x16x32_bf16 v[2:5], v[170:173], v[208:211], v[2:5]
	s_setprio 0
	s_barrier
	s_add_i32 s64, s64, 2
	s_add_u32 s56, s56, 0x100
	s_addc_u32 s57, s57, 0
	s_add_u32 s58, s58, 0x100
	s_addc_u32 s59, s59, 0
	s_cmpk_gt_u32 s64, 0x7d
	s_cbranch_scc0 .LBB0_1422
	s_and_b64 vcc, exec, s[46:47]
	s_cbranch_vccz .LBB0_1425
	s_barrier
